# scan state update on f32 matrix core; prep-wave load wait moved; GEMM epilogue rope rows staged in LDS (no per-group vmcnt drain)
# speedup vs baseline: 1.0773x; 1.0204x over previous
; #define G_STAGE_B(bufoff, upn, kt_, h_) do { const char* _g = Bbase + ((size_t)((upn) * 256 + (h_) * 128) * K + (size_t)(kt_) * 64) * 2; \
;     _Pragma("unroll") for (int _i = 0; _i < 2; ++_i) \
;       __builtin_amdgcn_global_load_lds((const unsigned*)(_g + voffB[_i]), (LAS unsigned*)(lds + (bufoff) + ldsw + _i * 8192), 16, 0, 0); } while (0)
; #define G_LDA(dst, b, h) do { _Pragma("unroll") for (int m = 0; m < 4; ++m) _Pragma("unroll") for (int k = 0; k < 2; ++k) dst[m][k] = *(const LAS bf16x8*)(lds + G_SA(b, h) + aoff + m * 2048 + k * 1024); } while (0)
; #define G_LDB(dst, b, h) do { _Pragma("unroll") for (int n = 0; n < 2; ++n) _Pragma("unroll") for (int k = 0; k < 2; ++k) dst[n][k] = *(const LAS bf16x8*)(lds + G_SB(b, h) + boff + n * 2048 + k * 1024); } while (0)
; #define G_MMA(ai, bj, At, Bt_) do { __builtin_amdgcn_s_setprio(1); _Pragma("unroll") for (int m = 0; m < 4; ++m) _Pragma("unroll") for (int n = 0; n < 2; ++n) _Pragma("unroll") for (int k = 0; k < 2; ++k) \
;     acc[ai][bj][m][n] = __builtin_amdgcn_mfma_f32_16x16x32_bf16(Bt_[n][k], At[m][k], acc[ai][bj][m][n], 0, 0, 0); __builtin_amdgcn_s_setprio(0); } while (0)
; #define G_WAIT_L(n) asm volatile("s_waitcnt lgkmcnt(" #n ")" ::: "memory")
; #define G_BAR __builtin_amdgcn_s_barrier()
; #define G_SCHED __builtin_amdgcn_sched_barrier(0)
; template <int MODE>
; DI void gemm_phase(const Params& p, char* smem, const int g_wave) {
;     ...
;     for (int t = 0; t < nt; t += 2) {
;       const bool last = (t == nt - 2);
;       const int pm2 = last ? npm : cpm, pn2 = last ? npn : cpn, t2 = last ? 0 : t + 2, t3 = t2 + 1;
;       G_LDB(B0, 0, 0); G_SCHED; G_LDA(At, 0, 0); G_STAGE_A(G_SA(1, 1), cpm, t + 1, 1);
;       G_WAIT_L(8); G_BAR; G_WAIT_L(0); G_MMA(0, 0, At, B0); G_BAR; G_SCHED;
;       G_LDB(B1, 0, 1); G_STAGE_B(G_SB(0, 0), pn2, t2, 0);
;       G_BAR; G_WAIT_L(0); G_MMA(0, 1, At, B1); G_BAR;
;       G_LDA(At, 0, 1); G_STAGE_A(G_SA(0, 0), pm2, t2, 0);
;       G_BAR; G_WAIT_L(0); G_MMA(1, 0, At, B0); G_BAR; G_SCHED;
.LBB0_86:
	ds_read_b128 v[134:137], v212
	ds_read_b128 v[138:141], v212 offset:1024
	ds_read_b128 v[142:145], v212 offset:2048
	ds_read_b128 v[186:189], v212 offset:3072
	s_add_i32 m0, s86, 0xc000
	s_add_i32 s0, s86, 0xe000
	s_cmp_eq_u32 s7, 12
	s_cselect_b32 s1, s33, s34
	s_cselect_b32 s10, s75, s35
	ds_read_b128 v[190:193], v171
	ds_read_b128 v[194:197], v171 offset:1024
	ds_read_b128 v[198:201], v171 offset:2048
	ds_read_b128 v[202:205], v171 offset:3072
	ds_read_b128 v[206:209], v171 offset:4096
	ds_read_b128 v[214:217], v171 offset:5120
	ds_read_b128 v[220:223], v171 offset:6144
	ds_read_b128 v[224:227], v171 offset:7168
	global_load_lds_dwordx4 v[130:131], off
	s_mov_b32 m0, s0
	s_nop 0
	global_load_lds_dwordx4 v[132:133], off
	s_waitcnt lgkmcnt(8)
	s_barrier
	s_waitcnt lgkmcnt(0)
	s_setprio 1
	s_waitcnt lgkmcnt(0)
	v_mfma_f32_16x16x32_bf16 v[126:129], v[134:137], v[190:193], v[126:129]
	v_mfma_f32_16x16x32_bf16 v[122:125], v[142:145], v[190:193], v[122:125]
	v_mfma_f32_16x16x32_bf16 v[118:121], v[134:137], v[198:201], v[118:121]
	v_mfma_f32_16x16x32_bf16 v[114:117], v[142:145], v[198:201], v[114:117]
	v_mfma_f32_16x16x32_bf16 v[110:113], v[134:137], v[206:209], v[110:113]
	v_mfma_f32_16x16x32_bf16 v[106:109], v[142:145], v[206:209], v[106:109]
	v_mfma_f32_16x16x32_bf16 v[102:105], v[134:137], v[220:223], v[102:105]
	v_mfma_f32_16x16x32_bf16 v[98:101], v[142:145], v[220:223], v[98:101]
	v_mfma_f32_16x16x32_bf16 v[126:129], v[138:141], v[194:197], v[126:129]
	v_mfma_f32_16x16x32_bf16 v[122:125], v[186:189], v[194:197], v[122:125]
	v_mfma_f32_16x16x32_bf16 v[118:121], v[138:141], v[202:205], v[118:121]
	v_mfma_f32_16x16x32_bf16 v[114:117], v[186:189], v[202:205], v[114:117]
	v_mfma_f32_16x16x32_bf16 v[110:113], v[138:141], v[214:217], v[110:113]
	v_mfma_f32_16x16x32_bf16 v[106:109], v[186:189], v[214:217], v[106:109]
	v_mfma_f32_16x16x32_bf16 v[102:105], v[138:141], v[224:227], v[102:105]
	v_mfma_f32_16x16x32_bf16 v[98:101], v[186:189], v[224:227], v[98:101]
	s_setprio 0
	s_barrier
	s_cselect_b32 s16, 0, s76
	s_lshl_b32 s0, s1, 8
	s_ashr_i32 s1, s0, 31
	s_lshl_b64 s[8:9], s[0:1], 10
	s_add_u32 s4, s8, s16
	s_addc_u32 s5, s9, 0
	s_lshl_b64 s[4:5], s[4:5], 1
	s_add_u32 s4, s31, s4
	s_addc_u32 s5, s30, s5
	s_add_i32 s1, s54, s29
	v_lshl_add_u64 v[210:211], s[4:5], 0, v[148:149]
	s_mov_b32 m0, s1
	ds_read_b128 v[228:231], v213
	ds_read_b128 v[232:235], v213 offset:1024
	ds_read_b128 v[236:239], v213 offset:2048
	ds_read_b128 v[240:243], v213 offset:3072
	global_load_lds_dwordx4 v[210:211], off
	v_lshl_add_u64 v[210:211], s[4:5], 0, v[152:153]
	s_add_i32 m0, s1, 0x2000
	s_nop 0
	global_load_lds_dwordx4 v[210:211], off
	s_barrier
	s_waitcnt lgkmcnt(0)
	s_setprio 1
	s_waitcnt lgkmcnt(0)
	v_mfma_f32_16x16x32_bf16 v[62:65], v[228:231], v[190:193], v[62:65]
	v_mfma_f32_16x16x32_bf16 v[58:61], v[236:239], v[190:193], v[58:61]
	v_mfma_f32_16x16x32_bf16 v[54:57], v[228:231], v[198:201], v[54:57]
	v_mfma_f32_16x16x32_bf16 v[50:53], v[236:239], v[198:201], v[50:53]
	v_mfma_f32_16x16x32_bf16 v[46:49], v[228:231], v[206:209], v[46:49]
	v_mfma_f32_16x16x32_bf16 v[42:45], v[236:239], v[206:209], v[42:45]
	v_mfma_f32_16x16x32_bf16 v[38:41], v[228:231], v[220:223], v[38:41]
	v_mfma_f32_16x16x32_bf16 v[34:37], v[236:239], v[220:223], v[34:37]
	v_mfma_f32_16x16x32_bf16 v[62:65], v[232:235], v[194:197], v[62:65]
	v_mfma_f32_16x16x32_bf16 v[58:61], v[240:243], v[194:197], v[58:61]
	v_mfma_f32_16x16x32_bf16 v[54:57], v[232:235], v[202:205], v[54:57]
	v_mfma_f32_16x16x32_bf16 v[50:53], v[240:243], v[202:205], v[50:53]
	v_mfma_f32_16x16x32_bf16 v[46:49], v[232:235], v[214:217], v[46:49]
	v_mfma_f32_16x16x32_bf16 v[42:45], v[240:243], v[214:217], v[42:45]
	v_mfma_f32_16x16x32_bf16 v[38:41], v[232:235], v[224:227], v[38:41]
	v_mfma_f32_16x16x32_bf16 v[34:37], v[240:243], v[224:227], v[34:37]
	s_setprio 0
	s_lshl_b32 s10, s10, 8
	s_ashr_i32 s11, s10, 31
	s_lshl_b64 s[4:5], s[10:11], 10
	s_add_u32 s90, s4, s16
	s_addc_u32 s91, s5, 0
	s_lshl_b64 s[90:91], s[90:91], 1
	s_add_u32 s90, s87, s90
	s_addc_u32 s91, s26, s91
	s_mov_b32 m0, s86
	v_lshl_add_u64 v[210:211], s[90:91], 0, v[146:147]
	s_barrier
	ds_read_b128 v[190:193], v171 offset:16384
	ds_read_b128 v[194:197], v171 offset:17408
	ds_read_b128 v[198:201], v171 offset:18432
	ds_read_b128 v[202:205], v171 offset:19456
	ds_read_b128 v[206:209], v171 offset:20480
	ds_read_b128 v[214:217], v171 offset:21504
	ds_read_b128 v[220:223], v171 offset:22528
	ds_read_b128 v[224:227], v171 offset:23552
	global_load_lds_dwordx4 v[210:211], off
	v_lshl_add_u64 v[210:211], s[90:91], 0, v[150:151]
	s_mov_b32 m0, s27
	s_nop 0
	global_load_lds_dwordx4 v[210:211], off
	s_barrier
	s_waitcnt lgkmcnt(0)
	s_setprio 1
	s_waitcnt lgkmcnt(0)
	v_mfma_f32_16x16x32_bf16 v[94:97], v[134:137], v[190:193], v[94:97]
	v_mfma_f32_16x16x32_bf16 v[90:93], v[142:145], v[190:193], v[90:93]
	v_mfma_f32_16x16x32_bf16 v[86:89], v[134:137], v[198:201], v[86:89]
	v_mfma_f32_16x16x32_bf16 v[82:85], v[142:145], v[198:201], v[82:85]
	v_mfma_f32_16x16x32_bf16 v[78:81], v[134:137], v[206:209], v[78:81]
	v_mfma_f32_16x16x32_bf16 v[74:77], v[142:145], v[206:209], v[74:77]
	v_mfma_f32_16x16x32_bf16 v[70:73], v[134:137], v[220:223], v[70:73]
	v_mfma_f32_16x16x32_bf16 v[66:69], v[142:145], v[220:223], v[66:69]
	v_mfma_f32_16x16x32_bf16 v[94:97], v[138:141], v[194:197], v[94:97]
	v_mfma_f32_16x16x32_bf16 v[90:93], v[186:189], v[194:197], v[90:93]
	v_mfma_f32_16x16x32_bf16 v[86:89], v[138:141], v[202:205], v[86:89]
	v_mfma_f32_16x16x32_bf16 v[82:85], v[186:189], v[202:205], v[82:85]
	v_mfma_f32_16x16x32_bf16 v[78:81], v[138:141], v[214:217], v[78:81]
	v_mfma_f32_16x16x32_bf16 v[74:77], v[186:189], v[214:217], v[74:77]
	v_mfma_f32_16x16x32_bf16 v[70:73], v[138:141], v[224:227], v[70:73]
	v_mfma_f32_16x16x32_bf16 v[66:69], v[186:189], v[224:227], v[66:69]
	s_setprio 0
	s_barrier
; #define G_STAGE_B(bufoff, upn, kt_, h_) do { const char* _g = Bbase + ((size_t)((upn) * 256 + (h_) * 128) * K + (size_t)(kt_) * 64) * 2; \
;     _Pragma("unroll") for (int _i = 0; _i < 2; ++_i) \
;       __builtin_amdgcn_global_load_lds((const unsigned*)(_g + voffB[_i]), (LAS unsigned*)(lds + (bufoff) + ldsw + _i * 8192), 16, 0, 0); } while (0)
; #define G_LDA(dst, b, h) do { _Pragma("unroll") for (int m = 0; m < 4; ++m) _Pragma("unroll") for (int k = 0; k < 2; ++k) dst[m][k] = *(const LAS bf16x8*)(lds + G_SA(b, h) + aoff + m * 2048 + k * 1024); } while (0)
; #define G_LDB(dst, b, h) do { _Pragma("unroll") for (int n = 0; n < 2; ++n) _Pragma("unroll") for (int k = 0; k < 2; ++k) dst[n][k] = *(const LAS bf16x8*)(lds + G_SB(b, h) + boff + n * 2048 + k * 1024); } while (0)
; #define G_MMA(ai, bj, At, Bt_) do { __builtin_amdgcn_s_setprio(1); _Pragma("unroll") for (int m = 0; m < 4; ++m) _Pragma("unroll") for (int n = 0; n < 2; ++n) _Pragma("unroll") for (int k = 0; k < 2; ++k) \
;     acc[ai][bj][m][n] = __builtin_amdgcn_mfma_f32_16x16x32_bf16(Bt_[n][k], At[m][k], acc[ai][bj][m][n], 0, 0, 0); __builtin_amdgcn_s_setprio(0); } while (0)
; #define G_WAIT_V(n) asm volatile("s_waitcnt vmcnt(" #n ")" ::: "memory")
; #define G_WAIT_L(n) asm volatile("s_waitcnt lgkmcnt(" #n ")" ::: "memory")
; #define G_BAR __builtin_amdgcn_s_barrier()
; #define G_SCHED __builtin_amdgcn_sched_barrier(0)
; template <int MODE>
; DI void gemm_phase(const Params& p, char* smem, const int g_wave) {
;     ...
;       G_BAR; G_WAIT_L(0); G_MMA(1, 0, At, B0); G_BAR; G_SCHED;
;       G_STAGE_B(G_SB(0, 1), pn2, t2, 1);
;       G_WAIT_V(6); G_BAR; G_MMA(1, 1, At, B1); G_BAR;
;       G_LDB(B0, 1, 0); G_SCHED; G_LDA(At, 1, 0); G_STAGE_A(G_SA(0, 1), pm2, t2, 1);
;       G_WAIT_L(8); G_BAR; G_WAIT_L(0); G_MMA(0, 0, At, B0); G_BAR; G_SCHED;
;       G_LDB(B1, 1, 1); G_STAGE_B(G_SB(1, 0), pn2, t3, 0);
;       G_BAR; G_WAIT_L(0); G_MMA(0, 1, At, B1); G_BAR;
;       G_LDA(At, 1, 1); G_STAGE_A(G_SA(1, 0), pm2, t3, 0);
;       G_BAR; G_WAIT_L(0); G_MMA(1, 0, At, B0); G_BAR; G_SCHED;
	s_bitset1_b32 s0, 7
	s_ashr_i32 s1, s0, 31
	s_lshl_b64 s[0:1], s[0:1], 10
	s_add_u32 s90, s0, s16
	s_addc_u32 s91, s1, 0
	s_lshl_b64 s[90:91], s[90:91], 1
	s_add_u32 s90, s31, s90
	s_addc_u32 s91, s30, s91
	s_add_i32 s11, s55, s29
	v_lshl_add_u64 v[134:135], s[90:91], 0, v[148:149]
	s_mov_b32 m0, s11
	s_nop 0
	global_load_lds_dwordx4 v[134:135], off
	v_lshl_add_u64 v[134:135], s[90:91], 0, v[152:153]
	s_add_i32 m0, s11, 0x2000
	s_nop 0
	global_load_lds_dwordx4 v[134:135], off
	s_waitcnt vmcnt(6)
	s_barrier
	s_setprio 1
	v_mfma_f32_16x16x32_bf16 v[30:33], v[228:231], v[190:193], v[30:33]
	v_mfma_f32_16x16x32_bf16 v[26:29], v[236:239], v[190:193], v[26:29]
	v_mfma_f32_16x16x32_bf16 v[22:25], v[228:231], v[198:201], v[22:25]
	v_mfma_f32_16x16x32_bf16 v[18:21], v[236:239], v[198:201], v[18:21]
	v_mfma_f32_16x16x32_bf16 v[14:17], v[228:231], v[206:209], v[14:17]
	v_mfma_f32_16x16x32_bf16 v[10:13], v[236:239], v[206:209], v[10:13]
	v_mfma_f32_16x16x32_bf16 v[6:9], v[228:231], v[220:223], v[6:9]
	v_mfma_f32_16x16x32_bf16 v[2:5], v[236:239], v[220:223], v[2:5]
	v_mfma_f32_16x16x32_bf16 v[30:33], v[232:235], v[194:197], v[30:33]
	v_mfma_f32_16x16x32_bf16 v[26:29], v[240:243], v[194:197], v[26:29]
	v_mfma_f32_16x16x32_bf16 v[22:25], v[232:235], v[202:205], v[22:25]
	v_mfma_f32_16x16x32_bf16 v[18:21], v[240:243], v[202:205], v[18:21]
	v_mfma_f32_16x16x32_bf16 v[14:17], v[232:235], v[214:217], v[14:17]
	v_mfma_f32_16x16x32_bf16 v[10:13], v[240:243], v[214:217], v[10:13]
	v_mfma_f32_16x16x32_bf16 v[6:9], v[232:235], v[224:227], v[6:9]
	v_mfma_f32_16x16x32_bf16 v[2:5], v[240:243], v[224:227], v[2:5]
	s_setprio 0
	s_add_i32 s77, 16, 0x18000
	v_add_u32_e32 v154, s77, v163
	s_barrier
	ds_read_b128 v[134:137], v154
	ds_read_b128 v[138:141], v154 offset:1024
	ds_read_b128 v[142:145], v154 offset:2048
	ds_read_b128 v[186:189], v154 offset:3072
	s_bitset1_b32 s10, 7
	s_ashr_i32 s11, s10, 31
	s_lshl_b64 s[10:11], s[10:11], 11
	s_lshl_b64 s[90:91], s[16:17], 1
	s_or_b64 s[10:11], s[10:11], s[90:91]
	s_add_u32 s10, s87, s10
	s_addc_u32 s11, s26, s11
	s_mov_b32 m0, s28
	v_lshl_add_u64 v[210:211], s[10:11], 0, v[146:147]
	ds_read_b128 v[190:193], v171 offset:32768
	ds_read_b128 v[194:197], v171 offset:33792
	ds_read_b128 v[198:201], v171 offset:34816
	ds_read_b128 v[202:205], v171 offset:35840
	ds_read_b128 v[206:209], v171 offset:36864
	ds_read_b128 v[214:217], v171 offset:37888
	ds_read_b128 v[220:223], v171 offset:38912
	ds_read_b128 v[224:227], v171 offset:39936
	global_load_lds_dwordx4 v[210:211], off
	v_lshl_add_u64 v[210:211], s[10:11], 0, v[150:151]
	s_mov_b32 m0, s50
	s_nop 0
	global_load_lds_dwordx4 v[210:211], off
	s_waitcnt lgkmcnt(8)
	s_barrier
	s_waitcnt lgkmcnt(0)
	s_setprio 1
	s_waitcnt lgkmcnt(0)
	v_mfma_f32_16x16x32_bf16 v[126:129], v[134:137], v[190:193], v[126:129]
	v_mfma_f32_16x16x32_bf16 v[122:125], v[142:145], v[190:193], v[122:125]
	v_mfma_f32_16x16x32_bf16 v[118:121], v[134:137], v[198:201], v[118:121]
	v_mfma_f32_16x16x32_bf16 v[114:117], v[142:145], v[198:201], v[114:117]
	v_mfma_f32_16x16x32_bf16 v[110:113], v[134:137], v[206:209], v[110:113]
	v_mfma_f32_16x16x32_bf16 v[106:109], v[142:145], v[206:209], v[106:109]
	v_mfma_f32_16x16x32_bf16 v[102:105], v[134:137], v[220:223], v[102:105]
	v_mfma_f32_16x16x32_bf16 v[98:101], v[142:145], v[220:223], v[98:101]
	v_mfma_f32_16x16x32_bf16 v[126:129], v[138:141], v[194:197], v[126:129]
	v_mfma_f32_16x16x32_bf16 v[122:125], v[186:189], v[194:197], v[122:125]
	v_mfma_f32_16x16x32_bf16 v[118:121], v[138:141], v[202:205], v[118:121]
	v_mfma_f32_16x16x32_bf16 v[114:117], v[186:189], v[202:205], v[114:117]
	v_mfma_f32_16x16x32_bf16 v[110:113], v[138:141], v[214:217], v[110:113]
	v_mfma_f32_16x16x32_bf16 v[106:109], v[186:189], v[214:217], v[106:109]
	v_mfma_f32_16x16x32_bf16 v[102:105], v[138:141], v[224:227], v[102:105]
	v_mfma_f32_16x16x32_bf16 v[98:101], v[186:189], v[224:227], v[98:101]
	s_setprio 0
	s_barrier
	s_add_i32 s10, 16, 0x1c000
	s_or_b32 s11, s16, 64
	s_add_u32 s8, s8, s11
	s_addc_u32 s9, s9, 0
	s_lshl_b64 s[8:9], s[8:9], 1
	s_add_u32 s8, s31, s8
	s_addc_u32 s9, s30, s9
	s_add_i32 s16, s77, s29
	v_add_u32_e32 v154, s10, v163
	v_lshl_add_u64 v[210:211], s[8:9], 0, v[148:149]
	s_mov_b32 m0, s16
	ds_read_b128 v[228:231], v154
	ds_read_b128 v[232:235], v154 offset:1024
	ds_read_b128 v[236:239], v154 offset:2048
	ds_read_b128 v[240:243], v154 offset:3072
	global_load_lds_dwordx4 v[210:211], off
	v_lshl_add_u64 v[210:211], s[8:9], 0, v[152:153]
	s_add_i32 m0, s16, 0x2000
	s_nop 0
	global_load_lds_dwordx4 v[210:211], off
	s_barrier
	s_waitcnt lgkmcnt(0)
	s_setprio 1
	s_waitcnt lgkmcnt(0)
	v_mfma_f32_16x16x32_bf16 v[62:65], v[228:231], v[190:193], v[62:65]
	v_mfma_f32_16x16x32_bf16 v[58:61], v[236:239], v[190:193], v[58:61]
	v_mfma_f32_16x16x32_bf16 v[54:57], v[228:231], v[198:201], v[54:57]
	v_mfma_f32_16x16x32_bf16 v[50:53], v[236:239], v[198:201], v[50:53]
	v_mfma_f32_16x16x32_bf16 v[46:49], v[228:231], v[206:209], v[46:49]
	v_mfma_f32_16x16x32_bf16 v[42:45], v[236:239], v[206:209], v[42:45]
	v_mfma_f32_16x16x32_bf16 v[38:41], v[228:231], v[220:223], v[38:41]
	v_mfma_f32_16x16x32_bf16 v[34:37], v[236:239], v[220:223], v[34:37]
	v_mfma_f32_16x16x32_bf16 v[62:65], v[232:235], v[194:197], v[62:65]
	v_mfma_f32_16x16x32_bf16 v[58:61], v[240:243], v[194:197], v[58:61]
	v_mfma_f32_16x16x32_bf16 v[54:57], v[232:235], v[202:205], v[54:57]
	v_mfma_f32_16x16x32_bf16 v[50:53], v[240:243], v[202:205], v[50:53]
	v_mfma_f32_16x16x32_bf16 v[46:49], v[232:235], v[214:217], v[46:49]
	v_mfma_f32_16x16x32_bf16 v[42:45], v[240:243], v[214:217], v[42:45]
	v_mfma_f32_16x16x32_bf16 v[38:41], v[232:235], v[224:227], v[38:41]
	v_mfma_f32_16x16x32_bf16 v[34:37], v[240:243], v[224:227], v[34:37]
	s_setprio 0
	s_add_u32 s4, s4, s11
	s_addc_u32 s5, s5, 0
	s_lshl_b64 s[4:5], s[4:5], 1
	s_add_u32 s4, s87, s4
	s_addc_u32 s5, s26, s5
	s_mov_b32 m0, s51
	v_lshl_add_u64 v[210:211], s[4:5], 0, v[146:147]
	s_barrier
; DI u32 cvtpk(float lo, float hi) { u32 r; asm volatile("v_cvt_pk_bf16_f32 %0, %1, %2" : "=v"(r) : "v"(lo), "v"(hi)); return r; }
; #define G_WAIT_V(n) asm volatile("s_waitcnt vmcnt(" #n ")" ::: "memory")
; #define G_BAR __builtin_amdgcn_s_barrier()
; template <int MODE>
; DI void gemm_epilogue(const Params& p, const f32x4 (&acc)[2][2][4][2], int pm, int pn, int wr, int wc, int fr, int fq) {
;     ...
;     const bool prompt = brow < TP;
;     const float* rope = (const float*)(p.ws + WS_ROPE);
; #pragma unroll
;     for (int bj = 0; bj < 2; ++bj) {
;       const int cb = bcol + bj * HALF;
;       if (cb >= 8320) continue;
; #pragma unroll
;       for (int ai = 0; ai < 2; ++ai)
; #pragma unroll
;         for (int m = 0; m < 4; ++m) {
;           const int row = brow + ai * HALF + wr * 64 + m * 16 + fr;
;           f32x4 va = acc[ai][bj][m][0], vb = acc[ai][bj][m][1];
;           const int col = cb + wc * 32 + 8 * fq;
;           if (cb < 2048) {
;             if ((wc & 1) == 0) {
;               const int pos = prompt ? (row & 8191) : 1024 + (row & 63);
;               const f32x4 c0 = *(const f32x4*)(rope + pos * 16), c1 = *(const f32x4*)(rope + pos * 16 + 4);
;               const f32x4 s0 = *(const f32x4*)(rope + pos * 16 + 8), s1 = *(const f32x4*)(rope + pos * 16 + 12);
;               f32x4 pa, pb;
; #pragma unroll
;               for (int j = 0; j < 4; ++j) { pa[j] = __shfl_xor(va[j], 16); pb[j] = __shfl_xor(vb[j], 16); }
;               if (fq == 0) { for (int j = 0; j < 4; ++j) { va[j] = va[j] * c0[j] - pa[j] * s0[j]; vb[j] = vb[j] * c1[j] - pb[j] * s1[j]; } }
;               else if (fq == 1) { for (int j = 0; j < 4; ++j) { va[j] = va[j] * c0[j] + pa[j] * s0[j]; vb[j] = vb[j] * c1[j] + pb[j] * s1[j]; } }
;             }
;             u32x4 pk = {cvtpk(va[0], va[1]), cvtpk(va[2], va[3]), cvtpk(vb[0], vb[1]), cvtpk(vb[2], vb[3])};
;             if (cb < 1024) {
;               *(u32x4*)((u16*)(p.ws + WS_Q) + (size_t)row * 1024 + col) = pk;
; template <int MODE>
; DI void gemm_phase(const Params& p, char* smem, const int g_wave) {
;     ...
;       G_STAGE_B(G_SB(1, 1), pn2, t3, 1);
;       G_WAIT_V(6); G_BAR; G_MMA(1, 1, At, B1); G_BAR;
;     }
;     gemm_epilogue<MODE>(p, acc, cpm, cpn, wr, wc, fr, fq);
	ds_read_b128 v[190:193], v171 offset:49152
	ds_read_b128 v[194:197], v171 offset:50176
	ds_read_b128 v[198:201], v171 offset:51200
	ds_read_b128 v[202:205], v171 offset:52224
	ds_read_b128 v[206:209], v171 offset:53248
	ds_read_b128 v[214:217], v171 offset:54272
	ds_read_b128 v[220:223], v171 offset:55296
	ds_read_b128 v[224:227], v171 offset:56320
	global_load_lds_dwordx4 v[210:211], off
	v_lshl_add_u64 v[210:211], s[4:5], 0, v[150:151]
	s_mov_b32 m0, s2
	s_nop 0
	global_load_lds_dwordx4 v[210:211], off
	s_barrier
	s_waitcnt lgkmcnt(0)
	s_setprio 1
	s_waitcnt lgkmcnt(0)
	v_mfma_f32_16x16x32_bf16 v[94:97], v[134:137], v[190:193], v[94:97]
	v_mfma_f32_16x16x32_bf16 v[90:93], v[142:145], v[190:193], v[90:93]
	v_mfma_f32_16x16x32_bf16 v[86:89], v[134:137], v[198:201], v[86:89]
	v_mfma_f32_16x16x32_bf16 v[82:85], v[142:145], v[198:201], v[82:85]
	v_mfma_f32_16x16x32_bf16 v[78:81], v[134:137], v[206:209], v[78:81]
	v_mfma_f32_16x16x32_bf16 v[74:77], v[142:145], v[206:209], v[74:77]
	v_mfma_f32_16x16x32_bf16 v[70:73], v[134:137], v[220:223], v[70:73]
	v_mfma_f32_16x16x32_bf16 v[66:69], v[142:145], v[220:223], v[66:69]
	v_mfma_f32_16x16x32_bf16 v[94:97], v[138:141], v[194:197], v[94:97]
	v_mfma_f32_16x16x32_bf16 v[90:93], v[186:189], v[194:197], v[90:93]
	v_mfma_f32_16x16x32_bf16 v[86:89], v[138:141], v[202:205], v[86:89]
	v_mfma_f32_16x16x32_bf16 v[82:85], v[186:189], v[202:205], v[82:85]
	v_mfma_f32_16x16x32_bf16 v[78:81], v[138:141], v[214:217], v[78:81]
	v_mfma_f32_16x16x32_bf16 v[74:77], v[186:189], v[214:217], v[74:77]
	v_mfma_f32_16x16x32_bf16 v[70:73], v[138:141], v[224:227], v[70:73]
	v_mfma_f32_16x16x32_bf16 v[66:69], v[186:189], v[224:227], v[66:69]
	s_setprio 0
	s_barrier
	s_add_u32 s0, s0, s11
	s_addc_u32 s1, s1, 0
	s_lshl_b64 s[0:1], s[0:1], 1
	s_add_u32 s0, s31, s0
	s_addc_u32 s1, s30, s1
	s_add_i32 s4, s10, s29
	v_lshl_add_u64 v[134:135], s[0:1], 0, v[148:149]
	s_mov_b32 m0, s4
	s_nop 0
	global_load_lds_dwordx4 v[134:135], off
	v_lshl_add_u64 v[134:135], s[0:1], 0, v[152:153]
	s_add_i32 m0, s4, 0x2000
	s_nop 0
	global_load_lds_dwordx4 v[134:135], off
	s_waitcnt vmcnt(6)
	s_barrier
	s_setprio 1
	v_mfma_f32_16x16x32_bf16 v[30:33], v[228:231], v[190:193], v[30:33]
	v_mfma_f32_16x16x32_bf16 v[26:29], v[236:239], v[190:193], v[26:29]
	v_mfma_f32_16x16x32_bf16 v[22:25], v[228:231], v[198:201], v[22:25]
	v_mfma_f32_16x16x32_bf16 v[18:21], v[236:239], v[198:201], v[18:21]
	v_mfma_f32_16x16x32_bf16 v[14:17], v[228:231], v[206:209], v[14:17]
	v_mfma_f32_16x16x32_bf16 v[10:13], v[236:239], v[206:209], v[10:13]
	v_mfma_f32_16x16x32_bf16 v[6:9], v[228:231], v[220:223], v[6:9]
	v_mfma_f32_16x16x32_bf16 v[2:5], v[236:239], v[220:223], v[2:5]
	v_mfma_f32_16x16x32_bf16 v[30:33], v[232:235], v[194:197], v[30:33]
	v_mfma_f32_16x16x32_bf16 v[26:29], v[240:243], v[194:197], v[26:29]
	v_mfma_f32_16x16x32_bf16 v[22:25], v[232:235], v[202:205], v[22:25]
	v_mfma_f32_16x16x32_bf16 v[18:21], v[240:243], v[202:205], v[18:21]
	v_mfma_f32_16x16x32_bf16 v[14:17], v[232:235], v[214:217], v[14:17]
	v_mfma_f32_16x16x32_bf16 v[10:13], v[240:243], v[214:217], v[10:13]
	v_mfma_f32_16x16x32_bf16 v[6:9], v[232:235], v[224:227], v[6:9]
	v_mfma_f32_16x16x32_bf16 v[2:5], v[240:243], v[224:227], v[2:5]
	s_setprio 0
	s_add_i32 s7, s7, 2
	s_addk_i32 s76, 0x80
	v_lshl_add_u64 v[130:131], v[130:131], 0, s[84:85]
	s_cmp_gt_u32 s7, 13
	v_lshl_add_u64 v[132:133], v[132:133], 0, s[84:85]
	s_barrier
	s_cbranch_scc0 .LBB0_86
	s_cmp_gt_i32 s34, 7
	s_cbranch_scc1 .Lrp_skip
	v_lshrrev_b32_e32 v220, 1, v218
	s_lshl_b32 s7, s35, 8
	v_add_u32_e32 v221, s7, v220
	v_and_b32_e32 v222, 0x1fff, v221
	v_and_b32_e32 v223, 63, v221
	v_add_u32_e32 v223, 0x400, v223
	s_cmpk_lt_i32 s35, 0x100
	s_cselect_b64 vcc, -1, 0
	s_nop 0
	v_cndmask_b32_e32 v222, v223, v222, vcc
	v_lshlrev_b32_e32 v222, 6, v222
	v_and_b32_e32 v224, 1, v218
	v_lshl_add_u32 v222, v224, 5, v222
	global_load_dwordx4 v[228:231], v222, s[24:25]
	global_load_dwordx4 v[232:235], v222, s[24:25] offset:16
	v_lshlrev_b32_e32 v225, 5, v218
	v_add_u32_e32 v225, 0x20100, v225
	s_waitcnt vmcnt(0)
	ds_write_b128 v225, v[228:231]
	ds_write_b128 v225, v[232:235] offset:16
	s_waitcnt lgkmcnt(0)
	s_barrier
	s_barrier
.Lrp_skip:
	s_lshl_b32 s90, s34, 8
	s_cmpk_lt_i32 s35, 0x100
	s_cselect_b64 s[4:5], -1, 0
	s_cmpk_gt_i32 s35, 0xff
	v_readlane_b32 s0, v255, 9
	s_cselect_b64 s[92:93], -1, 0
	s_add_i32 s76, s6, s0
	s_cmp_gt_i32 s34, 32
	v_or_b32_e32 v186, s76, v156
	s_cbranch_scc1 .LBB0_374
	s_cmp_gt_i32 s34, 7
	s_cselect_b64 s[0:1], -1, 0
	s_cmpk_gt_u32 s90, 0xbff
	s_cselect_b64 s[6:7], -1, 0
	s_cmpk_gt_u32 s90, 0xfff
	s_cselect_b64 s[96:97], -1, 0
	s_cmpk_gt_u32 s90, 0x1c7f
	v_or_b32_e32 v188, s90, v158
	s_cselect_b64 s[94:95], -1, 0
	s_cmp_gt_i32 s34, 3
	v_add_u32_e32 v190, 0xfffff800, v188
	s_cselect_b64 s[10:11], -1, 0
	s_ashr_i32 s8, s76, 10
	v_ashrrev_i32_e32 v214, 7, v190
	s_and_b32 s8, s8, -8
	v_add_u32_e32 v130, s8, v214
	v_add_u32_e32 v192, 0xfffff000, v188
	v_ashrrev_i32_e32 v131, 31, v130
	v_mov_b32_e32 v154, v188
	v_ashrrev_i32_e32 v193, 31, v192
	v_ashrrev_i32_e32 v191, 31, v190
	v_lshlrev_b64 v[194:195], 21, v[130:131]
	s_mov_b64 s[8:9], -1
	s_and_b64 vcc, exec, s[0:1]
	s_cbranch_vccz .LBB0_105
	s_and_b64 vcc, exec, s[6:7]
	s_cbranch_vccz .LBB0_99
	v_ashrrev_i32_e32 v187, 31, v186
	s_and_b64 vcc, exec, s[96:97]
	v_cvt_pk_bf16_f32 v130, v126, v127
	v_cvt_pk_bf16_f32 v131, v128, v129
	v_cvt_pk_bf16_f32 v132, v122, v123
	v_cvt_pk_bf16_f32 v133, v124, v125
	s_cbranch_vccz .LBB0_96
	s_and_b64 vcc, exec, s[94:95]
	s_cbranch_vccz .LBB0_93
	v_lshlrev_b64 v[134:135], 11, v[186:187]
	v_lshl_add_u64 v[134:135], s[70:71], 0, v[134:135]
	v_lshl_add_u64 v[134:135], v[154:155], 1, v[134:135]
	v_add_co_u32_e32 v134, vcc, 0x80fc000, v134
	s_mov_b64 s[8:9], 0
	s_nop 0
	v_addc_co_u32_e32 v135, vcc, 0, v135, vcc
	global_store_dwordx4 v[134:135], v[130:133], off offset:1792

; template <int MODE>
; DI void gemm_epilogue(const Params& p, const f32x4 (&acc)[2][2][4][2], int pm, int pn, int wr, int wc, int fr, int fq) {
;     ...
;             if ((wc & 1) == 0) {
;               const int pos = prompt ? (row & 8191) : 1024 + (row & 63);
;               const f32x4 c0 = *(const f32x4*)(rope + pos * 16), c1 = *(const f32x4*)(rope + pos * 16 + 4);
;               const f32x4 s0 = *(const f32x4*)(rope + pos * 16 + 8), s1 = *(const f32x4*)(rope + pos * 16 + 12);
;               f32x4 pa, pb;
; #pragma unroll
;               for (int j = 0; j < 4; ++j) { pa[j] = __shfl_xor(va[j], 16); pb[j] = __shfl_xor(vb[j], 16); }
;               if (fq == 0) { for (int j = 0; j < 4; ++j) { va[j] = va[j] * c0[j] - pa[j] * s0[j]; vb[j] = vb[j] * c1[j] - pb[j] * s1[j]; } }
.LBB0_105:
	s_andn2_b64 vcc, exec, s[8:9]
	v_ashrrev_i32_e32 v189, 31, v188
	s_cbranch_vccnz .LBB0_122
	s_andn2_b64 vcc, exec, s[18:19]
	s_cbranch_vccnz .LBB0_114
	v_and_b32_e32 v130, 0x1fcf, v186
	v_cndmask_b32_e64 v130, v160, v130, s[4:5]
	v_and_b32_e32 v142, 0xff, v186
	v_lshlrev_b32_e32 v142, 6, v142
	v_add_u32_e32 v142, 0x20100, v142
	ds_read_b128 v[130:133], v142 offset:48
	ds_read_b128 v[138:141], v142 offset:32
	ds_read_b128 v[134:137], v142 offset:16
	s_nop 0
	ds_read_b128 v[142:145], v142
	ds_bpermute_b32 v204, v167, v126
	ds_bpermute_b32 v200, v167, v122
	ds_bpermute_b32 v205, v167, v127
	ds_bpermute_b32 v201, v167, v123
	ds_bpermute_b32 v202, v167, v128
	ds_bpermute_b32 v187, v167, v124
	ds_bpermute_b32 v211, v167, v129
	ds_bpermute_b32 v203, v167, v125
	v_cmp_lt_i32_e32 vcc, 0, v157
	s_and_saveexec_b64 s[8:9], vcc
	s_xor_b64 s[8:9], exec, s[8:9]
	s_cbranch_execz .LBB0_111
	v_cmp_eq_u32_e32 vcc, 1, v157
	v_mov_b32_e32 v199, v129
	v_mov_b32_e32 v198, v128
	v_mov_b32_e32 v197, v127
	v_mov_b32_e32 v196, v126
	v_mov_b32_e32 v209, v125
	v_mov_b32_e32 v208, v124
	v_mov_b32_e32 v207, v123
	v_mov_b32_e32 v206, v122
	s_and_saveexec_b64 s[98:99], vcc
	s_cbranch_execz .LBB0_110
	s_waitcnt lgkmcnt(0)
	v_mul_f32_e32 v198, v140, v202
	v_mul_f32_e32 v208, v132, v187
	v_mov_b32_e32 v140, v129
	v_mov_b32_e32 v210, v145
	v_mov_b32_e32 v132, v125
	v_mov_b32_e32 v202, v137
	v_pk_mul_f32 v[140:141], v[140:141], v[210:211]
	v_pk_mul_f32 v[132:133], v[132:133], v[202:203]
	v_pk_mul_f32 v[142:143], v[126:127], v[142:143]
	v_pk_mul_f32 v[134:135], v[122:123], v[134:135]
	v_mul_f32_e32 v144, v128, v144
	v_mul_f32_e32 v136, v124, v136
	v_mov_b32_e32 v145, v140
	v_mov_b32_e32 v199, v141
	v_mov_b32_e32 v137, v132
	v_mov_b32_e32 v209, v133
	v_pk_fma_f32 v[196:197], v[138:139], v[204:205], v[142:143]
	v_pk_add_f32 v[198:199], v[144:145], v[198:199]
	v_pk_fma_f32 v[206:207], v[130:131], v[200:201], v[134:135]
	v_pk_add_f32 v[208:209], v[136:137], v[208:209]

; template <int MODE>
; DI void gemm_epilogue(const Params& p, const f32x4 (&acc)[2][2][4][2], int pm, int pn, int wr, int wc, int fr, int fq) {
;     ...
;               for (int j = 0; j < 4; ++j) { pa[j] = __shfl_xor(va[j], 16); pb[j] = __shfl_xor(vb[j], 16); }
;               if (fq == 0) { for (int j = 0; j < 4; ++j) { va[j] = va[j] * c0[j] - pa[j] * s0[j]; vb[j] = vb[j] * c1[j] - pb[j] * s1[j]; } }
.LBB0_111:
	s_andn2_saveexec_b64 s[8:9], s[8:9]
	s_cbranch_execz .LBB0_113
	s_waitcnt lgkmcnt(0)
	v_pk_mul_f32 v[126:127], v[126:127], v[142:143]
	v_pk_mul_f32 v[122:123], v[122:123], v[134:135]
	s_waitcnt lgkmcnt(0)
	v_mul_f32_e32 v134, v140, v202
	v_mul_f32_e32 v124, v124, v136
	v_mul_f32_e32 v136, v132, v187
	v_mov_b32_e32 v140, v129
	v_mov_b32_e32 v210, v145
	v_mov_b32_e32 v132, v125
	v_mov_b32_e32 v202, v137
	v_pk_mul_f32 v[140:141], v[140:141], v[210:211]
	v_pk_fma_f32 v[196:197], v[138:139], v[204:205], v[126:127] neg_lo:[1,0,0] neg_hi:[1,0,0]
	v_pk_mul_f32 v[126:127], v[132:133], v[202:203]
	v_mul_f32_e32 v128, v128, v144
	v_mov_b32_e32 v129, v140
	v_mov_b32_e32 v135, v141
	v_mov_b32_e32 v125, v126
	v_mov_b32_e32 v137, v127
	v_pk_add_f32 v[198:199], v[128:129], v[134:135] neg_lo:[0,1] neg_hi:[0,1]
	v_pk_fma_f32 v[206:207], v[130:131], v[200:201], v[122:123] neg_lo:[1,0,0] neg_hi:[1,0,0]
	v_pk_add_f32 v[208:209], v[124:125], v[136:137] neg_lo:[0,1] neg_hi:[0,1]

; DI u32 cvtpk(float lo, float hi) { u32 r; asm volatile("v_cvt_pk_bf16_f32 %0, %1, %2" : "=v"(r) : "v"(lo), "v"(hi)); return r; }
; template <int MODE>
; DI void gemm_epilogue(const Params& p, const f32x4 (&acc)[2][2][4][2], int pm, int pn, int wr, int wc, int fr, int fq) {
;     ...
;             u32x4 pk = {cvtpk(va[0], va[1]), cvtpk(va[2], va[3]), cvtpk(vb[0], vb[1]), cvtpk(vb[2], vb[3])};
;             if (cb < 1024) {
;               *(u32x4*)((u16*)(p.ws + WS_Q) + (size_t)row * 1024 + col) = pk;
;             } else {
;               const int c = col - 1024;
;               if (prompt) {
;                 float* ko = p.out + O_KP + (size_t)row * 1024 + c; *(f32x4*)ko = va; *(f32x4*)(ko + 4) = vb;
;                 *(u32x4*)((u16*)(p.ws + WS_K) + (size_t)row * 1024 + c) = pk;
;               } else {
;                 const int rs = row - TP, b = rs >> 6, t = rs & 63;
;                 float* ko = p.out + O_KS + (size_t)rs * 1024 + c; *(f32x4*)ko = va; *(f32x4*)(ko + 4) = vb;
;                 *(u32x4*)((u16*)(p.ws + WS_KC) + ((size_t)b * 1088 + 1024 + t) * 1024 + c) = pk;
;               }
.LBB0_114:
	s_mov_b64 s[8:9], -1
	s_and_b64 vcc, exec, s[10:11]
	s_waitcnt lgkmcnt(0)
	v_cvt_pk_bf16_f32 v130, v126, v127
	v_cvt_pk_bf16_f32 v131, v128, v129
	v_cvt_pk_bf16_f32 v132, v122, v123
	v_cvt_pk_bf16_f32 v133, v124, v125
	s_cbranch_vccz .LBB0_120
	s_and_b64 vcc, exec, s[92:93]
	s_cbranch_vccz .LBB0_117
	v_add_u32_e32 v134, 0xffff0000, v186
	v_ashrrev_i32_e32 v135, 31, v134
	v_readlane_b32 s8, v255, 21
	v_ashrrev_i32_e32 v136, 6, v134
	v_lshlrev_b64 v[134:135], 12, v[134:135]
	v_readlane_b32 s9, v255, 22
	s_nop 1
	v_lshl_add_u64 v[134:135], s[8:9], 0, v[134:135]
	v_lshl_add_u64 v[134:135], v[188:189], 2, v[134:135]
	s_movk_i32 s8, 0x440
	global_store_dwordx4 v[134:135], v[126:129], off offset:-4096
	global_store_dwordx4 v[134:135], v[122:125], off offset:-4080
	v_mad_i64_i32 v[134:135], s[8:9], v136, s8, v[160:161]
	v_readlane_b32 s8, v255, 23
	v_lshlrev_b64 v[134:135], 11, v[134:135]
	v_readlane_b32 s9, v255, 24
	s_nop 1
	v_lshl_add_u64 v[134:135], s[8:9], 0, v[134:135]
	v_lshl_add_u64 v[134:135], v[188:189], 1, v[134:135]
	global_store_dwordx4 v[134:135], v[130:133], off offset:-2048
	s_mov_b64 s[8:9], 0

; template <int MODE>
; DI void gemm_epilogue(const Params& p, const f32x4 (&acc)[2][2][4][2], int pm, int pn, int wr, int wc, int fr, int fq) {
;     ...
;             if ((wc & 1) == 0) {
;               const int pos = prompt ? (row & 8191) : 1024 + (row & 63);
;               const f32x4 c0 = *(const f32x4*)(rope + pos * 16), c1 = *(const f32x4*)(rope + pos * 16 + 4);
;               const f32x4 s0 = *(const f32x4*)(rope + pos * 16 + 8), s1 = *(const f32x4*)(rope + pos * 16 + 12);
;               f32x4 pa, pb;
; #pragma unroll
;               for (int j = 0; j < 4; ++j) { pa[j] = __shfl_xor(va[j], 16); pb[j] = __shfl_xor(vb[j], 16); }
;               if (fq == 0) { for (int j = 0; j < 4; ++j) { va[j] = va[j] * c0[j] - pa[j] * s0[j]; vb[j] = vb[j] * c1[j] - pb[j] * s1[j]; } }
.LBB0_139:
	s_andn2_b64 vcc, exec, s[34:35]
	s_cbranch_vccnz .LBB0_156
	s_andn2_b64 vcc, exec, s[18:19]
	s_cbranch_vccnz .LBB0_148
	v_and_b32_e32 v122, 0x1fdf, v138
	v_cndmask_b32_e64 v122, v164, v122, s[4:5]
	v_and_b32_e32 v134, 0xff, v138
	v_lshlrev_b32_e32 v134, 6, v134
	v_add_u32_e32 v134, 0x20100, v134
	ds_read_b128 v[122:125], v134 offset:48
	ds_read_b128 v[130:133], v134 offset:32
	ds_read_b128 v[126:129], v134 offset:16
	s_nop 0
	ds_read_b128 v[134:137], v134
	ds_bpermute_b32 v198, v167, v118
	ds_bpermute_b32 v144, v167, v114
	ds_bpermute_b32 v199, v167, v119
	ds_bpermute_b32 v145, v167, v115
	s_waitcnt lgkmcnt(0)
	ds_bpermute_b32 v187, v167, v120
	ds_bpermute_b32 v139, v167, v116
	ds_bpermute_b32 v205, v167, v121
	ds_bpermute_b32 v197, v167, v117
	v_cmp_lt_i32_e32 vcc, 0, v157
	s_and_saveexec_b64 s[0:1], vcc
	s_xor_b64 s[0:1], exec, s[0:1]
	s_cbranch_execz .LBB0_145
	v_cmp_eq_u32_e32 vcc, 1, v157
	v_mov_b32_e32 v143, v121
	v_mov_b32_e32 v142, v120
	v_mov_b32_e32 v141, v119
	v_mov_b32_e32 v140, v118
	v_mov_b32_e32 v203, v117
	v_mov_b32_e32 v202, v116
	v_mov_b32_e32 v201, v115
	v_mov_b32_e32 v200, v114
	s_and_saveexec_b64 s[98:99], vcc
	s_cbranch_execz .LBB0_144
	s_waitcnt lgkmcnt(0)
	v_mul_f32_e32 v142, v132, v187
	v_mul_f32_e32 v202, v124, v139
	v_mov_b32_e32 v132, v121
	v_mov_b32_e32 v204, v137
	v_mov_b32_e32 v124, v117
	v_mov_b32_e32 v196, v129
	v_pk_mul_f32 v[132:133], v[132:133], v[204:205]
	v_pk_mul_f32 v[124:125], v[124:125], v[196:197]
	v_pk_mul_f32 v[134:135], v[118:119], v[134:135]
	v_pk_mul_f32 v[126:127], v[114:115], v[126:127]
	v_mul_f32_e32 v136, v120, v136
	v_mul_f32_e32 v128, v116, v128
	v_mov_b32_e32 v137, v132
	v_mov_b32_e32 v143, v133
	v_mov_b32_e32 v129, v124
	v_mov_b32_e32 v203, v125
	v_pk_fma_f32 v[140:141], v[130:131], v[198:199], v[134:135]
	v_pk_add_f32 v[142:143], v[136:137], v[142:143]
	v_pk_fma_f32 v[200:201], v[122:123], v[144:145], v[126:127]
	v_pk_add_f32 v[202:203], v[128:129], v[202:203]

; template <int MODE>
; DI void gemm_epilogue(const Params& p, const f32x4 (&acc)[2][2][4][2], int pm, int pn, int wr, int wc, int fr, int fq) {
;     ...
;               for (int j = 0; j < 4; ++j) { pa[j] = __shfl_xor(va[j], 16); pb[j] = __shfl_xor(vb[j], 16); }
;               if (fq == 0) { for (int j = 0; j < 4; ++j) { va[j] = va[j] * c0[j] - pa[j] * s0[j]; vb[j] = vb[j] * c1[j] - pb[j] * s1[j]; } }
.LBB0_145:
	s_andn2_saveexec_b64 s[0:1], s[0:1]
	s_cbranch_execz .LBB0_147
	s_waitcnt lgkmcnt(0)
	v_pk_mul_f32 v[118:119], v[118:119], v[134:135]
	v_pk_mul_f32 v[114:115], v[114:115], v[126:127]
	s_waitcnt lgkmcnt(3)
	v_mul_f32_e32 v126, v132, v187
	v_mul_f32_e32 v116, v116, v128
	s_waitcnt lgkmcnt(2)
	v_mul_f32_e32 v128, v124, v139
	v_mov_b32_e32 v132, v121
	v_mov_b32_e32 v204, v137
	v_mov_b32_e32 v124, v117
	v_mov_b32_e32 v196, v129
	s_waitcnt lgkmcnt(1)
	v_pk_mul_f32 v[132:133], v[132:133], v[204:205]
	v_pk_fma_f32 v[140:141], v[130:131], v[198:199], v[118:119] neg_lo:[1,0,0] neg_hi:[1,0,0]
	s_waitcnt lgkmcnt(0)
	v_pk_mul_f32 v[118:119], v[124:125], v[196:197]
	v_mul_f32_e32 v120, v120, v136
	v_mov_b32_e32 v121, v132
	v_mov_b32_e32 v127, v133
	v_mov_b32_e32 v117, v118
	v_mov_b32_e32 v129, v119
	v_pk_add_f32 v[142:143], v[120:121], v[126:127] neg_lo:[0,1] neg_hi:[0,1]
	v_pk_fma_f32 v[200:201], v[122:123], v[144:145], v[114:115] neg_lo:[1,0,0] neg_hi:[1,0,0]
	v_pk_add_f32 v[202:203], v[116:117], v[128:129] neg_lo:[0,1] neg_hi:[0,1]

; DI u32 cvtpk(float lo, float hi) { u32 r; asm volatile("v_cvt_pk_bf16_f32 %0, %1, %2" : "=v"(r) : "v"(lo), "v"(hi)); return r; }
; template <int MODE>
; DI void gemm_epilogue(const Params& p, const f32x4 (&acc)[2][2][4][2], int pm, int pn, int wr, int wc, int fr, int fq) {
;     ...
;             u32x4 pk = {cvtpk(va[0], va[1]), cvtpk(va[2], va[3]), cvtpk(vb[0], vb[1]), cvtpk(vb[2], vb[3])};
;             if (cb < 1024) {
;               *(u32x4*)((u16*)(p.ws + WS_Q) + (size_t)row * 1024 + col) = pk;
;             } else {
;               const int c = col - 1024;
;               if (prompt) {
;                 float* ko = p.out + O_KP + (size_t)row * 1024 + c; *(f32x4*)ko = va; *(f32x4*)(ko + 4) = vb;
;                 *(u32x4*)((u16*)(p.ws + WS_K) + (size_t)row * 1024 + c) = pk;
;               } else {
;                 const int rs = row - TP, b = rs >> 6, t = rs & 63;
;                 float* ko = p.out + O_KS + (size_t)rs * 1024 + c; *(f32x4*)ko = va; *(f32x4*)(ko + 4) = vb;
;                 *(u32x4*)((u16*)(p.ws + WS_KC) + ((size_t)b * 1088 + 1024 + t) * 1024 + c) = pk;
;               }
.LBB0_148:
	s_andn2_b64 vcc, exec, s[10:11]
	s_mov_b64 s[0:1], -1
	s_waitcnt lgkmcnt(0)
	v_cvt_pk_bf16_f32 v122, v118, v119
	v_cvt_pk_bf16_f32 v123, v120, v121
	v_cvt_pk_bf16_f32 v124, v114, v115
	v_cvt_pk_bf16_f32 v125, v116, v117
	s_cbranch_vccnz .LBB0_154
	s_andn2_b64 vcc, exec, s[92:93]
	s_cbranch_vccnz .LBB0_151
	v_add_u32_e32 v126, 0xffff0000, v138
	v_ashrrev_i32_e32 v127, 31, v126
	v_readlane_b32 s0, v255, 21
	v_ashrrev_i32_e32 v128, 6, v126
	v_lshlrev_b64 v[126:127], 12, v[126:127]
	v_readlane_b32 s1, v255, 22
	s_nop 1
	v_lshl_add_u64 v[126:127], s[0:1], 0, v[126:127]
	v_lshl_add_u64 v[126:127], v[188:189], 2, v[126:127]
	s_movk_i32 s0, 0x440
	global_store_dwordx4 v[126:127], v[118:121], off offset:-4096
	global_store_dwordx4 v[126:127], v[114:117], off offset:-4080
	v_mad_i64_i32 v[126:127], s[0:1], v128, s0, v[164:165]
	v_readlane_b32 s0, v255, 23
	v_lshlrev_b64 v[126:127], 11, v[126:127]
	v_readlane_b32 s1, v255, 24
	s_nop 1
	v_lshl_add_u64 v[126:127], s[0:1], 0, v[126:127]
	v_lshl_add_u64 v[126:127], v[188:189], 1, v[126:127]
	s_mov_b64 s[0:1], 0
	global_store_dwordx4 v[126:127], v[122:125], off offset:-2048

; template <int MODE>
; DI void gemm_epilogue(const Params& p, const f32x4 (&acc)[2][2][4][2], int pm, int pn, int wr, int wc, int fr, int fq) {
;     ...
;             if ((wc & 1) == 0) {
;               const int pos = prompt ? (row & 8191) : 1024 + (row & 63);
;               const f32x4 c0 = *(const f32x4*)(rope + pos * 16), c1 = *(const f32x4*)(rope + pos * 16 + 4);
;               const f32x4 s0 = *(const f32x4*)(rope + pos * 16 + 8), s1 = *(const f32x4*)(rope + pos * 16 + 12);
;               f32x4 pa, pb;
; #pragma unroll
;               for (int j = 0; j < 4; ++j) { pa[j] = __shfl_xor(va[j], 16); pb[j] = __shfl_xor(vb[j], 16); }
;               if (fq == 0) { for (int j = 0; j < 4; ++j) { va[j] = va[j] * c0[j] - pa[j] * s0[j]; vb[j] = vb[j] * c1[j] - pb[j] * s1[j]; } }
.LBB0_173:
	s_andn2_b64 vcc, exec, s[0:1]
	s_cbranch_vccnz .LBB0_190
	s_andn2_b64 vcc, exec, s[18:19]
	s_cbranch_vccnz .LBB0_182
	v_and_b32_e32 v114, 0x1fef, v130
	v_cndmask_b32_e64 v114, v168, v114, s[4:5]
	v_and_b32_e32 v126, 0xff, v130
	v_lshlrev_b32_e32 v126, 6, v126
	v_add_u32_e32 v126, 0x20100, v126
	ds_read_b128 v[114:117], v126 offset:48
	ds_read_b128 v[122:125], v126 offset:32
	ds_read_b128 v[118:121], v126 offset:16
	s_nop 0
	ds_read_b128 v[126:129], v126
	ds_bpermute_b32 v140, v167, v110
	ds_bpermute_b32 v136, v167, v106
	ds_bpermute_b32 v141, v167, v111
	ds_bpermute_b32 v137, v167, v107
	ds_bpermute_b32 v138, v167, v112
	ds_bpermute_b32 v131, v167, v108
	s_waitcnt lgkmcnt(0)
	ds_bpermute_b32 v197, v167, v113
	ds_bpermute_b32 v139, v167, v109
	v_cmp_lt_i32_e32 vcc, 0, v157
	s_and_saveexec_b64 s[0:1], vcc
	s_xor_b64 s[0:1], exec, s[0:1]
	s_cbranch_execz .LBB0_179
	v_cmp_eq_u32_e32 vcc, 1, v157
	v_mov_b32_e32 v135, v113
	v_mov_b32_e32 v134, v112
	v_mov_b32_e32 v133, v111
	v_mov_b32_e32 v132, v110
	v_mov_b32_e32 v145, v109
	v_mov_b32_e32 v144, v108
	v_mov_b32_e32 v143, v107
	v_mov_b32_e32 v142, v106
	s_and_saveexec_b64 s[98:99], vcc
	s_cbranch_execz .LBB0_178
	s_waitcnt lgkmcnt(0)
	v_mul_f32_e32 v134, v124, v138
	v_mul_f32_e32 v144, v116, v131
	v_mov_b32_e32 v124, v113
	v_mov_b32_e32 v196, v129
	v_mov_b32_e32 v116, v109
	v_mov_b32_e32 v138, v121
	s_waitcnt lgkmcnt(1)
	v_pk_mul_f32 v[124:125], v[124:125], v[196:197]
	s_waitcnt lgkmcnt(0)
	v_pk_mul_f32 v[116:117], v[116:117], v[138:139]
	v_pk_mul_f32 v[126:127], v[110:111], v[126:127]
	v_pk_mul_f32 v[118:119], v[106:107], v[118:119]
	v_mul_f32_e32 v128, v112, v128
	v_mul_f32_e32 v120, v108, v120
	v_mov_b32_e32 v129, v124
	v_mov_b32_e32 v135, v125
	v_mov_b32_e32 v121, v116
	v_mov_b32_e32 v145, v117
	v_pk_fma_f32 v[132:133], v[122:123], v[140:141], v[126:127]
	v_pk_add_f32 v[134:135], v[128:129], v[134:135]
	v_pk_fma_f32 v[142:143], v[114:115], v[136:137], v[118:119]
	v_pk_add_f32 v[144:145], v[120:121], v[144:145]

; template <int MODE>
; DI void gemm_epilogue(const Params& p, const f32x4 (&acc)[2][2][4][2], int pm, int pn, int wr, int wc, int fr, int fq) {
;     ...
;               for (int j = 0; j < 4; ++j) { pa[j] = __shfl_xor(va[j], 16); pb[j] = __shfl_xor(vb[j], 16); }
;               if (fq == 0) { for (int j = 0; j < 4; ++j) { va[j] = va[j] * c0[j] - pa[j] * s0[j]; vb[j] = vb[j] * c1[j] - pb[j] * s1[j]; } }
.LBB0_179:
	s_andn2_saveexec_b64 s[0:1], s[0:1]
	s_cbranch_execz .LBB0_181
	s_waitcnt lgkmcnt(0)
	v_pk_mul_f32 v[110:111], v[110:111], v[126:127]
	v_pk_mul_f32 v[106:107], v[106:107], v[118:119]
	v_mul_f32_e32 v118, v124, v138
	v_mul_f32_e32 v108, v108, v120
	v_mul_f32_e32 v120, v116, v131
	v_mov_b32_e32 v124, v113
	v_mov_b32_e32 v196, v129
	v_mov_b32_e32 v116, v109
	v_mov_b32_e32 v138, v121
	s_waitcnt lgkmcnt(1)
	v_pk_mul_f32 v[124:125], v[124:125], v[196:197]
	v_pk_fma_f32 v[132:133], v[122:123], v[140:141], v[110:111] neg_lo:[1,0,0] neg_hi:[1,0,0]
	s_waitcnt lgkmcnt(0)
	v_pk_mul_f32 v[110:111], v[116:117], v[138:139]
	v_mul_f32_e32 v112, v112, v128
	v_mov_b32_e32 v113, v124
	v_mov_b32_e32 v119, v125
	v_mov_b32_e32 v109, v110
	v_mov_b32_e32 v121, v111
	v_pk_add_f32 v[134:135], v[112:113], v[118:119] neg_lo:[0,1] neg_hi:[0,1]
	v_pk_fma_f32 v[142:143], v[114:115], v[136:137], v[106:107] neg_lo:[1,0,0] neg_hi:[1,0,0]
	v_pk_add_f32 v[144:145], v[108:109], v[120:121] neg_lo:[0,1] neg_hi:[0,1]

; DI u32 cvtpk(float lo, float hi) { u32 r; asm volatile("v_cvt_pk_bf16_f32 %0, %1, %2" : "=v"(r) : "v"(lo), "v"(hi)); return r; }
; template <int MODE>
; DI void gemm_epilogue(const Params& p, const f32x4 (&acc)[2][2][4][2], int pm, int pn, int wr, int wc, int fr, int fq) {
;     ...
;             u32x4 pk = {cvtpk(va[0], va[1]), cvtpk(va[2], va[3]), cvtpk(vb[0], vb[1]), cvtpk(vb[2], vb[3])};
;             if (cb < 1024) {
;               *(u32x4*)((u16*)(p.ws + WS_Q) + (size_t)row * 1024 + col) = pk;
;             } else {
;               const int c = col - 1024;
;               if (prompt) {
;                 float* ko = p.out + O_KP + (size_t)row * 1024 + c; *(f32x4*)ko = va; *(f32x4*)(ko + 4) = vb;
;                 *(u32x4*)((u16*)(p.ws + WS_K) + (size_t)row * 1024 + c) = pk;
;               } else {
;                 const int rs = row - TP, b = rs >> 6, t = rs & 63;
;                 float* ko = p.out + O_KS + (size_t)rs * 1024 + c; *(f32x4*)ko = va; *(f32x4*)(ko + 4) = vb;
;                 *(u32x4*)((u16*)(p.ws + WS_KC) + ((size_t)b * 1088 + 1024 + t) * 1024 + c) = pk;
;               }
.LBB0_182:
	s_andn2_b64 vcc, exec, s[10:11]
	s_mov_b64 s[0:1], -1
	s_waitcnt lgkmcnt(0)
	v_cvt_pk_bf16_f32 v114, v110, v111
	v_cvt_pk_bf16_f32 v115, v112, v113
	v_cvt_pk_bf16_f32 v116, v106, v107
	v_cvt_pk_bf16_f32 v117, v108, v109
	s_cbranch_vccnz .LBB0_188
	s_andn2_b64 vcc, exec, s[92:93]
	s_cbranch_vccnz .LBB0_185
	v_add_u32_e32 v118, 0xffff0000, v130
	v_ashrrev_i32_e32 v119, 31, v118
	v_readlane_b32 s0, v255, 21
	v_ashrrev_i32_e32 v120, 6, v118
	v_lshlrev_b64 v[118:119], 12, v[118:119]
	v_readlane_b32 s1, v255, 22
	s_nop 1
	v_lshl_add_u64 v[118:119], s[0:1], 0, v[118:119]
	v_lshl_add_u64 v[118:119], v[188:189], 2, v[118:119]
	s_movk_i32 s0, 0x440
	global_store_dwordx4 v[118:119], v[110:113], off offset:-4096
	global_store_dwordx4 v[118:119], v[106:109], off offset:-4080
	v_mad_i64_i32 v[118:119], s[0:1], v120, s0, v[168:169]
	v_readlane_b32 s0, v255, 23
	v_lshlrev_b64 v[118:119], 11, v[118:119]
	v_readlane_b32 s1, v255, 24
	s_nop 1
	v_lshl_add_u64 v[118:119], s[0:1], 0, v[118:119]
	v_lshl_add_u64 v[118:119], v[188:189], 1, v[118:119]
	s_mov_b64 s[0:1], 0
	global_store_dwordx4 v[118:119], v[114:117], off offset:-2048

; template <int MODE>
; DI void gemm_epilogue(const Params& p, const f32x4 (&acc)[2][2][4][2], int pm, int pn, int wr, int wc, int fr, int fq) {
;     ...
;             if ((wc & 1) == 0) {
;               const int pos = prompt ? (row & 8191) : 1024 + (row & 63);
;               const f32x4 c0 = *(const f32x4*)(rope + pos * 16), c1 = *(const f32x4*)(rope + pos * 16 + 4);
;               const f32x4 s0 = *(const f32x4*)(rope + pos * 16 + 8), s1 = *(const f32x4*)(rope + pos * 16 + 12);
;               f32x4 pa, pb;
; #pragma unroll
;               for (int j = 0; j < 4; ++j) { pa[j] = __shfl_xor(va[j], 16); pb[j] = __shfl_xor(vb[j], 16); }
;               if (fq == 0) { for (int j = 0; j < 4; ++j) { va[j] = va[j] * c0[j] - pa[j] * s0[j]; vb[j] = vb[j] * c1[j] - pb[j] * s1[j]; } }
.LBB0_214:
	s_andn2_b64 vcc, exec, s[0:1]
	s_cbranch_vccnz .LBB0_231
	s_andn2_b64 vcc, exec, s[18:19]
	s_cbranch_vccnz .LBB0_223
	v_and_b32_e32 v106, 0x1fff, v122
	v_cndmask_b32_e64 v106, v172, v106, s[4:5]
	v_and_b32_e32 v118, 0xff, v122
	v_lshlrev_b32_e32 v118, 6, v118
	v_add_u32_e32 v118, 0x20100, v118
	ds_read_b128 v[106:109], v118 offset:48
	ds_read_b128 v[114:117], v118 offset:32
	ds_read_b128 v[110:113], v118 offset:16
	s_nop 0
	ds_read_b128 v[118:121], v118
	ds_bpermute_b32 v132, v167, v102
	ds_bpermute_b32 v128, v167, v98
	ds_bpermute_b32 v133, v167, v103
	ds_bpermute_b32 v129, v167, v99
	ds_bpermute_b32 v130, v167, v104
	ds_bpermute_b32 v123, v167, v100
	s_waitcnt lgkmcnt(0)
	ds_bpermute_b32 v139, v167, v105
	ds_bpermute_b32 v131, v167, v101
	v_cmp_lt_i32_e32 vcc, 0, v157
	s_and_saveexec_b64 s[0:1], vcc
	s_xor_b64 s[0:1], exec, s[0:1]
	s_cbranch_execz .LBB0_220
	v_cmp_eq_u32_e32 vcc, 1, v157
	v_mov_b32_e32 v127, v105
	v_mov_b32_e32 v126, v104
	v_mov_b32_e32 v125, v103
	v_mov_b32_e32 v124, v102
	v_mov_b32_e32 v137, v101
	v_mov_b32_e32 v136, v100
	v_mov_b32_e32 v135, v99
	v_mov_b32_e32 v134, v98
	s_and_saveexec_b64 s[98:99], vcc
	s_cbranch_execz .LBB0_219
	s_waitcnt lgkmcnt(0)
	v_mul_f32_e32 v126, v116, v130
	v_mul_f32_e32 v136, v108, v123
	v_mov_b32_e32 v116, v105
	v_mov_b32_e32 v138, v121
	v_mov_b32_e32 v108, v101
	v_mov_b32_e32 v130, v113
	s_waitcnt lgkmcnt(1)
	v_pk_mul_f32 v[116:117], v[116:117], v[138:139]
	s_waitcnt lgkmcnt(0)
	v_pk_mul_f32 v[108:109], v[108:109], v[130:131]
	v_pk_mul_f32 v[118:119], v[102:103], v[118:119]
	v_pk_mul_f32 v[110:111], v[98:99], v[110:111]
	v_mul_f32_e32 v120, v104, v120
	v_mul_f32_e32 v112, v100, v112
	v_mov_b32_e32 v121, v116
	v_mov_b32_e32 v127, v117
	v_mov_b32_e32 v113, v108
	v_mov_b32_e32 v137, v109
	v_pk_fma_f32 v[124:125], v[114:115], v[132:133], v[118:119]
	v_pk_add_f32 v[126:127], v[120:121], v[126:127]
	v_pk_fma_f32 v[134:135], v[106:107], v[128:129], v[110:111]
	v_pk_add_f32 v[136:137], v[112:113], v[136:137]

; template <int MODE>
; DI void gemm_epilogue(const Params& p, const f32x4 (&acc)[2][2][4][2], int pm, int pn, int wr, int wc, int fr, int fq) {
;     ...
;               for (int j = 0; j < 4; ++j) { pa[j] = __shfl_xor(va[j], 16); pb[j] = __shfl_xor(vb[j], 16); }
;               if (fq == 0) { for (int j = 0; j < 4; ++j) { va[j] = va[j] * c0[j] - pa[j] * s0[j]; vb[j] = vb[j] * c1[j] - pb[j] * s1[j]; } }
.LBB0_220:
	s_andn2_saveexec_b64 s[0:1], s[0:1]
	s_cbranch_execz .LBB0_222
	s_waitcnt lgkmcnt(0)
	v_pk_mul_f32 v[102:103], v[102:103], v[118:119]
	v_pk_mul_f32 v[98:99], v[98:99], v[110:111]
	v_mul_f32_e32 v110, v116, v130
	v_mul_f32_e32 v100, v100, v112
	v_mul_f32_e32 v112, v108, v123
	v_mov_b32_e32 v116, v105
	v_mov_b32_e32 v138, v121
	v_mov_b32_e32 v108, v101
	v_mov_b32_e32 v130, v113
	s_waitcnt lgkmcnt(1)
	v_pk_mul_f32 v[116:117], v[116:117], v[138:139]
	v_pk_fma_f32 v[124:125], v[114:115], v[132:133], v[102:103] neg_lo:[1,0,0] neg_hi:[1,0,0]
	s_waitcnt lgkmcnt(0)
	v_pk_mul_f32 v[102:103], v[108:109], v[130:131]
	v_mul_f32_e32 v104, v104, v120
	v_mov_b32_e32 v105, v116
	v_mov_b32_e32 v111, v117
	v_mov_b32_e32 v101, v102
	v_mov_b32_e32 v113, v103
	v_pk_add_f32 v[126:127], v[104:105], v[110:111] neg_lo:[0,1] neg_hi:[0,1]
	v_pk_fma_f32 v[134:135], v[106:107], v[128:129], v[98:99] neg_lo:[1,0,0] neg_hi:[1,0,0]
	v_pk_add_f32 v[136:137], v[100:101], v[112:113] neg_lo:[0,1] neg_hi:[0,1]

; DI u32 cvtpk(float lo, float hi) { u32 r; asm volatile("v_cvt_pk_bf16_f32 %0, %1, %2" : "=v"(r) : "v"(lo), "v"(hi)); return r; }
; template <int MODE>
; DI void gemm_epilogue(const Params& p, const f32x4 (&acc)[2][2][4][2], int pm, int pn, int wr, int wc, int fr, int fq) {
;     ...
;             u32x4 pk = {cvtpk(va[0], va[1]), cvtpk(va[2], va[3]), cvtpk(vb[0], vb[1]), cvtpk(vb[2], vb[3])};
;             if (cb < 1024) {
;               *(u32x4*)((u16*)(p.ws + WS_Q) + (size_t)row * 1024 + col) = pk;
;             } else {
;               const int c = col - 1024;
;               if (prompt) {
;                 float* ko = p.out + O_KP + (size_t)row * 1024 + c; *(f32x4*)ko = va; *(f32x4*)(ko + 4) = vb;
;                 *(u32x4*)((u16*)(p.ws + WS_K) + (size_t)row * 1024 + c) = pk;
;               } else {
;                 const int rs = row - TP, b = rs >> 6, t = rs & 63;
;                 float* ko = p.out + O_KS + (size_t)rs * 1024 + c; *(f32x4*)ko = va; *(f32x4*)(ko + 4) = vb;
;                 *(u32x4*)((u16*)(p.ws + WS_KC) + ((size_t)b * 1088 + 1024 + t) * 1024 + c) = pk;
;               }
.LBB0_223:
	s_andn2_b64 vcc, exec, s[10:11]
	s_mov_b64 s[0:1], -1
	s_waitcnt lgkmcnt(0)
	v_cvt_pk_bf16_f32 v106, v102, v103
	v_cvt_pk_bf16_f32 v107, v104, v105
	v_cvt_pk_bf16_f32 v108, v98, v99
	v_cvt_pk_bf16_f32 v109, v100, v101
	s_cbranch_vccnz .LBB0_229
	s_andn2_b64 vcc, exec, s[92:93]
	s_cbranch_vccnz .LBB0_226
	v_add_u32_e32 v110, 0xffff0000, v122
	v_ashrrev_i32_e32 v111, 31, v110
	v_readlane_b32 s0, v255, 21
	v_ashrrev_i32_e32 v112, 6, v110
	v_lshlrev_b64 v[110:111], 12, v[110:111]
	v_readlane_b32 s1, v255, 22
	s_nop 1
	v_lshl_add_u64 v[110:111], s[0:1], 0, v[110:111]
	v_lshl_add_u64 v[110:111], v[188:189], 2, v[110:111]
	s_movk_i32 s0, 0x440
	global_store_dwordx4 v[110:111], v[102:105], off offset:-4096
	global_store_dwordx4 v[110:111], v[98:101], off offset:-4080
	v_mad_i64_i32 v[110:111], s[0:1], v112, s0, v[172:173]
	v_readlane_b32 s0, v255, 23
	v_lshlrev_b64 v[110:111], 11, v[110:111]
	v_readlane_b32 s1, v255, 24
	s_nop 1
	v_lshl_add_u64 v[110:111], s[0:1], 0, v[110:111]
	v_lshl_add_u64 v[110:111], v[188:189], 1, v[110:111]
	s_mov_b64 s[0:1], 0
	global_store_dwordx4 v[110:111], v[106:109], off offset:-2048

; template <int MODE>
; DI void gemm_epilogue(const Params& p, const f32x4 (&acc)[2][2][4][2], int pm, int pn, int wr, int wc, int fr, int fq) {
;     ...
;             if ((wc & 1) == 0) {
;               const int pos = prompt ? (row & 8191) : 1024 + (row & 63);
;               const f32x4 c0 = *(const f32x4*)(rope + pos * 16), c1 = *(const f32x4*)(rope + pos * 16 + 4);
;               const f32x4 s0 = *(const f32x4*)(rope + pos * 16 + 8), s1 = *(const f32x4*)(rope + pos * 16 + 12);
;               f32x4 pa, pb;
; #pragma unroll
;               for (int j = 0; j < 4; ++j) { pa[j] = __shfl_xor(va[j], 16); pb[j] = __shfl_xor(vb[j], 16); }
;               if (fq == 0) { for (int j = 0; j < 4; ++j) { va[j] = va[j] * c0[j] - pa[j] * s0[j]; vb[j] = vb[j] * c1[j] - pb[j] * s1[j]; } }
.LBB0_248:
	s_andn2_b64 vcc, exec, s[0:1]
	s_cbranch_vccnz .LBB0_265
	s_andn2_b64 vcc, exec, s[18:19]
	s_cbranch_vccnz .LBB0_257
	v_and_b32_e32 v98, 0x1fcf, v116
	v_cndmask_b32_e64 v98, v160, v98, s[4:5]
	v_and_b32_e32 v110, 0xff, v116
	v_lshlrev_b32_e32 v110, 6, v110
	v_add_u32_e32 v110, 0x20100, v110
	ds_read_b128 v[98:101], v110 offset:48
	ds_read_b128 v[106:109], v110 offset:32
	ds_read_b128 v[102:105], v110 offset:16
	s_nop 0
	ds_read_b128 v[110:113], v110
	ds_bpermute_b32 v126, v167, v94
	ds_bpermute_b32 v122, v167, v90
	ds_bpermute_b32 v127, v167, v95
	ds_bpermute_b32 v123, v167, v91
	ds_bpermute_b32 v124, v167, v96
	ds_bpermute_b32 v117, v167, v92
	ds_bpermute_b32 v133, v167, v97
	ds_bpermute_b32 v125, v167, v93
	v_cmp_lt_i32_e32 vcc, 0, v157
	s_and_saveexec_b64 s[0:1], vcc
	s_xor_b64 s[0:1], exec, s[0:1]
	s_cbranch_execz .LBB0_254
	v_cmp_eq_u32_e32 vcc, 1, v157
	v_mov_b32_e32 v121, v97
	v_mov_b32_e32 v120, v96
	v_mov_b32_e32 v119, v95
	v_mov_b32_e32 v118, v94
	s_waitcnt lgkmcnt(0)
	v_mov_b32_e32 v131, v93
	v_mov_b32_e32 v130, v92
	v_mov_b32_e32 v129, v91
	v_mov_b32_e32 v128, v90
	s_and_saveexec_b64 s[98:99], vcc
	s_cbranch_execz .LBB0_253
	s_waitcnt lgkmcnt(0)
	v_mul_f32_e32 v120, v108, v124
	v_mul_f32_e32 v130, v100, v117
	v_mov_b32_e32 v108, v97
	v_mov_b32_e32 v132, v113
	v_mov_b32_e32 v100, v93
	v_mov_b32_e32 v124, v105
	v_pk_mul_f32 v[108:109], v[108:109], v[132:133]
	v_pk_mul_f32 v[100:101], v[100:101], v[124:125]
	v_pk_mul_f32 v[110:111], v[94:95], v[110:111]
	v_pk_mul_f32 v[102:103], v[90:91], v[102:103]
	v_mul_f32_e32 v112, v96, v112
	v_mul_f32_e32 v104, v92, v104
	v_mov_b32_e32 v113, v108
	v_mov_b32_e32 v121, v109
	v_mov_b32_e32 v105, v100
	v_mov_b32_e32 v131, v101
	v_pk_fma_f32 v[118:119], v[106:107], v[126:127], v[110:111]
	v_pk_add_f32 v[120:121], v[112:113], v[120:121]
	v_pk_fma_f32 v[128:129], v[98:99], v[122:123], v[102:103]
	v_pk_add_f32 v[130:131], v[104:105], v[130:131]

; template <int MODE>
; DI void gemm_epilogue(const Params& p, const f32x4 (&acc)[2][2][4][2], int pm, int pn, int wr, int wc, int fr, int fq) {
;     ...
;               for (int j = 0; j < 4; ++j) { pa[j] = __shfl_xor(va[j], 16); pb[j] = __shfl_xor(vb[j], 16); }
;               if (fq == 0) { for (int j = 0; j < 4; ++j) { va[j] = va[j] * c0[j] - pa[j] * s0[j]; vb[j] = vb[j] * c1[j] - pb[j] * s1[j]; } }
.LBB0_254:
	s_andn2_saveexec_b64 s[0:1], s[0:1]
	s_cbranch_execz .LBB0_256
	s_waitcnt lgkmcnt(0)
	v_pk_mul_f32 v[94:95], v[94:95], v[110:111]
	v_pk_mul_f32 v[90:91], v[90:91], v[102:103]
	s_waitcnt lgkmcnt(0)
	v_mul_f32_e32 v102, v108, v124
	v_mul_f32_e32 v92, v92, v104
	v_mul_f32_e32 v104, v100, v117
	v_mov_b32_e32 v108, v97
	v_mov_b32_e32 v132, v113
	v_mov_b32_e32 v100, v93
	v_mov_b32_e32 v124, v105
	v_pk_mul_f32 v[108:109], v[108:109], v[132:133]
	v_pk_fma_f32 v[118:119], v[106:107], v[126:127], v[94:95] neg_lo:[1,0,0] neg_hi:[1,0,0]
	v_pk_mul_f32 v[94:95], v[100:101], v[124:125]
	v_mul_f32_e32 v96, v96, v112
	v_mov_b32_e32 v97, v108
	v_mov_b32_e32 v103, v109
	v_mov_b32_e32 v93, v94
	v_mov_b32_e32 v105, v95
	v_pk_add_f32 v[120:121], v[96:97], v[102:103] neg_lo:[0,1] neg_hi:[0,1]
	v_pk_fma_f32 v[128:129], v[98:99], v[122:123], v[90:91] neg_lo:[1,0,0] neg_hi:[1,0,0]
	v_pk_add_f32 v[130:131], v[92:93], v[104:105] neg_lo:[0,1] neg_hi:[0,1]

; DI u32 cvtpk(float lo, float hi) { u32 r; asm volatile("v_cvt_pk_bf16_f32 %0, %1, %2" : "=v"(r) : "v"(lo), "v"(hi)); return r; }
; template <int MODE>
; DI void gemm_epilogue(const Params& p, const f32x4 (&acc)[2][2][4][2], int pm, int pn, int wr, int wc, int fr, int fq) {
;     ...
;             u32x4 pk = {cvtpk(va[0], va[1]), cvtpk(va[2], va[3]), cvtpk(vb[0], vb[1]), cvtpk(vb[2], vb[3])};
;             if (cb < 1024) {
;               *(u32x4*)((u16*)(p.ws + WS_Q) + (size_t)row * 1024 + col) = pk;
;             } else {
;               const int c = col - 1024;
;               if (prompt) {
;                 float* ko = p.out + O_KP + (size_t)row * 1024 + c; *(f32x4*)ko = va; *(f32x4*)(ko + 4) = vb;
;                 *(u32x4*)((u16*)(p.ws + WS_K) + (size_t)row * 1024 + c) = pk;
;               } else {
;                 const int rs = row - TP, b = rs >> 6, t = rs & 63;
;                 float* ko = p.out + O_KS + (size_t)rs * 1024 + c; *(f32x4*)ko = va; *(f32x4*)(ko + 4) = vb;
;                 *(u32x4*)((u16*)(p.ws + WS_KC) + ((size_t)b * 1088 + 1024 + t) * 1024 + c) = pk;
;               }
.LBB0_257:
	s_andn2_b64 vcc, exec, s[10:11]
	s_mov_b64 s[0:1], -1
	s_waitcnt lgkmcnt(0)
	v_cvt_pk_bf16_f32 v98, v94, v95
	v_cvt_pk_bf16_f32 v99, v96, v97
	v_cvt_pk_bf16_f32 v100, v90, v91
	v_cvt_pk_bf16_f32 v101, v92, v93
	s_cbranch_vccnz .LBB0_263
	s_andn2_b64 vcc, exec, s[92:93]
	s_cbranch_vccnz .LBB0_260
	v_add_u32_e32 v102, 0xffff0000, v116
	v_ashrrev_i32_e32 v103, 31, v102
	v_readlane_b32 s0, v255, 21
	v_ashrrev_i32_e32 v104, 6, v102
	v_lshlrev_b64 v[102:103], 12, v[102:103]
	v_readlane_b32 s1, v255, 22
	s_nop 1
	v_lshl_add_u64 v[102:103], s[0:1], 0, v[102:103]
	v_lshl_add_u64 v[102:103], v[188:189], 2, v[102:103]
	s_movk_i32 s0, 0x440
	global_store_dwordx4 v[102:103], v[94:97], off offset:-4096
	global_store_dwordx4 v[102:103], v[90:93], off offset:-4080
	v_mad_i64_i32 v[102:103], s[0:1], v104, s0, v[160:161]
	v_readlane_b32 s0, v255, 23
	v_lshlrev_b64 v[102:103], 11, v[102:103]
	v_readlane_b32 s1, v255, 24
	s_nop 1
	v_lshl_add_u64 v[102:103], s[0:1], 0, v[102:103]
	v_lshl_add_u64 v[102:103], v[188:189], 1, v[102:103]
	s_mov_b64 s[0:1], 0
	global_store_dwordx4 v[102:103], v[98:101], off offset:-2048

; template <int MODE>
; DI void gemm_epilogue(const Params& p, const f32x4 (&acc)[2][2][4][2], int pm, int pn, int wr, int wc, int fr, int fq) {
;     ...
;               const int pos = prompt ? (row & 8191) : 1024 + (row & 63);
;               const f32x4 c0 = *(const f32x4*)(rope + pos * 16), c1 = *(const f32x4*)(rope + pos * 16 + 4);
;               const f32x4 s0 = *(const f32x4*)(rope + pos * 16 + 8), s1 = *(const f32x4*)(rope + pos * 16 + 12);
;               f32x4 pa, pb;
; #pragma unroll
;               for (int j = 0; j < 4; ++j) { pa[j] = __shfl_xor(va[j], 16); pb[j] = __shfl_xor(vb[j], 16); }
;               if (fq == 0) { for (int j = 0; j < 4; ++j) { va[j] = va[j] * c0[j] - pa[j] * s0[j]; vb[j] = vb[j] * c1[j] - pb[j] * s1[j]; } }
;               else if (fq == 1) { for (int j = 0; j < 4; ++j) { va[j] = va[j] * c0[j] + pa[j] * s0[j]; vb[j] = vb[j] * c1[j] + pb[j] * s1[j]; } }
.LBB0_282:
	s_andn2_b64 vcc, exec, s[0:1]
	s_cbranch_vccnz .LBB0_299
	s_andn2_b64 vcc, exec, s[18:19]
	s_cbranch_vccnz .LBB0_291
	v_and_b32_e32 v90, 0x1fdf, v106
	v_cndmask_b32_e64 v90, v164, v90, s[4:5]
	v_and_b32_e32 v102, 0xff, v106
	v_lshlrev_b32_e32 v102, 6, v102
	v_add_u32_e32 v102, 0x20100, v102
	ds_read_b128 v[90:93], v102 offset:48
	ds_read_b128 v[98:101], v102 offset:32
	ds_read_b128 v[94:97], v102 offset:16
	s_nop 0
	ds_read_b128 v[102:105], v102
	ds_bpermute_b32 v118, v167, v86
	ds_bpermute_b32 v112, v167, v82
	ds_bpermute_b32 v119, v167, v87
	ds_bpermute_b32 v113, v167, v83
	ds_bpermute_b32 v116, v167, v88
	ds_bpermute_b32 v107, v167, v84
	ds_bpermute_b32 v125, v167, v89
	ds_bpermute_b32 v117, v167, v85
	v_cmp_lt_i32_e32 vcc, 0, v157
	s_and_saveexec_b64 s[0:1], vcc
	s_xor_b64 s[0:1], exec, s[0:1]
	s_cbranch_execz .LBB0_288
	v_cmp_eq_u32_e32 vcc, 1, v157
	v_mov_b32_e32 v111, v89
	v_mov_b32_e32 v110, v88
	v_mov_b32_e32 v109, v87
	v_mov_b32_e32 v108, v86
	v_mov_b32_e32 v123, v85
	v_mov_b32_e32 v122, v84
	v_mov_b32_e32 v121, v83
	v_mov_b32_e32 v120, v82
	s_and_saveexec_b64 s[98:99], vcc
	s_cbranch_execz .LBB0_287
	s_waitcnt lgkmcnt(0)
	v_mul_f32_e32 v110, v100, v116
	v_mul_f32_e32 v122, v92, v107
	v_mov_b32_e32 v100, v89
	v_mov_b32_e32 v124, v105
	v_mov_b32_e32 v92, v85
	v_mov_b32_e32 v116, v97
	v_pk_mul_f32 v[100:101], v[100:101], v[124:125]
	v_pk_mul_f32 v[92:93], v[92:93], v[116:117]
	v_pk_mul_f32 v[102:103], v[86:87], v[102:103]
	v_pk_mul_f32 v[94:95], v[82:83], v[94:95]
	v_mul_f32_e32 v104, v88, v104
	v_mul_f32_e32 v96, v84, v96
	v_mov_b32_e32 v105, v100
	v_mov_b32_e32 v111, v101
	v_mov_b32_e32 v97, v92
	v_mov_b32_e32 v123, v93
	v_pk_fma_f32 v[108:109], v[98:99], v[118:119], v[102:103]
	v_pk_add_f32 v[110:111], v[104:105], v[110:111]
	v_pk_fma_f32 v[120:121], v[90:91], v[112:113], v[94:95]
	v_pk_add_f32 v[122:123], v[96:97], v[122:123]

; template <int MODE>
; DI void gemm_epilogue(const Params& p, const f32x4 (&acc)[2][2][4][2], int pm, int pn, int wr, int wc, int fr, int fq) {
;     ...
;               if (fq == 0) { for (int j = 0; j < 4; ++j) { va[j] = va[j] * c0[j] - pa[j] * s0[j]; vb[j] = vb[j] * c1[j] - pb[j] * s1[j]; } }
.LBB0_288:
	s_andn2_saveexec_b64 s[0:1], s[0:1]
	s_cbranch_execz .LBB0_290
	s_waitcnt lgkmcnt(0)
	v_pk_mul_f32 v[86:87], v[86:87], v[102:103]
	v_pk_mul_f32 v[82:83], v[82:83], v[94:95]
	s_waitcnt lgkmcnt(0)
	v_mul_f32_e32 v94, v100, v116
	v_mul_f32_e32 v84, v84, v96
	v_mul_f32_e32 v96, v92, v107
	v_mov_b32_e32 v100, v89
	v_mov_b32_e32 v124, v105
	v_mov_b32_e32 v92, v85
	v_mov_b32_e32 v116, v97
	v_pk_mul_f32 v[100:101], v[100:101], v[124:125]
	v_pk_fma_f32 v[108:109], v[98:99], v[118:119], v[86:87] neg_lo:[1,0,0] neg_hi:[1,0,0]
	v_pk_mul_f32 v[86:87], v[92:93], v[116:117]
	v_mul_f32_e32 v88, v88, v104
	v_mov_b32_e32 v89, v100
	v_mov_b32_e32 v95, v101
	v_mov_b32_e32 v85, v86
	v_mov_b32_e32 v97, v87
	v_pk_add_f32 v[110:111], v[88:89], v[94:95] neg_lo:[0,1] neg_hi:[0,1]
	v_pk_fma_f32 v[120:121], v[90:91], v[112:113], v[82:83] neg_lo:[1,0,0] neg_hi:[1,0,0]
	v_pk_add_f32 v[122:123], v[84:85], v[96:97] neg_lo:[0,1] neg_hi:[0,1]

; DI u32 cvtpk(float lo, float hi) { u32 r; asm volatile("v_cvt_pk_bf16_f32 %0, %1, %2" : "=v"(r) : "v"(lo), "v"(hi)); return r; }
; template <int MODE>
; DI void gemm_epilogue(const Params& p, const f32x4 (&acc)[2][2][4][2], int pm, int pn, int wr, int wc, int fr, int fq) {
;     ...
;             u32x4 pk = {cvtpk(va[0], va[1]), cvtpk(va[2], va[3]), cvtpk(vb[0], vb[1]), cvtpk(vb[2], vb[3])};
;             if (cb < 1024) {
;               *(u32x4*)((u16*)(p.ws + WS_Q) + (size_t)row * 1024 + col) = pk;
;             } else {
;               const int c = col - 1024;
;               if (prompt) {
;                 float* ko = p.out + O_KP + (size_t)row * 1024 + c; *(f32x4*)ko = va; *(f32x4*)(ko + 4) = vb;
;                 *(u32x4*)((u16*)(p.ws + WS_K) + (size_t)row * 1024 + c) = pk;
;               } else {
;                 const int rs = row - TP, b = rs >> 6, t = rs & 63;
;                 float* ko = p.out + O_KS + (size_t)rs * 1024 + c; *(f32x4*)ko = va; *(f32x4*)(ko + 4) = vb;
;                 *(u32x4*)((u16*)(p.ws + WS_KC) + ((size_t)b * 1088 + 1024 + t) * 1024 + c) = pk;
.LBB0_291:
	s_andn2_b64 vcc, exec, s[10:11]
	s_mov_b64 s[0:1], -1
	s_waitcnt lgkmcnt(0)
	v_cvt_pk_bf16_f32 v90, v86, v87
	v_cvt_pk_bf16_f32 v91, v88, v89
	v_cvt_pk_bf16_f32 v92, v82, v83
	v_cvt_pk_bf16_f32 v93, v84, v85
	s_cbranch_vccnz .LBB0_297
	s_andn2_b64 vcc, exec, s[92:93]
	s_cbranch_vccnz .LBB0_294
	v_add_u32_e32 v94, 0xffff0000, v106
	v_ashrrev_i32_e32 v95, 31, v94
	v_readlane_b32 s0, v255, 21
	v_ashrrev_i32_e32 v96, 6, v94
	v_lshlrev_b64 v[94:95], 12, v[94:95]
	v_readlane_b32 s1, v255, 22
	s_nop 1
	v_lshl_add_u64 v[94:95], s[0:1], 0, v[94:95]
	v_lshl_add_u64 v[94:95], v[188:189], 2, v[94:95]
	s_movk_i32 s0, 0x440
	global_store_dwordx4 v[94:95], v[86:89], off offset:-4096
	global_store_dwordx4 v[94:95], v[82:85], off offset:-4080
	v_mad_i64_i32 v[94:95], s[0:1], v96, s0, v[164:165]
	v_readlane_b32 s0, v255, 23
	v_lshlrev_b64 v[94:95], 11, v[94:95]
	v_readlane_b32 s1, v255, 24
	s_nop 1
	v_lshl_add_u64 v[94:95], s[0:1], 0, v[94:95]
	v_lshl_add_u64 v[94:95], v[188:189], 1, v[94:95]
	s_mov_b64 s[0:1], 0
	global_store_dwordx4 v[94:95], v[90:93], off offset:-2048

; template <int MODE>
; DI void gemm_epilogue(const Params& p, const f32x4 (&acc)[2][2][4][2], int pm, int pn, int wr, int wc, int fr, int fq) {
;     ...
;               const int pos = prompt ? (row & 8191) : 1024 + (row & 63);
;               const f32x4 c0 = *(const f32x4*)(rope + pos * 16), c1 = *(const f32x4*)(rope + pos * 16 + 4);
;               const f32x4 s0 = *(const f32x4*)(rope + pos * 16 + 8), s1 = *(const f32x4*)(rope + pos * 16 + 12);
;               f32x4 pa, pb;
; #pragma unroll
;               for (int j = 0; j < 4; ++j) { pa[j] = __shfl_xor(va[j], 16); pb[j] = __shfl_xor(vb[j], 16); }
;               if (fq == 0) { for (int j = 0; j < 4; ++j) { va[j] = va[j] * c0[j] - pa[j] * s0[j]; vb[j] = vb[j] * c1[j] - pb[j] * s1[j]; } }
;               else if (fq == 1) { for (int j = 0; j < 4; ++j) { va[j] = va[j] * c0[j] + pa[j] * s0[j]; vb[j] = vb[j] * c1[j] + pb[j] * s1[j]; } }
.LBB0_316:
	s_andn2_b64 vcc, exec, s[0:1]
	s_cbranch_vccnz .LBB0_333
	s_andn2_b64 vcc, exec, s[18:19]
	s_cbranch_vccnz .LBB0_325
	v_and_b32_e32 v82, 0x1fef, v98
	v_cndmask_b32_e64 v82, v168, v82, s[4:5]
	v_and_b32_e32 v94, 0xff, v98
	v_lshlrev_b32_e32 v94, 6, v94
	v_add_u32_e32 v94, 0x20100, v94
	ds_read_b128 v[82:85], v94 offset:48
	ds_read_b128 v[90:93], v94 offset:32
	ds_read_b128 v[86:89], v94 offset:16
	s_nop 0
	ds_read_b128 v[94:97], v94
	ds_bpermute_b32 v108, v167, v78
	ds_bpermute_b32 v104, v167, v74
	ds_bpermute_b32 v109, v167, v79
	ds_bpermute_b32 v105, v167, v75
	ds_bpermute_b32 v106, v167, v80
	ds_bpermute_b32 v99, v167, v76
	s_waitcnt lgkmcnt(0)
	ds_bpermute_b32 v117, v167, v81
	ds_bpermute_b32 v107, v167, v77
	v_cmp_lt_i32_e32 vcc, 0, v157
	s_and_saveexec_b64 s[0:1], vcc
	s_xor_b64 s[0:1], exec, s[0:1]
	s_cbranch_execz .LBB0_322
	v_cmp_eq_u32_e32 vcc, 1, v157
	v_mov_b32_e32 v103, v81
	v_mov_b32_e32 v102, v80
	v_mov_b32_e32 v101, v79
	v_mov_b32_e32 v100, v78
	v_mov_b32_e32 v113, v77
	v_mov_b32_e32 v112, v76
	v_mov_b32_e32 v111, v75
	v_mov_b32_e32 v110, v74
	s_and_saveexec_b64 s[98:99], vcc
	s_cbranch_execz .LBB0_321
	s_waitcnt lgkmcnt(0)
	v_mul_f32_e32 v102, v92, v106
	v_mul_f32_e32 v112, v84, v99
	v_mov_b32_e32 v92, v81
	v_mov_b32_e32 v116, v97
	v_mov_b32_e32 v84, v77
	v_mov_b32_e32 v106, v89
	s_waitcnt lgkmcnt(1)
	v_pk_mul_f32 v[92:93], v[92:93], v[116:117]
	s_waitcnt lgkmcnt(0)
	v_pk_mul_f32 v[84:85], v[84:85], v[106:107]
	v_pk_mul_f32 v[94:95], v[78:79], v[94:95]
	v_pk_mul_f32 v[86:87], v[74:75], v[86:87]
	v_mul_f32_e32 v96, v80, v96
	v_mul_f32_e32 v88, v76, v88
	v_mov_b32_e32 v97, v92
	v_mov_b32_e32 v103, v93
	v_mov_b32_e32 v89, v84
	v_mov_b32_e32 v113, v85
	v_pk_fma_f32 v[100:101], v[90:91], v[108:109], v[94:95]
	v_pk_add_f32 v[102:103], v[96:97], v[102:103]
	v_pk_fma_f32 v[110:111], v[82:83], v[104:105], v[86:87]
	v_pk_add_f32 v[112:113], v[88:89], v[112:113]

; template <int MODE>
; DI void gemm_epilogue(const Params& p, const f32x4 (&acc)[2][2][4][2], int pm, int pn, int wr, int wc, int fr, int fq) {
;     ...
;               if (fq == 0) { for (int j = 0; j < 4; ++j) { va[j] = va[j] * c0[j] - pa[j] * s0[j]; vb[j] = vb[j] * c1[j] - pb[j] * s1[j]; } }
.LBB0_322:
	s_andn2_saveexec_b64 s[0:1], s[0:1]
	s_cbranch_execz .LBB0_324
	s_waitcnt lgkmcnt(0)
	v_pk_mul_f32 v[78:79], v[78:79], v[94:95]
	v_pk_mul_f32 v[74:75], v[74:75], v[86:87]
	v_mul_f32_e32 v86, v92, v106
	v_mul_f32_e32 v76, v76, v88
	v_mul_f32_e32 v88, v84, v99
	v_mov_b32_e32 v92, v81
	v_mov_b32_e32 v116, v97
	v_mov_b32_e32 v84, v77
	v_mov_b32_e32 v106, v89
	s_waitcnt lgkmcnt(1)
	v_pk_mul_f32 v[92:93], v[92:93], v[116:117]
	v_pk_fma_f32 v[100:101], v[90:91], v[108:109], v[78:79] neg_lo:[1,0,0] neg_hi:[1,0,0]
	s_waitcnt lgkmcnt(0)
	v_pk_mul_f32 v[78:79], v[84:85], v[106:107]
	v_mul_f32_e32 v80, v80, v96
	v_mov_b32_e32 v81, v92
	v_mov_b32_e32 v87, v93
	v_mov_b32_e32 v77, v78
	v_mov_b32_e32 v89, v79
	v_pk_add_f32 v[102:103], v[80:81], v[86:87] neg_lo:[0,1] neg_hi:[0,1]
	v_pk_fma_f32 v[110:111], v[82:83], v[104:105], v[74:75] neg_lo:[1,0,0] neg_hi:[1,0,0]
	v_pk_add_f32 v[112:113], v[76:77], v[88:89] neg_lo:[0,1] neg_hi:[0,1]

; DI u32 cvtpk(float lo, float hi) { u32 r; asm volatile("v_cvt_pk_bf16_f32 %0, %1, %2" : "=v"(r) : "v"(lo), "v"(hi)); return r; }
; template <int MODE>
; DI void gemm_epilogue(const Params& p, const f32x4 (&acc)[2][2][4][2], int pm, int pn, int wr, int wc, int fr, int fq) {
;     ...
;             u32x4 pk = {cvtpk(va[0], va[1]), cvtpk(va[2], va[3]), cvtpk(vb[0], vb[1]), cvtpk(vb[2], vb[3])};
;             if (cb < 1024) {
;               *(u32x4*)((u16*)(p.ws + WS_Q) + (size_t)row * 1024 + col) = pk;
;             } else {
;               const int c = col - 1024;
;               if (prompt) {
;                 float* ko = p.out + O_KP + (size_t)row * 1024 + c; *(f32x4*)ko = va; *(f32x4*)(ko + 4) = vb;
;                 *(u32x4*)((u16*)(p.ws + WS_K) + (size_t)row * 1024 + c) = pk;
;               } else {
;                 const int rs = row - TP, b = rs >> 6, t = rs & 63;
;                 float* ko = p.out + O_KS + (size_t)rs * 1024 + c; *(f32x4*)ko = va; *(f32x4*)(ko + 4) = vb;
;                 *(u32x4*)((u16*)(p.ws + WS_KC) + ((size_t)b * 1088 + 1024 + t) * 1024 + c) = pk;
.LBB0_325:
	s_andn2_b64 vcc, exec, s[10:11]
	s_mov_b64 s[0:1], -1
	s_waitcnt lgkmcnt(0)
	v_cvt_pk_bf16_f32 v82, v78, v79
	v_cvt_pk_bf16_f32 v83, v80, v81
	v_cvt_pk_bf16_f32 v84, v74, v75
	v_cvt_pk_bf16_f32 v85, v76, v77
	s_cbranch_vccnz .LBB0_331
	s_andn2_b64 vcc, exec, s[92:93]
	s_cbranch_vccnz .LBB0_328
	v_add_u32_e32 v86, 0xffff0000, v98
	v_ashrrev_i32_e32 v87, 31, v86
	v_readlane_b32 s0, v255, 21
	v_ashrrev_i32_e32 v88, 6, v86
	v_lshlrev_b64 v[86:87], 12, v[86:87]
	v_readlane_b32 s1, v255, 22
	s_nop 1
	v_lshl_add_u64 v[86:87], s[0:1], 0, v[86:87]
	v_lshl_add_u64 v[86:87], v[188:189], 2, v[86:87]
	s_movk_i32 s0, 0x440
	global_store_dwordx4 v[86:87], v[78:81], off offset:-4096
	global_store_dwordx4 v[86:87], v[74:77], off offset:-4080
	v_mad_i64_i32 v[86:87], s[0:1], v88, s0, v[168:169]
	v_readlane_b32 s0, v255, 23
	v_lshlrev_b64 v[86:87], 11, v[86:87]
	v_readlane_b32 s1, v255, 24
	s_nop 1
	v_lshl_add_u64 v[86:87], s[0:1], 0, v[86:87]
	v_lshl_add_u64 v[86:87], v[188:189], 1, v[86:87]
	s_mov_b64 s[0:1], 0
	global_store_dwordx4 v[86:87], v[82:85], off offset:-2048

; template <int MODE>
; DI void gemm_epilogue(const Params& p, const f32x4 (&acc)[2][2][4][2], int pm, int pn, int wr, int wc, int fr, int fq) {
;     ...
;               const int pos = prompt ? (row & 8191) : 1024 + (row & 63);
;               const f32x4 c0 = *(const f32x4*)(rope + pos * 16), c1 = *(const f32x4*)(rope + pos * 16 + 4);
;               const f32x4 s0 = *(const f32x4*)(rope + pos * 16 + 8), s1 = *(const f32x4*)(rope + pos * 16 + 12);
;               f32x4 pa, pb;
; #pragma unroll
;               for (int j = 0; j < 4; ++j) { pa[j] = __shfl_xor(va[j], 16); pb[j] = __shfl_xor(vb[j], 16); }
;               if (fq == 0) { for (int j = 0; j < 4; ++j) { va[j] = va[j] * c0[j] - pa[j] * s0[j]; vb[j] = vb[j] * c1[j] - pb[j] * s1[j]; } }
;               else if (fq == 1) { for (int j = 0; j < 4; ++j) { va[j] = va[j] * c0[j] + pa[j] * s0[j]; vb[j] = vb[j] * c1[j] + pb[j] * s1[j]; } }
.LBB0_357:
	s_andn2_b64 vcc, exec, s[0:1]
	s_cbranch_vccnz .LBB0_374
	s_andn2_b64 vcc, exec, s[18:19]
	s_cbranch_vccnz .LBB0_366
	v_and_b32_e32 v74, 0x1fff, v90
	v_cndmask_b32_e64 v74, v172, v74, s[4:5]
	v_and_b32_e32 v86, 0xff, v90
	v_lshlrev_b32_e32 v86, 6, v86
	v_add_u32_e32 v86, 0x20100, v86
	ds_read_b128 v[74:77], v86 offset:48
	ds_read_b128 v[82:85], v86 offset:32
	ds_read_b128 v[78:81], v86 offset:16
	s_nop 0
	ds_read_b128 v[86:89], v86
	ds_bpermute_b32 v100, v167, v70
	ds_bpermute_b32 v96, v167, v66
	ds_bpermute_b32 v101, v167, v71
	ds_bpermute_b32 v97, v167, v67
	ds_bpermute_b32 v98, v167, v72
	ds_bpermute_b32 v91, v167, v68
	s_waitcnt lgkmcnt(0)
	ds_bpermute_b32 v107, v167, v73
	ds_bpermute_b32 v99, v167, v69
	v_cmp_lt_i32_e32 vcc, 0, v157
	s_and_saveexec_b64 s[0:1], vcc
	s_xor_b64 s[0:1], exec, s[0:1]
	s_cbranch_execz .LBB0_363
	v_cmp_eq_u32_e32 vcc, 1, v157
	v_mov_b32_e32 v95, v73
	v_mov_b32_e32 v94, v72
	v_mov_b32_e32 v93, v71
	v_mov_b32_e32 v92, v70
	v_mov_b32_e32 v105, v69
	v_mov_b32_e32 v104, v68
	v_mov_b32_e32 v103, v67
	v_mov_b32_e32 v102, v66
	s_and_saveexec_b64 s[6:7], vcc
	s_cbranch_execz .LBB0_362
	s_waitcnt lgkmcnt(0)
	v_mul_f32_e32 v94, v84, v98
	v_mul_f32_e32 v104, v76, v91
	v_mov_b32_e32 v84, v73
	v_mov_b32_e32 v106, v89
	v_mov_b32_e32 v76, v69
	v_mov_b32_e32 v98, v81
	s_waitcnt lgkmcnt(1)
	v_pk_mul_f32 v[84:85], v[84:85], v[106:107]
	s_waitcnt lgkmcnt(0)
	v_pk_mul_f32 v[76:77], v[76:77], v[98:99]
	v_pk_mul_f32 v[86:87], v[70:71], v[86:87]
	v_pk_mul_f32 v[78:79], v[66:67], v[78:79]
	v_mul_f32_e32 v88, v72, v88
	v_mul_f32_e32 v80, v68, v80
	v_mov_b32_e32 v89, v84
	v_mov_b32_e32 v95, v85
	v_mov_b32_e32 v81, v76
	v_mov_b32_e32 v105, v77
	v_pk_fma_f32 v[92:93], v[82:83], v[100:101], v[86:87]
	v_pk_add_f32 v[94:95], v[88:89], v[94:95]
	v_pk_fma_f32 v[102:103], v[74:75], v[96:97], v[78:79]
	v_pk_add_f32 v[104:105], v[80:81], v[104:105]

; template <int MODE>
; DI void gemm_epilogue(const Params& p, const f32x4 (&acc)[2][2][4][2], int pm, int pn, int wr, int wc, int fr, int fq) {
;     ...
;               if (fq == 0) { for (int j = 0; j < 4; ++j) { va[j] = va[j] * c0[j] - pa[j] * s0[j]; vb[j] = vb[j] * c1[j] - pb[j] * s1[j]; } }
.LBB0_363:
	s_andn2_saveexec_b64 s[0:1], s[0:1]
	s_cbranch_execz .LBB0_365
	s_waitcnt lgkmcnt(0)
	v_pk_mul_f32 v[70:71], v[70:71], v[86:87]
	v_pk_mul_f32 v[66:67], v[66:67], v[78:79]
	v_mul_f32_e32 v78, v84, v98
	v_mul_f32_e32 v68, v68, v80
	v_mul_f32_e32 v80, v76, v91
	v_mov_b32_e32 v84, v73
	v_mov_b32_e32 v106, v89
	v_mov_b32_e32 v76, v69
	v_mov_b32_e32 v98, v81
	s_waitcnt lgkmcnt(1)
	v_pk_mul_f32 v[84:85], v[84:85], v[106:107]
	v_pk_fma_f32 v[92:93], v[82:83], v[100:101], v[70:71] neg_lo:[1,0,0] neg_hi:[1,0,0]
	s_waitcnt lgkmcnt(0)
	v_pk_mul_f32 v[70:71], v[76:77], v[98:99]
	v_mul_f32_e32 v72, v72, v88
	v_mov_b32_e32 v73, v84
	v_mov_b32_e32 v79, v85
	v_mov_b32_e32 v69, v70
	v_mov_b32_e32 v81, v71
	v_pk_add_f32 v[94:95], v[72:73], v[78:79] neg_lo:[0,1] neg_hi:[0,1]
	v_pk_fma_f32 v[102:103], v[74:75], v[96:97], v[66:67] neg_lo:[1,0,0] neg_hi:[1,0,0]
	v_pk_add_f32 v[104:105], v[68:69], v[80:81] neg_lo:[0,1] neg_hi:[0,1]

; DI u32 cvtpk(float lo, float hi) { u32 r; asm volatile("v_cvt_pk_bf16_f32 %0, %1, %2" : "=v"(r) : "v"(lo), "v"(hi)); return r; }
; template <int MODE>
; DI void gemm_epilogue(const Params& p, const f32x4 (&acc)[2][2][4][2], int pm, int pn, int wr, int wc, int fr, int fq) {
;     ...
;             u32x4 pk = {cvtpk(va[0], va[1]), cvtpk(va[2], va[3]), cvtpk(vb[0], vb[1]), cvtpk(vb[2], vb[3])};
;             if (cb < 1024) {
;               *(u32x4*)((u16*)(p.ws + WS_Q) + (size_t)row * 1024 + col) = pk;
;             } else {
;               const int c = col - 1024;
;               if (prompt) {
;                 float* ko = p.out + O_KP + (size_t)row * 1024 + c; *(f32x4*)ko = va; *(f32x4*)(ko + 4) = vb;
;                 *(u32x4*)((u16*)(p.ws + WS_K) + (size_t)row * 1024 + c) = pk;
;               } else {
;                 const int rs = row - TP, b = rs >> 6, t = rs & 63;
;                 float* ko = p.out + O_KS + (size_t)rs * 1024 + c; *(f32x4*)ko = va; *(f32x4*)(ko + 4) = vb;
;                 *(u32x4*)((u16*)(p.ws + WS_KC) + ((size_t)b * 1088 + 1024 + t) * 1024 + c) = pk;
.LBB0_366:
	s_andn2_b64 vcc, exec, s[10:11]
	s_mov_b64 s[0:1], -1
	s_waitcnt lgkmcnt(0)
	v_cvt_pk_bf16_f32 v74, v70, v71
	v_cvt_pk_bf16_f32 v75, v72, v73
	v_cvt_pk_bf16_f32 v76, v66, v67
	v_cvt_pk_bf16_f32 v77, v68, v69
	s_cbranch_vccnz .LBB0_372
	s_andn2_b64 vcc, exec, s[92:93]
	s_cbranch_vccnz .LBB0_369
	v_add_u32_e32 v78, 0xffff0000, v90
	v_ashrrev_i32_e32 v79, 31, v78
	v_readlane_b32 s0, v255, 21
	v_ashrrev_i32_e32 v80, 6, v78
	v_lshlrev_b64 v[78:79], 12, v[78:79]
	v_readlane_b32 s1, v255, 22
	s_nop 1
	v_lshl_add_u64 v[78:79], s[0:1], 0, v[78:79]
	v_lshl_add_u64 v[78:79], v[188:189], 2, v[78:79]
	s_movk_i32 s0, 0x440
	global_store_dwordx4 v[78:79], v[70:73], off offset:-4096
	global_store_dwordx4 v[78:79], v[66:69], off offset:-4080
	v_mad_i64_i32 v[78:79], s[0:1], v80, s0, v[172:173]
	v_readlane_b32 s0, v255, 23
	v_lshlrev_b64 v[78:79], 11, v[78:79]
	v_readlane_b32 s1, v255, 24
	s_nop 1
	v_lshl_add_u64 v[78:79], s[0:1], 0, v[78:79]
	v_lshl_add_u64 v[78:79], v[188:189], 1, v[78:79]
	s_mov_b64 s[0:1], 0
	global_store_dwordx4 v[78:79], v[74:77], off offset:-2048

; template <int MODE>
; DI void gemm_epilogue(const Params& p, const f32x4 (&acc)[2][2][4][2], int pm, int pn, int wr, int wc, int fr, int fq) {
;     ...
;               const int pos = prompt ? (row & 8191) : 1024 + (row & 63);
;               const f32x4 c0 = *(const f32x4*)(rope + pos * 16), c1 = *(const f32x4*)(rope + pos * 16 + 4);
;               const f32x4 s0 = *(const f32x4*)(rope + pos * 16 + 8), s1 = *(const f32x4*)(rope + pos * 16 + 12);
;               f32x4 pa, pb;
; #pragma unroll
;               for (int j = 0; j < 4; ++j) { pa[j] = __shfl_xor(va[j], 16); pb[j] = __shfl_xor(vb[j], 16); }
;               if (fq == 0) { for (int j = 0; j < 4; ++j) { va[j] = va[j] * c0[j] - pa[j] * s0[j]; vb[j] = vb[j] * c1[j] - pb[j] * s1[j]; } }
;               else if (fq == 1) { for (int j = 0; j < 4; ++j) { va[j] = va[j] * c0[j] + pa[j] * s0[j]; vb[j] = vb[j] * c1[j] + pb[j] * s1[j]; } }
.LBB0_392:
	v_cndmask_b32_e64 v66, 0, 1, s[18:19]
	s_andn2_b64 vcc, exec, s[6:7]
	v_cmp_ne_u32_e64 s[6:7], 1, v66
	s_cbranch_vccnz .LBB0_409
	s_and_b64 vcc, exec, s[6:7]
	s_cbranch_vccnz .LBB0_401
	v_and_b32_e32 v66, 0x1fcf, v186
	v_cndmask_b32_e64 v66, v160, v66, s[4:5]
	v_and_b32_e32 v78, 0xff, v186
	v_lshlrev_b32_e32 v78, 6, v78
	v_add_u32_e32 v78, 0x20100, v78
	ds_read_b128 v[66:69], v78 offset:48
	ds_read_b128 v[74:77], v78 offset:32
	ds_read_b128 v[70:73], v78 offset:16
	s_nop 0
	ds_read_b128 v[78:81], v78
	ds_bpermute_b32 v92, v167, v62
	ds_bpermute_b32 v88, v167, v58
	ds_bpermute_b32 v93, v167, v63
	ds_bpermute_b32 v89, v167, v59
	ds_bpermute_b32 v98, v167, v64
	ds_bpermute_b32 v90, v167, v60
	s_waitcnt lgkmcnt(0)
	ds_bpermute_b32 v99, v167, v65
	ds_bpermute_b32 v91, v167, v61
	v_cmp_lt_i32_e32 vcc, 0, v157
	s_and_saveexec_b64 s[10:11], vcc
	s_xor_b64 s[10:11], exec, s[10:11]
	s_cbranch_execz .LBB0_398
	v_cmp_eq_u32_e32 vcc, 1, v157
	v_mov_b32_e32 v87, v65
	v_mov_b32_e32 v86, v64
	v_mov_b32_e32 v85, v63
	v_mov_b32_e32 v84, v62
	v_mov_b32_e32 v97, v61
	v_mov_b32_e32 v96, v60
	v_mov_b32_e32 v95, v59
	v_mov_b32_e32 v94, v58
	s_and_saveexec_b64 s[34:35], vcc
	s_cbranch_execz .LBB0_397
	s_waitcnt lgkmcnt(0)
	v_mul_f32_e32 v86, v76, v98
	v_mul_f32_e32 v96, v68, v90
	v_mov_b32_e32 v76, v65
	v_mov_b32_e32 v98, v81
	v_mov_b32_e32 v68, v61
	v_mov_b32_e32 v90, v73
	s_waitcnt lgkmcnt(1)
	v_pk_mul_f32 v[76:77], v[76:77], v[98:99]
	s_waitcnt lgkmcnt(0)
	v_pk_mul_f32 v[68:69], v[68:69], v[90:91]
	v_pk_mul_f32 v[78:79], v[62:63], v[78:79]
	v_pk_mul_f32 v[70:71], v[58:59], v[70:71]
	v_mul_f32_e32 v80, v64, v80
	v_mul_f32_e32 v72, v60, v72
	v_mov_b32_e32 v81, v76
	v_mov_b32_e32 v87, v77
	v_mov_b32_e32 v73, v68
	v_mov_b32_e32 v97, v69
	v_pk_fma_f32 v[84:85], v[74:75], v[92:93], v[78:79]
	v_pk_add_f32 v[86:87], v[80:81], v[86:87]
	v_pk_fma_f32 v[94:95], v[66:67], v[88:89], v[70:71]
	v_pk_add_f32 v[96:97], v[72:73], v[96:97]

; template <int MODE>
; DI void gemm_epilogue(const Params& p, const f32x4 (&acc)[2][2][4][2], int pm, int pn, int wr, int wc, int fr, int fq) {
;     ...
;               if (fq == 0) { for (int j = 0; j < 4; ++j) { va[j] = va[j] * c0[j] - pa[j] * s0[j]; vb[j] = vb[j] * c1[j] - pb[j] * s1[j]; } }
.LBB0_398:
	s_andn2_saveexec_b64 s[10:11], s[10:11]
	s_cbranch_execz .LBB0_400
	s_waitcnt lgkmcnt(0)
	v_pk_mul_f32 v[62:63], v[62:63], v[78:79]
	v_pk_mul_f32 v[58:59], v[58:59], v[70:71]
	v_mul_f32_e32 v70, v76, v98
	v_mul_f32_e32 v60, v60, v72
	v_mul_f32_e32 v72, v68, v90
	v_mov_b32_e32 v76, v65
	v_mov_b32_e32 v98, v81
	v_mov_b32_e32 v68, v61
	v_mov_b32_e32 v90, v73
	s_waitcnt lgkmcnt(1)
	v_pk_mul_f32 v[76:77], v[76:77], v[98:99]
	v_pk_fma_f32 v[84:85], v[74:75], v[92:93], v[62:63] neg_lo:[1,0,0] neg_hi:[1,0,0]
	s_waitcnt lgkmcnt(0)
	v_pk_mul_f32 v[62:63], v[68:69], v[90:91]
	v_mul_f32_e32 v64, v64, v80
	v_mov_b32_e32 v65, v76
	v_mov_b32_e32 v71, v77
	v_mov_b32_e32 v61, v62
	v_mov_b32_e32 v73, v63
	v_pk_add_f32 v[86:87], v[64:65], v[70:71] neg_lo:[0,1] neg_hi:[0,1]
	v_pk_fma_f32 v[94:95], v[66:67], v[88:89], v[58:59] neg_lo:[1,0,0] neg_hi:[1,0,0]
	v_pk_add_f32 v[96:97], v[60:61], v[72:73] neg_lo:[0,1] neg_hi:[0,1]

; DI u32 cvtpk(float lo, float hi) { u32 r; asm volatile("v_cvt_pk_bf16_f32 %0, %1, %2" : "=v"(r) : "v"(lo), "v"(hi)); return r; }
; template <int MODE>
; DI void gemm_epilogue(const Params& p, const f32x4 (&acc)[2][2][4][2], int pm, int pn, int wr, int wc, int fr, int fq) {
;     ...
;             u32x4 pk = {cvtpk(va[0], va[1]), cvtpk(va[2], va[3]), cvtpk(vb[0], vb[1]), cvtpk(vb[2], vb[3])};
;             if (cb < 1024) {
;               *(u32x4*)((u16*)(p.ws + WS_Q) + (size_t)row * 1024 + col) = pk;
;             } else {
;               const int c = col - 1024;
;               if (prompt) {
;                 float* ko = p.out + O_KP + (size_t)row * 1024 + c; *(f32x4*)ko = va; *(f32x4*)(ko + 4) = vb;
;                 *(u32x4*)((u16*)(p.ws + WS_K) + (size_t)row * 1024 + c) = pk;
;               } else {
;                 const int rs = row - TP, b = rs >> 6, t = rs & 63;
;                 float* ko = p.out + O_KS + (size_t)rs * 1024 + c; *(f32x4*)ko = va; *(f32x4*)(ko + 4) = vb;
;                 *(u32x4*)((u16*)(p.ws + WS_KC) + ((size_t)b * 1088 + 1024 + t) * 1024 + c) = pk;
.LBB0_401:
	s_andn2_b64 vcc, exec, s[94:95]
	s_mov_b64 s[10:11], -1
	s_waitcnt lgkmcnt(0)
	v_cvt_pk_bf16_f32 v66, v62, v63
	v_cvt_pk_bf16_f32 v67, v64, v65
	v_cvt_pk_bf16_f32 v68, v58, v59
	v_cvt_pk_bf16_f32 v69, v60, v61
	s_cbranch_vccnz .LBB0_407
	s_andn2_b64 vcc, exec, s[92:93]
	s_cbranch_vccnz .LBB0_404
	v_add_u32_e32 v70, 0xffff0000, v186
	v_ashrrev_i32_e32 v71, 31, v70
	v_readlane_b32 s10, v255, 21
	v_ashrrev_i32_e32 v74, 6, v70
	v_lshlrev_b64 v[70:71], 12, v[70:71]
	v_readlane_b32 s11, v255, 22
	s_ashr_i32 s91, s90, 31
	v_lshl_add_u64 v[72:73], s[90:91], 0, v[180:181]
	v_lshl_add_u64 v[70:71], s[10:11], 0, v[70:71]
	v_lshl_add_u64 v[70:71], v[72:73], 2, v[70:71]
	s_movk_i32 s10, 0x440
	global_store_dwordx4 v[70:71], v[62:65], off offset:512
	global_store_dwordx4 v[70:71], v[58:61], off offset:528
	v_mad_i64_i32 v[70:71], s[10:11], v74, s10, v[160:161]
	v_readlane_b32 s10, v255, 23
	v_lshlrev_b64 v[70:71], 11, v[70:71]
	v_readlane_b32 s11, v255, 24
	s_nop 1
	v_lshl_add_u64 v[70:71], s[10:11], 0, v[70:71]
	v_lshl_add_u64 v[70:71], v[72:73], 1, v[70:71]
	s_mov_b64 s[10:11], 0
	global_store_dwordx4 v[70:71], v[66:69], off offset:256

; template <int MODE>
; DI void gemm_epilogue(const Params& p, const f32x4 (&acc)[2][2][4][2], int pm, int pn, int wr, int wc, int fr, int fq) {
;     ...
;               const int pos = prompt ? (row & 8191) : 1024 + (row & 63);
;               const f32x4 c0 = *(const f32x4*)(rope + pos * 16), c1 = *(const f32x4*)(rope + pos * 16 + 4);
;               const f32x4 s0 = *(const f32x4*)(rope + pos * 16 + 8), s1 = *(const f32x4*)(rope + pos * 16 + 12);
;               f32x4 pa, pb;
; #pragma unroll
;               for (int j = 0; j < 4; ++j) { pa[j] = __shfl_xor(va[j], 16); pb[j] = __shfl_xor(vb[j], 16); }
;               if (fq == 0) { for (int j = 0; j < 4; ++j) { va[j] = va[j] * c0[j] - pa[j] * s0[j]; vb[j] = vb[j] * c1[j] - pb[j] * s1[j]; } }
;               else if (fq == 1) { for (int j = 0; j < 4; ++j) { va[j] = va[j] * c0[j] + pa[j] * s0[j]; vb[j] = vb[j] * c1[j] + pb[j] * s1[j]; } }
.LBB0_426:
	s_andn2_b64 vcc, exec, s[0:1]
	s_cbranch_vccnz .LBB0_443
	s_and_b64 vcc, exec, s[6:7]
	s_cbranch_vccnz .LBB0_435
	v_and_b32_e32 v58, 0x1fdf, v74
	v_cndmask_b32_e64 v58, v164, v58, s[4:5]
	v_and_b32_e32 v70, 0xff, v74
	v_lshlrev_b32_e32 v70, 6, v70
	v_add_u32_e32 v70, 0x20100, v70
	ds_read_b128 v[58:61], v70 offset:48
	ds_read_b128 v[66:69], v70 offset:32
	ds_read_b128 v[62:65], v70 offset:16
	s_nop 0
	ds_read_b128 v[70:73], v70
	ds_bpermute_b32 v86, v167, v54
	ds_bpermute_b32 v80, v167, v50
	ds_bpermute_b32 v87, v167, v55
	ds_bpermute_b32 v81, v167, v51
	ds_bpermute_b32 v84, v167, v56
	ds_bpermute_b32 v75, v167, v52
	ds_bpermute_b32 v93, v167, v57
	ds_bpermute_b32 v85, v167, v53
	v_cmp_lt_i32_e32 vcc, 0, v157
	s_and_saveexec_b64 s[0:1], vcc
	s_xor_b64 s[0:1], exec, s[0:1]
	s_cbranch_execz .LBB0_432
	v_cmp_eq_u32_e32 vcc, 1, v157
	v_mov_b32_e32 v79, v57
	v_mov_b32_e32 v78, v56
	v_mov_b32_e32 v77, v55
	v_mov_b32_e32 v76, v54
	s_waitcnt lgkmcnt(0)
	v_mov_b32_e32 v91, v53
	v_mov_b32_e32 v90, v52
	v_mov_b32_e32 v89, v51
	v_mov_b32_e32 v88, v50
	s_and_saveexec_b64 s[34:35], vcc
	s_cbranch_execz .LBB0_431
	s_waitcnt lgkmcnt(0)
	v_mul_f32_e32 v78, v68, v84
	v_mul_f32_e32 v90, v60, v75
	v_mov_b32_e32 v68, v57
	v_mov_b32_e32 v92, v73
	v_mov_b32_e32 v60, v53
	v_mov_b32_e32 v84, v65
	v_pk_mul_f32 v[68:69], v[68:69], v[92:93]
	v_pk_mul_f32 v[60:61], v[60:61], v[84:85]
	v_pk_mul_f32 v[70:71], v[54:55], v[70:71]
	v_pk_mul_f32 v[62:63], v[50:51], v[62:63]
	v_mul_f32_e32 v72, v56, v72
	v_mul_f32_e32 v64, v52, v64
	v_mov_b32_e32 v73, v68
	v_mov_b32_e32 v79, v69
	v_mov_b32_e32 v65, v60
	v_mov_b32_e32 v91, v61
	v_pk_fma_f32 v[76:77], v[66:67], v[86:87], v[70:71]
	v_pk_add_f32 v[78:79], v[72:73], v[78:79]
	v_pk_fma_f32 v[88:89], v[58:59], v[80:81], v[62:63]
	v_pk_add_f32 v[90:91], v[64:65], v[90:91]

; template <int MODE>
; DI void gemm_epilogue(const Params& p, const f32x4 (&acc)[2][2][4][2], int pm, int pn, int wr, int wc, int fr, int fq) {
;     ...
;               if (fq == 0) { for (int j = 0; j < 4; ++j) { va[j] = va[j] * c0[j] - pa[j] * s0[j]; vb[j] = vb[j] * c1[j] - pb[j] * s1[j]; } }
.LBB0_432:
	s_andn2_saveexec_b64 s[0:1], s[0:1]
	s_cbranch_execz .LBB0_434
	s_waitcnt lgkmcnt(0)
	v_pk_mul_f32 v[54:55], v[54:55], v[70:71]
	v_pk_mul_f32 v[50:51], v[50:51], v[62:63]
	s_waitcnt lgkmcnt(0)
	v_mul_f32_e32 v62, v68, v84
	v_mul_f32_e32 v52, v52, v64
	v_mul_f32_e32 v64, v60, v75
	v_mov_b32_e32 v68, v57
	v_mov_b32_e32 v92, v73
	v_mov_b32_e32 v60, v53
	v_mov_b32_e32 v84, v65
	v_pk_mul_f32 v[68:69], v[68:69], v[92:93]
	v_pk_fma_f32 v[76:77], v[66:67], v[86:87], v[54:55] neg_lo:[1,0,0] neg_hi:[1,0,0]
	v_pk_mul_f32 v[54:55], v[60:61], v[84:85]
	v_mul_f32_e32 v56, v56, v72
	v_mov_b32_e32 v57, v68
	v_mov_b32_e32 v63, v69
	v_mov_b32_e32 v53, v54
	v_mov_b32_e32 v65, v55
	v_pk_add_f32 v[78:79], v[56:57], v[62:63] neg_lo:[0,1] neg_hi:[0,1]
	v_pk_fma_f32 v[88:89], v[58:59], v[80:81], v[50:51] neg_lo:[1,0,0] neg_hi:[1,0,0]
	v_pk_add_f32 v[90:91], v[52:53], v[64:65] neg_lo:[0,1] neg_hi:[0,1]

; DI u32 cvtpk(float lo, float hi) { u32 r; asm volatile("v_cvt_pk_bf16_f32 %0, %1, %2" : "=v"(r) : "v"(lo), "v"(hi)); return r; }
; template <int MODE>
; DI void gemm_epilogue(const Params& p, const f32x4 (&acc)[2][2][4][2], int pm, int pn, int wr, int wc, int fr, int fq) {
;     ...
;             u32x4 pk = {cvtpk(va[0], va[1]), cvtpk(va[2], va[3]), cvtpk(vb[0], vb[1]), cvtpk(vb[2], vb[3])};
;             if (cb < 1024) {
;               *(u32x4*)((u16*)(p.ws + WS_Q) + (size_t)row * 1024 + col) = pk;
;             } else {
;               const int c = col - 1024;
;               if (prompt) {
;                 float* ko = p.out + O_KP + (size_t)row * 1024 + c; *(f32x4*)ko = va; *(f32x4*)(ko + 4) = vb;
;                 *(u32x4*)((u16*)(p.ws + WS_K) + (size_t)row * 1024 + c) = pk;
;               } else {
;                 const int rs = row - TP, b = rs >> 6, t = rs & 63;
;                 float* ko = p.out + O_KS + (size_t)rs * 1024 + c; *(f32x4*)ko = va; *(f32x4*)(ko + 4) = vb;
;                 *(u32x4*)((u16*)(p.ws + WS_KC) + ((size_t)b * 1088 + 1024 + t) * 1024 + c) = pk;
.LBB0_435:
	s_andn2_b64 vcc, exec, s[94:95]
	s_mov_b64 s[0:1], -1
	s_waitcnt lgkmcnt(0)
	v_cvt_pk_bf16_f32 v58, v54, v55
	v_cvt_pk_bf16_f32 v59, v56, v57
	v_cvt_pk_bf16_f32 v60, v50, v51
	v_cvt_pk_bf16_f32 v61, v52, v53
	s_cbranch_vccnz .LBB0_441
	s_andn2_b64 vcc, exec, s[92:93]
	s_cbranch_vccnz .LBB0_438
	v_add_u32_e32 v62, 0xffff0000, v74
	v_ashrrev_i32_e32 v63, 31, v62
	v_readlane_b32 s0, v255, 21
	v_ashrrev_i32_e32 v66, 6, v62
	v_lshlrev_b64 v[62:63], 12, v[62:63]
	v_readlane_b32 s1, v255, 22
	s_ashr_i32 s91, s90, 31
	v_lshl_add_u64 v[64:65], s[90:91], 0, v[180:181]
	v_lshl_add_u64 v[62:63], s[0:1], 0, v[62:63]
	v_lshl_add_u64 v[62:63], v[64:65], 2, v[62:63]
	s_movk_i32 s0, 0x440
	global_store_dwordx4 v[62:63], v[54:57], off offset:512
	global_store_dwordx4 v[62:63], v[50:53], off offset:528
	v_mad_i64_i32 v[62:63], s[0:1], v66, s0, v[164:165]
	v_readlane_b32 s0, v255, 23
	v_lshlrev_b64 v[62:63], 11, v[62:63]
	v_readlane_b32 s1, v255, 24
	s_nop 1
	v_lshl_add_u64 v[62:63], s[0:1], 0, v[62:63]
	v_lshl_add_u64 v[62:63], v[64:65], 1, v[62:63]
	s_mov_b64 s[0:1], 0
	global_store_dwordx4 v[62:63], v[58:61], off offset:256

; template <int MODE>
; DI void gemm_epilogue(const Params& p, const f32x4 (&acc)[2][2][4][2], int pm, int pn, int wr, int wc, int fr, int fq) {
;     ...
;               const int pos = prompt ? (row & 8191) : 1024 + (row & 63);
;               const f32x4 c0 = *(const f32x4*)(rope + pos * 16), c1 = *(const f32x4*)(rope + pos * 16 + 4);
;               const f32x4 s0 = *(const f32x4*)(rope + pos * 16 + 8), s1 = *(const f32x4*)(rope + pos * 16 + 12);
;               f32x4 pa, pb;
; #pragma unroll
;               for (int j = 0; j < 4; ++j) { pa[j] = __shfl_xor(va[j], 16); pb[j] = __shfl_xor(vb[j], 16); }
;               if (fq == 0) { for (int j = 0; j < 4; ++j) { va[j] = va[j] * c0[j] - pa[j] * s0[j]; vb[j] = vb[j] * c1[j] - pb[j] * s1[j]; } }
;               else if (fq == 1) { for (int j = 0; j < 4; ++j) { va[j] = va[j] * c0[j] + pa[j] * s0[j]; vb[j] = vb[j] * c1[j] + pb[j] * s1[j]; } }
.LBB0_460:
	s_andn2_b64 vcc, exec, s[0:1]
	s_cbranch_vccnz .LBB0_477
	s_and_b64 vcc, exec, s[6:7]
	s_cbranch_vccnz .LBB0_469
	v_and_b32_e32 v50, 0x1fef, v66
	v_cndmask_b32_e64 v50, v168, v50, s[4:5]
	v_and_b32_e32 v62, 0xff, v66
	v_lshlrev_b32_e32 v62, 6, v62
	v_add_u32_e32 v62, 0x20100, v62
	ds_read_b128 v[50:53], v62 offset:48
	ds_read_b128 v[58:61], v62 offset:32
	ds_read_b128 v[54:57], v62 offset:16
	s_nop 0
	ds_read_b128 v[62:65], v62
	ds_bpermute_b32 v76, v167, v46
	ds_bpermute_b32 v72, v167, v42
	ds_bpermute_b32 v77, v167, v47
	ds_bpermute_b32 v73, v167, v43
	ds_bpermute_b32 v74, v167, v48
	ds_bpermute_b32 v67, v167, v44
	ds_bpermute_b32 v85, v167, v49
	ds_bpermute_b32 v75, v167, v45
	v_cmp_lt_i32_e32 vcc, 0, v157
	s_and_saveexec_b64 s[0:1], vcc
	s_xor_b64 s[0:1], exec, s[0:1]
	s_cbranch_execz .LBB0_466
	v_cmp_eq_u32_e32 vcc, 1, v157
	v_mov_b32_e32 v71, v49
	v_mov_b32_e32 v70, v48
	v_mov_b32_e32 v69, v47
	v_mov_b32_e32 v68, v46
	v_mov_b32_e32 v81, v45
	v_mov_b32_e32 v80, v44
	v_mov_b32_e32 v79, v43
	v_mov_b32_e32 v78, v42
	s_and_saveexec_b64 s[34:35], vcc
	s_cbranch_execz .LBB0_465
	s_waitcnt lgkmcnt(0)
	v_mul_f32_e32 v70, v60, v74
	v_mul_f32_e32 v80, v52, v67
	v_mov_b32_e32 v60, v49
	v_mov_b32_e32 v84, v65
	v_mov_b32_e32 v52, v45
	v_mov_b32_e32 v74, v57
	v_pk_mul_f32 v[60:61], v[60:61], v[84:85]
	v_pk_mul_f32 v[52:53], v[52:53], v[74:75]
	v_pk_mul_f32 v[62:63], v[46:47], v[62:63]
	v_pk_mul_f32 v[54:55], v[42:43], v[54:55]
	v_mul_f32_e32 v64, v48, v64
	v_mul_f32_e32 v56, v44, v56
	v_mov_b32_e32 v65, v60
	v_mov_b32_e32 v71, v61
	v_mov_b32_e32 v57, v52
	v_mov_b32_e32 v81, v53
	v_pk_fma_f32 v[68:69], v[58:59], v[76:77], v[62:63]
	v_pk_add_f32 v[70:71], v[64:65], v[70:71]
	v_pk_fma_f32 v[78:79], v[50:51], v[72:73], v[54:55]
	v_pk_add_f32 v[80:81], v[56:57], v[80:81]

; template <int MODE>
; DI void gemm_epilogue(const Params& p, const f32x4 (&acc)[2][2][4][2], int pm, int pn, int wr, int wc, int fr, int fq) {
;     ...
;               if (fq == 0) { for (int j = 0; j < 4; ++j) { va[j] = va[j] * c0[j] - pa[j] * s0[j]; vb[j] = vb[j] * c1[j] - pb[j] * s1[j]; } }
.LBB0_466:
	s_andn2_saveexec_b64 s[0:1], s[0:1]
	s_cbranch_execz .LBB0_468
	s_waitcnt lgkmcnt(0)
	v_pk_mul_f32 v[46:47], v[46:47], v[62:63]
	v_pk_mul_f32 v[42:43], v[42:43], v[54:55]
	s_waitcnt lgkmcnt(0)
	v_mul_f32_e32 v54, v60, v74
	v_mul_f32_e32 v44, v44, v56
	v_mul_f32_e32 v56, v52, v67
	v_mov_b32_e32 v60, v49
	v_mov_b32_e32 v84, v65
	v_mov_b32_e32 v52, v45
	v_mov_b32_e32 v74, v57
	v_pk_mul_f32 v[60:61], v[60:61], v[84:85]
	v_pk_fma_f32 v[68:69], v[58:59], v[76:77], v[46:47] neg_lo:[1,0,0] neg_hi:[1,0,0]
	v_pk_mul_f32 v[46:47], v[52:53], v[74:75]
	v_mul_f32_e32 v48, v48, v64
	v_mov_b32_e32 v49, v60
	v_mov_b32_e32 v55, v61
	v_mov_b32_e32 v45, v46
	v_mov_b32_e32 v57, v47
	v_pk_add_f32 v[70:71], v[48:49], v[54:55] neg_lo:[0,1] neg_hi:[0,1]
	v_pk_fma_f32 v[78:79], v[50:51], v[72:73], v[42:43] neg_lo:[1,0,0] neg_hi:[1,0,0]
	v_pk_add_f32 v[80:81], v[44:45], v[56:57] neg_lo:[0,1] neg_hi:[0,1]

; DI u32 cvtpk(float lo, float hi) { u32 r; asm volatile("v_cvt_pk_bf16_f32 %0, %1, %2" : "=v"(r) : "v"(lo), "v"(hi)); return r; }
; template <int MODE>
; DI void gemm_epilogue(const Params& p, const f32x4 (&acc)[2][2][4][2], int pm, int pn, int wr, int wc, int fr, int fq) {
;     ...
;             u32x4 pk = {cvtpk(va[0], va[1]), cvtpk(va[2], va[3]), cvtpk(vb[0], vb[1]), cvtpk(vb[2], vb[3])};
;             if (cb < 1024) {
;               *(u32x4*)((u16*)(p.ws + WS_Q) + (size_t)row * 1024 + col) = pk;
;             } else {
;               const int c = col - 1024;
;               if (prompt) {
;                 float* ko = p.out + O_KP + (size_t)row * 1024 + c; *(f32x4*)ko = va; *(f32x4*)(ko + 4) = vb;
;                 *(u32x4*)((u16*)(p.ws + WS_K) + (size_t)row * 1024 + c) = pk;
;               } else {
;                 const int rs = row - TP, b = rs >> 6, t = rs & 63;
;                 float* ko = p.out + O_KS + (size_t)rs * 1024 + c; *(f32x4*)ko = va; *(f32x4*)(ko + 4) = vb;
;                 *(u32x4*)((u16*)(p.ws + WS_KC) + ((size_t)b * 1088 + 1024 + t) * 1024 + c) = pk;
.LBB0_469:
	s_andn2_b64 vcc, exec, s[94:95]
	s_mov_b64 s[0:1], -1
	s_waitcnt lgkmcnt(0)
	v_cvt_pk_bf16_f32 v50, v46, v47
	v_cvt_pk_bf16_f32 v51, v48, v49
	v_cvt_pk_bf16_f32 v52, v42, v43
	v_cvt_pk_bf16_f32 v53, v44, v45
	s_cbranch_vccnz .LBB0_475
	s_andn2_b64 vcc, exec, s[92:93]
	s_cbranch_vccnz .LBB0_472
	v_add_u32_e32 v54, 0xffff0000, v66
	v_ashrrev_i32_e32 v55, 31, v54
	v_readlane_b32 s0, v255, 21
	v_ashrrev_i32_e32 v58, 6, v54
	v_lshlrev_b64 v[54:55], 12, v[54:55]
	v_readlane_b32 s1, v255, 22
	s_ashr_i32 s91, s90, 31
	v_lshl_add_u64 v[56:57], s[90:91], 0, v[180:181]
	v_lshl_add_u64 v[54:55], s[0:1], 0, v[54:55]
	v_lshl_add_u64 v[54:55], v[56:57], 2, v[54:55]
	s_movk_i32 s0, 0x440
	global_store_dwordx4 v[54:55], v[46:49], off offset:512
	global_store_dwordx4 v[54:55], v[42:45], off offset:528
	v_mad_i64_i32 v[54:55], s[0:1], v58, s0, v[168:169]
	v_readlane_b32 s0, v255, 23
	v_lshlrev_b64 v[54:55], 11, v[54:55]
	v_readlane_b32 s1, v255, 24
	s_nop 1
	v_lshl_add_u64 v[54:55], s[0:1], 0, v[54:55]
	v_lshl_add_u64 v[54:55], v[56:57], 1, v[54:55]
	s_mov_b64 s[0:1], 0
	global_store_dwordx4 v[54:55], v[50:53], off offset:256

; template <int MODE>
; DI void gemm_epilogue(const Params& p, const f32x4 (&acc)[2][2][4][2], int pm, int pn, int wr, int wc, int fr, int fq) {
;     ...
;               const int pos = prompt ? (row & 8191) : 1024 + (row & 63);
;               const f32x4 c0 = *(const f32x4*)(rope + pos * 16), c1 = *(const f32x4*)(rope + pos * 16 + 4);
;               const f32x4 s0 = *(const f32x4*)(rope + pos * 16 + 8), s1 = *(const f32x4*)(rope + pos * 16 + 12);
;               f32x4 pa, pb;
; #pragma unroll
;               for (int j = 0; j < 4; ++j) { pa[j] = __shfl_xor(va[j], 16); pb[j] = __shfl_xor(vb[j], 16); }
;               if (fq == 0) { for (int j = 0; j < 4; ++j) { va[j] = va[j] * c0[j] - pa[j] * s0[j]; vb[j] = vb[j] * c1[j] - pb[j] * s1[j]; } }
;               else if (fq == 1) { for (int j = 0; j < 4; ++j) { va[j] = va[j] * c0[j] + pa[j] * s0[j]; vb[j] = vb[j] * c1[j] + pb[j] * s1[j]; } }
.LBB0_501:
	s_andn2_b64 vcc, exec, s[0:1]
	s_cbranch_vccnz .LBB0_518
	s_and_b64 vcc, exec, s[6:7]
	s_cbranch_vccnz .LBB0_510
	v_and_b32_e32 v42, 0x1fff, v58
	v_cndmask_b32_e64 v42, v172, v42, s[4:5]
	v_and_b32_e32 v54, 0xff, v58
	v_lshlrev_b32_e32 v54, 6, v54
	v_add_u32_e32 v54, 0x20100, v54
	ds_read_b128 v[42:45], v54 offset:48
	ds_read_b128 v[50:53], v54 offset:32
	ds_read_b128 v[46:49], v54 offset:16
	s_nop 0
	ds_read_b128 v[54:57], v54
	ds_bpermute_b32 v68, v167, v38
	ds_bpermute_b32 v64, v167, v34
	ds_bpermute_b32 v69, v167, v39
	ds_bpermute_b32 v65, v167, v35
	ds_bpermute_b32 v66, v167, v40
	ds_bpermute_b32 v59, v167, v36
	s_waitcnt lgkmcnt(0)
	ds_bpermute_b32 v75, v167, v41
	ds_bpermute_b32 v67, v167, v37
	v_cmp_lt_i32_e32 vcc, 0, v157
	s_and_saveexec_b64 s[0:1], vcc
	s_xor_b64 s[0:1], exec, s[0:1]
	s_cbranch_execz .LBB0_507
	v_cmp_eq_u32_e32 vcc, 1, v157
	v_mov_b32_e32 v63, v41
	v_mov_b32_e32 v62, v40
	v_mov_b32_e32 v61, v39
	v_mov_b32_e32 v60, v38
	v_mov_b32_e32 v73, v37
	v_mov_b32_e32 v72, v36
	v_mov_b32_e32 v71, v35
	v_mov_b32_e32 v70, v34
	s_and_saveexec_b64 s[34:35], vcc
	s_cbranch_execz .LBB0_506
	s_waitcnt lgkmcnt(0)
	v_mul_f32_e32 v62, v52, v66
	v_mul_f32_e32 v72, v44, v59
	v_mov_b32_e32 v52, v41
	v_mov_b32_e32 v74, v57
	v_mov_b32_e32 v44, v37
	v_mov_b32_e32 v66, v49
	s_waitcnt lgkmcnt(1)
	v_pk_mul_f32 v[52:53], v[52:53], v[74:75]
	s_waitcnt lgkmcnt(0)
	v_pk_mul_f32 v[44:45], v[44:45], v[66:67]
	v_pk_mul_f32 v[54:55], v[38:39], v[54:55]
	v_pk_mul_f32 v[46:47], v[34:35], v[46:47]
	v_mul_f32_e32 v56, v40, v56
	v_mul_f32_e32 v48, v36, v48
	v_mov_b32_e32 v57, v52
	v_mov_b32_e32 v63, v53
	v_mov_b32_e32 v49, v44
	v_mov_b32_e32 v73, v45
	v_pk_fma_f32 v[60:61], v[50:51], v[68:69], v[54:55]
	v_pk_add_f32 v[62:63], v[56:57], v[62:63]
	v_pk_fma_f32 v[70:71], v[42:43], v[64:65], v[46:47]
	v_pk_add_f32 v[72:73], v[48:49], v[72:73]

; template <int MODE>
; DI void gemm_epilogue(const Params& p, const f32x4 (&acc)[2][2][4][2], int pm, int pn, int wr, int wc, int fr, int fq) {
;     ...
;               if (fq == 0) { for (int j = 0; j < 4; ++j) { va[j] = va[j] * c0[j] - pa[j] * s0[j]; vb[j] = vb[j] * c1[j] - pb[j] * s1[j]; } }
.LBB0_507:
	s_andn2_saveexec_b64 s[0:1], s[0:1]
	s_cbranch_execz .LBB0_509
	s_waitcnt lgkmcnt(0)
	v_pk_mul_f32 v[38:39], v[38:39], v[54:55]
	v_pk_mul_f32 v[34:35], v[34:35], v[46:47]
	v_mul_f32_e32 v46, v52, v66
	v_mul_f32_e32 v36, v36, v48
	v_mul_f32_e32 v48, v44, v59
	v_mov_b32_e32 v52, v41
	v_mov_b32_e32 v74, v57
	v_mov_b32_e32 v44, v37
	v_mov_b32_e32 v66, v49
	s_waitcnt lgkmcnt(1)
	v_pk_mul_f32 v[52:53], v[52:53], v[74:75]
	v_pk_fma_f32 v[60:61], v[50:51], v[68:69], v[38:39] neg_lo:[1,0,0] neg_hi:[1,0,0]
	s_waitcnt lgkmcnt(0)
	v_pk_mul_f32 v[38:39], v[44:45], v[66:67]
	v_mul_f32_e32 v40, v40, v56
	v_mov_b32_e32 v41, v52
	v_mov_b32_e32 v47, v53
	v_mov_b32_e32 v37, v38
	v_mov_b32_e32 v49, v39
	v_pk_add_f32 v[62:63], v[40:41], v[46:47] neg_lo:[0,1] neg_hi:[0,1]
	v_pk_fma_f32 v[70:71], v[42:43], v[64:65], v[34:35] neg_lo:[1,0,0] neg_hi:[1,0,0]
	v_pk_add_f32 v[72:73], v[36:37], v[48:49] neg_lo:[0,1] neg_hi:[0,1]

; DI u32 cvtpk(float lo, float hi) { u32 r; asm volatile("v_cvt_pk_bf16_f32 %0, %1, %2" : "=v"(r) : "v"(lo), "v"(hi)); return r; }
; template <int MODE>
; DI void gemm_epilogue(const Params& p, const f32x4 (&acc)[2][2][4][2], int pm, int pn, int wr, int wc, int fr, int fq) {
;     ...
;             u32x4 pk = {cvtpk(va[0], va[1]), cvtpk(va[2], va[3]), cvtpk(vb[0], vb[1]), cvtpk(vb[2], vb[3])};
;             if (cb < 1024) {
;               *(u32x4*)((u16*)(p.ws + WS_Q) + (size_t)row * 1024 + col) = pk;
;             } else {
;               const int c = col - 1024;
;               if (prompt) {
;                 float* ko = p.out + O_KP + (size_t)row * 1024 + c; *(f32x4*)ko = va; *(f32x4*)(ko + 4) = vb;
;                 *(u32x4*)((u16*)(p.ws + WS_K) + (size_t)row * 1024 + c) = pk;
;               } else {
;                 const int rs = row - TP, b = rs >> 6, t = rs & 63;
;                 float* ko = p.out + O_KS + (size_t)rs * 1024 + c; *(f32x4*)ko = va; *(f32x4*)(ko + 4) = vb;
;                 *(u32x4*)((u16*)(p.ws + WS_KC) + ((size_t)b * 1088 + 1024 + t) * 1024 + c) = pk;
.LBB0_510:
	s_andn2_b64 vcc, exec, s[94:95]
	s_mov_b64 s[0:1], -1
	s_waitcnt lgkmcnt(0)
	v_cvt_pk_bf16_f32 v42, v38, v39
	v_cvt_pk_bf16_f32 v43, v40, v41
	v_cvt_pk_bf16_f32 v44, v34, v35
	v_cvt_pk_bf16_f32 v45, v36, v37
	s_cbranch_vccnz .LBB0_516
	s_andn2_b64 vcc, exec, s[92:93]
	s_cbranch_vccnz .LBB0_513
	v_add_u32_e32 v46, 0xffff0000, v58
	v_ashrrev_i32_e32 v47, 31, v46
	v_readlane_b32 s0, v255, 21
	v_ashrrev_i32_e32 v50, 6, v46
	v_lshlrev_b64 v[46:47], 12, v[46:47]
	v_readlane_b32 s1, v255, 22
	s_ashr_i32 s91, s90, 31
	v_lshl_add_u64 v[48:49], s[90:91], 0, v[180:181]
	v_lshl_add_u64 v[46:47], s[0:1], 0, v[46:47]
	v_lshl_add_u64 v[46:47], v[48:49], 2, v[46:47]
	s_movk_i32 s0, 0x440
	global_store_dwordx4 v[46:47], v[38:41], off offset:512
	global_store_dwordx4 v[46:47], v[34:37], off offset:528
	v_mad_i64_i32 v[46:47], s[0:1], v50, s0, v[172:173]
	v_readlane_b32 s0, v255, 23
	v_lshlrev_b64 v[46:47], 11, v[46:47]
	v_readlane_b32 s1, v255, 24
	s_nop 1
	v_lshl_add_u64 v[46:47], s[0:1], 0, v[46:47]
	v_lshl_add_u64 v[46:47], v[48:49], 1, v[46:47]
	s_mov_b64 s[0:1], 0
	global_store_dwordx4 v[46:47], v[42:45], off offset:256

; template <int MODE>
; DI void gemm_epilogue(const Params& p, const f32x4 (&acc)[2][2][4][2], int pm, int pn, int wr, int wc, int fr, int fq) {
;     ...
;               const int pos = prompt ? (row & 8191) : 1024 + (row & 63);
;               const f32x4 c0 = *(const f32x4*)(rope + pos * 16), c1 = *(const f32x4*)(rope + pos * 16 + 4);
;               const f32x4 s0 = *(const f32x4*)(rope + pos * 16 + 8), s1 = *(const f32x4*)(rope + pos * 16 + 12);
;               f32x4 pa, pb;
; #pragma unroll
;               for (int j = 0; j < 4; ++j) { pa[j] = __shfl_xor(va[j], 16); pb[j] = __shfl_xor(vb[j], 16); }
;               if (fq == 0) { for (int j = 0; j < 4; ++j) { va[j] = va[j] * c0[j] - pa[j] * s0[j]; vb[j] = vb[j] * c1[j] - pb[j] * s1[j]; } }
;               else if (fq == 1) { for (int j = 0; j < 4; ++j) { va[j] = va[j] * c0[j] + pa[j] * s0[j]; vb[j] = vb[j] * c1[j] + pb[j] * s1[j]; } }
.LBB0_535:
	s_andn2_b64 vcc, exec, s[0:1]
	s_cbranch_vccnz .LBB0_552
	s_and_b64 vcc, exec, s[6:7]
	s_cbranch_vccnz .LBB0_544
	v_and_b32_e32 v34, 0x1fcf, v52
	v_cndmask_b32_e64 v34, v160, v34, s[4:5]
	v_and_b32_e32 v46, 0xff, v52
	v_lshlrev_b32_e32 v46, 6, v46
	v_add_u32_e32 v46, 0x20100, v46
	ds_read_b128 v[34:37], v46 offset:48
	ds_read_b128 v[42:45], v46 offset:32
	ds_read_b128 v[38:41], v46 offset:16
	s_nop 0
	ds_read_b128 v[46:49], v46
	ds_bpermute_b32 v62, v167, v30
	ds_bpermute_b32 v58, v167, v26
	ds_bpermute_b32 v63, v167, v31
	ds_bpermute_b32 v59, v167, v27
	ds_bpermute_b32 v60, v167, v32
	ds_bpermute_b32 v53, v167, v28
	ds_bpermute_b32 v69, v167, v33
	ds_bpermute_b32 v61, v167, v29
	v_cmp_lt_i32_e32 vcc, 0, v157
	s_and_saveexec_b64 s[0:1], vcc
	s_xor_b64 s[0:1], exec, s[0:1]
	s_cbranch_execz .LBB0_541
	v_cmp_eq_u32_e32 vcc, 1, v157
	v_mov_b32_e32 v57, v33
	v_mov_b32_e32 v56, v32
	v_mov_b32_e32 v55, v31
	v_mov_b32_e32 v54, v30
	s_waitcnt lgkmcnt(0)
	v_mov_b32_e32 v67, v29
	v_mov_b32_e32 v66, v28
	v_mov_b32_e32 v65, v27
	v_mov_b32_e32 v64, v26
	s_and_saveexec_b64 s[34:35], vcc
	s_cbranch_execz .LBB0_540
	s_waitcnt lgkmcnt(0)
	v_mul_f32_e32 v56, v44, v60
	v_mul_f32_e32 v66, v36, v53
	v_mov_b32_e32 v44, v33
	v_mov_b32_e32 v68, v49
	v_mov_b32_e32 v36, v29
	v_mov_b32_e32 v60, v41
	v_pk_mul_f32 v[44:45], v[44:45], v[68:69]
	v_pk_mul_f32 v[36:37], v[36:37], v[60:61]
	v_pk_mul_f32 v[46:47], v[30:31], v[46:47]
	v_pk_mul_f32 v[38:39], v[26:27], v[38:39]
	v_mul_f32_e32 v48, v32, v48
	v_mul_f32_e32 v40, v28, v40
	v_mov_b32_e32 v49, v44
	v_mov_b32_e32 v57, v45
	v_mov_b32_e32 v41, v36
	v_mov_b32_e32 v67, v37
	v_pk_fma_f32 v[54:55], v[42:43], v[62:63], v[46:47]
	v_pk_add_f32 v[56:57], v[48:49], v[56:57]
	v_pk_fma_f32 v[64:65], v[34:35], v[58:59], v[38:39]
	v_pk_add_f32 v[66:67], v[40:41], v[66:67]

; template <int MODE>
; DI void gemm_epilogue(const Params& p, const f32x4 (&acc)[2][2][4][2], int pm, int pn, int wr, int wc, int fr, int fq) {
;     ...
;               if (fq == 0) { for (int j = 0; j < 4; ++j) { va[j] = va[j] * c0[j] - pa[j] * s0[j]; vb[j] = vb[j] * c1[j] - pb[j] * s1[j]; } }
.LBB0_541:
	s_andn2_saveexec_b64 s[0:1], s[0:1]
	s_cbranch_execz .LBB0_543
	s_waitcnt lgkmcnt(0)
	v_pk_mul_f32 v[30:31], v[30:31], v[46:47]
	v_pk_mul_f32 v[26:27], v[26:27], v[38:39]
	s_waitcnt lgkmcnt(0)
	v_mul_f32_e32 v38, v44, v60
	v_mul_f32_e32 v28, v28, v40
	v_mul_f32_e32 v40, v36, v53
	v_mov_b32_e32 v44, v33
	v_mov_b32_e32 v68, v49
	v_mov_b32_e32 v36, v29
	v_mov_b32_e32 v60, v41
	v_pk_mul_f32 v[44:45], v[44:45], v[68:69]
	v_pk_fma_f32 v[54:55], v[42:43], v[62:63], v[30:31] neg_lo:[1,0,0] neg_hi:[1,0,0]
	v_pk_mul_f32 v[30:31], v[36:37], v[60:61]
	v_mul_f32_e32 v32, v32, v48
	v_mov_b32_e32 v33, v44
	v_mov_b32_e32 v39, v45
	v_mov_b32_e32 v29, v30
	v_mov_b32_e32 v41, v31
	v_pk_add_f32 v[56:57], v[32:33], v[38:39] neg_lo:[0,1] neg_hi:[0,1]
	v_pk_fma_f32 v[64:65], v[34:35], v[58:59], v[26:27] neg_lo:[1,0,0] neg_hi:[1,0,0]
	v_pk_add_f32 v[66:67], v[28:29], v[40:41] neg_lo:[0,1] neg_hi:[0,1]

; DI u32 cvtpk(float lo, float hi) { u32 r; asm volatile("v_cvt_pk_bf16_f32 %0, %1, %2" : "=v"(r) : "v"(lo), "v"(hi)); return r; }
; template <int MODE>
; DI void gemm_epilogue(const Params& p, const f32x4 (&acc)[2][2][4][2], int pm, int pn, int wr, int wc, int fr, int fq) {
;     ...
;             u32x4 pk = {cvtpk(va[0], va[1]), cvtpk(va[2], va[3]), cvtpk(vb[0], vb[1]), cvtpk(vb[2], vb[3])};
;             if (cb < 1024) {
;               *(u32x4*)((u16*)(p.ws + WS_Q) + (size_t)row * 1024 + col) = pk;
;             } else {
;               const int c = col - 1024;
;               if (prompt) {
;                 float* ko = p.out + O_KP + (size_t)row * 1024 + c; *(f32x4*)ko = va; *(f32x4*)(ko + 4) = vb;
;                 *(u32x4*)((u16*)(p.ws + WS_K) + (size_t)row * 1024 + c) = pk;
;               } else {
;                 const int rs = row - TP, b = rs >> 6, t = rs & 63;
;                 float* ko = p.out + O_KS + (size_t)rs * 1024 + c; *(f32x4*)ko = va; *(f32x4*)(ko + 4) = vb;
;                 *(u32x4*)((u16*)(p.ws + WS_KC) + ((size_t)b * 1088 + 1024 + t) * 1024 + c) = pk;
.LBB0_544:
	s_andn2_b64 vcc, exec, s[94:95]
	s_mov_b64 s[0:1], -1
	s_waitcnt lgkmcnt(0)
	v_cvt_pk_bf16_f32 v34, v30, v31
	v_cvt_pk_bf16_f32 v35, v32, v33
	v_cvt_pk_bf16_f32 v36, v26, v27
	v_cvt_pk_bf16_f32 v37, v28, v29
	s_cbranch_vccnz .LBB0_550
	s_andn2_b64 vcc, exec, s[92:93]
	s_cbranch_vccnz .LBB0_547
	v_add_u32_e32 v38, 0xffff0000, v52
	v_ashrrev_i32_e32 v39, 31, v38
	v_readlane_b32 s0, v255, 21
	v_ashrrev_i32_e32 v42, 6, v38
	v_lshlrev_b64 v[38:39], 12, v[38:39]
	v_readlane_b32 s1, v255, 22
	s_ashr_i32 s91, s90, 31
	v_lshl_add_u64 v[40:41], s[90:91], 0, v[180:181]
	v_lshl_add_u64 v[38:39], s[0:1], 0, v[38:39]
	v_lshl_add_u64 v[38:39], v[40:41], 2, v[38:39]
	s_movk_i32 s0, 0x440
	global_store_dwordx4 v[38:39], v[30:33], off offset:512
	global_store_dwordx4 v[38:39], v[26:29], off offset:528
	v_mad_i64_i32 v[38:39], s[0:1], v42, s0, v[160:161]
	v_readlane_b32 s0, v255, 23
	v_lshlrev_b64 v[38:39], 11, v[38:39]
	v_readlane_b32 s1, v255, 24
	s_nop 1
	v_lshl_add_u64 v[38:39], s[0:1], 0, v[38:39]
	v_lshl_add_u64 v[38:39], v[40:41], 1, v[38:39]
	s_mov_b64 s[0:1], 0
	global_store_dwordx4 v[38:39], v[34:37], off offset:256

; template <int MODE>
; DI void gemm_epilogue(const Params& p, const f32x4 (&acc)[2][2][4][2], int pm, int pn, int wr, int wc, int fr, int fq) {
;     ...
;               const int pos = prompt ? (row & 8191) : 1024 + (row & 63);
;               const f32x4 c0 = *(const f32x4*)(rope + pos * 16), c1 = *(const f32x4*)(rope + pos * 16 + 4);
;               const f32x4 s0 = *(const f32x4*)(rope + pos * 16 + 8), s1 = *(const f32x4*)(rope + pos * 16 + 12);
;               f32x4 pa, pb;
; #pragma unroll
;               for (int j = 0; j < 4; ++j) { pa[j] = __shfl_xor(va[j], 16); pb[j] = __shfl_xor(vb[j], 16); }
;               if (fq == 0) { for (int j = 0; j < 4; ++j) { va[j] = va[j] * c0[j] - pa[j] * s0[j]; vb[j] = vb[j] * c1[j] - pb[j] * s1[j]; } }
;               else if (fq == 1) { for (int j = 0; j < 4; ++j) { va[j] = va[j] * c0[j] + pa[j] * s0[j]; vb[j] = vb[j] * c1[j] + pb[j] * s1[j]; } }
.LBB0_569:
	s_andn2_b64 vcc, exec, s[0:1]
	s_cbranch_vccnz .LBB0_586
	s_and_b64 vcc, exec, s[6:7]
	s_cbranch_vccnz .LBB0_578
	v_and_b32_e32 v26, 0x1fdf, v42
	v_cndmask_b32_e64 v26, v164, v26, s[4:5]
	v_and_b32_e32 v38, 0xff, v42
	v_lshlrev_b32_e32 v38, 6, v38
	v_add_u32_e32 v38, 0x20100, v38
	ds_read_b128 v[26:29], v38 offset:48
	ds_read_b128 v[34:37], v38 offset:32
	ds_read_b128 v[30:33], v38 offset:16
	s_nop 0
	ds_read_b128 v[38:41], v38
	ds_bpermute_b32 v54, v167, v22
	ds_bpermute_b32 v48, v167, v18
	ds_bpermute_b32 v55, v167, v23
	ds_bpermute_b32 v49, v167, v19
	ds_bpermute_b32 v52, v167, v24
	ds_bpermute_b32 v43, v167, v20
	ds_bpermute_b32 v61, v167, v25
	ds_bpermute_b32 v53, v167, v21
	v_cmp_lt_i32_e32 vcc, 0, v157
	s_and_saveexec_b64 s[0:1], vcc
	s_xor_b64 s[0:1], exec, s[0:1]
	s_cbranch_execz .LBB0_575
	v_cmp_eq_u32_e32 vcc, 1, v157
	v_mov_b32_e32 v47, v25
	v_mov_b32_e32 v46, v24
	v_mov_b32_e32 v45, v23
	v_mov_b32_e32 v44, v22
	v_mov_b32_e32 v59, v21
	v_mov_b32_e32 v58, v20
	v_mov_b32_e32 v57, v19
	v_mov_b32_e32 v56, v18
	s_and_saveexec_b64 s[34:35], vcc
	s_cbranch_execz .LBB0_574
	s_waitcnt lgkmcnt(0)
	v_mul_f32_e32 v46, v36, v52
	v_mul_f32_e32 v58, v28, v43
	v_mov_b32_e32 v36, v25
	v_mov_b32_e32 v60, v41
	v_mov_b32_e32 v28, v21
	v_mov_b32_e32 v52, v33
	v_pk_mul_f32 v[36:37], v[36:37], v[60:61]
	v_pk_mul_f32 v[28:29], v[28:29], v[52:53]
	v_pk_mul_f32 v[38:39], v[22:23], v[38:39]
	v_pk_mul_f32 v[30:31], v[18:19], v[30:31]
	v_mul_f32_e32 v40, v24, v40
	v_mul_f32_e32 v32, v20, v32
	v_mov_b32_e32 v41, v36
	v_mov_b32_e32 v47, v37
	v_mov_b32_e32 v33, v28
	v_mov_b32_e32 v59, v29
	v_pk_fma_f32 v[44:45], v[34:35], v[54:55], v[38:39]
	v_pk_add_f32 v[46:47], v[40:41], v[46:47]
	v_pk_fma_f32 v[56:57], v[26:27], v[48:49], v[30:31]
	v_pk_add_f32 v[58:59], v[32:33], v[58:59]

; template <int MODE>
; DI void gemm_epilogue(const Params& p, const f32x4 (&acc)[2][2][4][2], int pm, int pn, int wr, int wc, int fr, int fq) {
;     ...
;               if (fq == 0) { for (int j = 0; j < 4; ++j) { va[j] = va[j] * c0[j] - pa[j] * s0[j]; vb[j] = vb[j] * c1[j] - pb[j] * s1[j]; } }
.LBB0_575:
	s_andn2_saveexec_b64 s[0:1], s[0:1]
	s_cbranch_execz .LBB0_577
	s_waitcnt lgkmcnt(0)
	v_pk_mul_f32 v[22:23], v[22:23], v[38:39]
	v_pk_mul_f32 v[18:19], v[18:19], v[30:31]
	s_waitcnt lgkmcnt(0)
	v_mul_f32_e32 v30, v36, v52
	v_mul_f32_e32 v20, v20, v32
	v_mul_f32_e32 v32, v28, v43
	v_mov_b32_e32 v36, v25
	v_mov_b32_e32 v60, v41
	v_mov_b32_e32 v28, v21
	v_mov_b32_e32 v52, v33
	v_pk_mul_f32 v[36:37], v[36:37], v[60:61]
	v_pk_fma_f32 v[44:45], v[34:35], v[54:55], v[22:23] neg_lo:[1,0,0] neg_hi:[1,0,0]
	v_pk_mul_f32 v[22:23], v[28:29], v[52:53]
	v_mul_f32_e32 v24, v24, v40
	v_mov_b32_e32 v25, v36
	v_mov_b32_e32 v31, v37
	v_mov_b32_e32 v21, v22
	v_mov_b32_e32 v33, v23
	v_pk_add_f32 v[46:47], v[24:25], v[30:31] neg_lo:[0,1] neg_hi:[0,1]
	v_pk_fma_f32 v[56:57], v[26:27], v[48:49], v[18:19] neg_lo:[1,0,0] neg_hi:[1,0,0]
	v_pk_add_f32 v[58:59], v[20:21], v[32:33] neg_lo:[0,1] neg_hi:[0,1]

; DI u32 cvtpk(float lo, float hi) { u32 r; asm volatile("v_cvt_pk_bf16_f32 %0, %1, %2" : "=v"(r) : "v"(lo), "v"(hi)); return r; }
; template <int MODE>
; DI void gemm_epilogue(const Params& p, const f32x4 (&acc)[2][2][4][2], int pm, int pn, int wr, int wc, int fr, int fq) {
;     ...
;             u32x4 pk = {cvtpk(va[0], va[1]), cvtpk(va[2], va[3]), cvtpk(vb[0], vb[1]), cvtpk(vb[2], vb[3])};
;             if (cb < 1024) {
;               *(u32x4*)((u16*)(p.ws + WS_Q) + (size_t)row * 1024 + col) = pk;
;             } else {
;               const int c = col - 1024;
;               if (prompt) {
;                 float* ko = p.out + O_KP + (size_t)row * 1024 + c; *(f32x4*)ko = va; *(f32x4*)(ko + 4) = vb;
;                 *(u32x4*)((u16*)(p.ws + WS_K) + (size_t)row * 1024 + c) = pk;
;               } else {
;                 const int rs = row - TP, b = rs >> 6, t = rs & 63;
;                 float* ko = p.out + O_KS + (size_t)rs * 1024 + c; *(f32x4*)ko = va; *(f32x4*)(ko + 4) = vb;
;                 *(u32x4*)((u16*)(p.ws + WS_KC) + ((size_t)b * 1088 + 1024 + t) * 1024 + c) = pk;
.LBB0_578:
	s_andn2_b64 vcc, exec, s[94:95]
	s_mov_b64 s[0:1], -1
	s_waitcnt lgkmcnt(0)
	v_cvt_pk_bf16_f32 v26, v22, v23
	v_cvt_pk_bf16_f32 v27, v24, v25
	v_cvt_pk_bf16_f32 v28, v18, v19
	v_cvt_pk_bf16_f32 v29, v20, v21
	s_cbranch_vccnz .LBB0_584
	s_andn2_b64 vcc, exec, s[92:93]
	s_cbranch_vccnz .LBB0_581
	v_add_u32_e32 v30, 0xffff0000, v42
	v_ashrrev_i32_e32 v31, 31, v30
	v_readlane_b32 s0, v255, 21
	v_ashrrev_i32_e32 v34, 6, v30
	v_lshlrev_b64 v[30:31], 12, v[30:31]
	v_readlane_b32 s1, v255, 22
	s_ashr_i32 s91, s90, 31
	v_lshl_add_u64 v[32:33], s[90:91], 0, v[180:181]
	v_lshl_add_u64 v[30:31], s[0:1], 0, v[30:31]
	v_lshl_add_u64 v[30:31], v[32:33], 2, v[30:31]
	s_movk_i32 s0, 0x440
	global_store_dwordx4 v[30:31], v[22:25], off offset:512
	global_store_dwordx4 v[30:31], v[18:21], off offset:528
	v_mad_i64_i32 v[30:31], s[0:1], v34, s0, v[164:165]
	v_readlane_b32 s0, v255, 23
	v_lshlrev_b64 v[30:31], 11, v[30:31]
	v_readlane_b32 s1, v255, 24
	s_nop 1
	v_lshl_add_u64 v[30:31], s[0:1], 0, v[30:31]
	v_lshl_add_u64 v[30:31], v[32:33], 1, v[30:31]
	s_mov_b64 s[0:1], 0
	global_store_dwordx4 v[30:31], v[26:29], off offset:256

; template <int MODE>
; DI void gemm_epilogue(const Params& p, const f32x4 (&acc)[2][2][4][2], int pm, int pn, int wr, int wc, int fr, int fq) {
;     ...
;               const int pos = prompt ? (row & 8191) : 1024 + (row & 63);
;               const f32x4 c0 = *(const f32x4*)(rope + pos * 16), c1 = *(const f32x4*)(rope + pos * 16 + 4);
;               const f32x4 s0 = *(const f32x4*)(rope + pos * 16 + 8), s1 = *(const f32x4*)(rope + pos * 16 + 12);
;               f32x4 pa, pb;
; #pragma unroll
;               for (int j = 0; j < 4; ++j) { pa[j] = __shfl_xor(va[j], 16); pb[j] = __shfl_xor(vb[j], 16); }
;               if (fq == 0) { for (int j = 0; j < 4; ++j) { va[j] = va[j] * c0[j] - pa[j] * s0[j]; vb[j] = vb[j] * c1[j] - pb[j] * s1[j]; } }
;               else if (fq == 1) { for (int j = 0; j < 4; ++j) { va[j] = va[j] * c0[j] + pa[j] * s0[j]; vb[j] = vb[j] * c1[j] + pb[j] * s1[j]; } }
.LBB0_603:
	s_andn2_b64 vcc, exec, s[0:1]
	s_cbranch_vccnz .LBB0_620
	s_and_b64 vcc, exec, s[6:7]
	s_cbranch_vccnz .LBB0_612
	v_and_b32_e32 v18, 0x1fef, v34
	v_cndmask_b32_e64 v18, v168, v18, s[4:5]
	v_and_b32_e32 v30, 0xff, v34
	v_lshlrev_b32_e32 v30, 6, v30
	v_add_u32_e32 v30, 0x20100, v30
	ds_read_b128 v[18:21], v30 offset:48
	ds_read_b128 v[26:29], v30 offset:32
	ds_read_b128 v[22:25], v30 offset:16
	s_nop 0
	ds_read_b128 v[30:33], v30
	ds_bpermute_b32 v44, v167, v14
	ds_bpermute_b32 v40, v167, v10
	ds_bpermute_b32 v45, v167, v15
	ds_bpermute_b32 v41, v167, v11
	ds_bpermute_b32 v42, v167, v16
	ds_bpermute_b32 v35, v167, v12
	s_waitcnt lgkmcnt(0)
	ds_bpermute_b32 v53, v167, v17
	ds_bpermute_b32 v43, v167, v13
	v_cmp_lt_i32_e32 vcc, 0, v157
	s_and_saveexec_b64 s[0:1], vcc
	s_xor_b64 s[0:1], exec, s[0:1]
	s_cbranch_execz .LBB0_609
	v_cmp_eq_u32_e32 vcc, 1, v157
	v_mov_b32_e32 v39, v17
	v_mov_b32_e32 v38, v16
	v_mov_b32_e32 v37, v15
	v_mov_b32_e32 v36, v14
	v_mov_b32_e32 v49, v13
	v_mov_b32_e32 v48, v12
	v_mov_b32_e32 v47, v11
	v_mov_b32_e32 v46, v10
	s_and_saveexec_b64 s[34:35], vcc
	s_cbranch_execz .LBB0_608
	s_waitcnt lgkmcnt(0)
	v_mul_f32_e32 v38, v28, v42
	v_mul_f32_e32 v48, v20, v35
	v_mov_b32_e32 v28, v17
	v_mov_b32_e32 v52, v33
	v_mov_b32_e32 v20, v13
	v_mov_b32_e32 v42, v25
	s_waitcnt lgkmcnt(1)
	v_pk_mul_f32 v[28:29], v[28:29], v[52:53]
	s_waitcnt lgkmcnt(0)
	v_pk_mul_f32 v[20:21], v[20:21], v[42:43]
	v_pk_mul_f32 v[30:31], v[14:15], v[30:31]
	v_pk_mul_f32 v[22:23], v[10:11], v[22:23]
	v_mul_f32_e32 v32, v16, v32
	v_mul_f32_e32 v24, v12, v24
	v_mov_b32_e32 v33, v28
	v_mov_b32_e32 v39, v29
	v_mov_b32_e32 v25, v20
	v_mov_b32_e32 v49, v21
	v_pk_fma_f32 v[36:37], v[26:27], v[44:45], v[30:31]
	v_pk_add_f32 v[38:39], v[32:33], v[38:39]
	v_pk_fma_f32 v[46:47], v[18:19], v[40:41], v[22:23]
	v_pk_add_f32 v[48:49], v[24:25], v[48:49]

; template <int MODE>
; DI void gemm_epilogue(const Params& p, const f32x4 (&acc)[2][2][4][2], int pm, int pn, int wr, int wc, int fr, int fq) {
;     ...
;               if (fq == 0) { for (int j = 0; j < 4; ++j) { va[j] = va[j] * c0[j] - pa[j] * s0[j]; vb[j] = vb[j] * c1[j] - pb[j] * s1[j]; } }
.LBB0_609:
	s_andn2_saveexec_b64 s[0:1], s[0:1]
	s_cbranch_execz .LBB0_611
	s_waitcnt lgkmcnt(0)
	v_pk_mul_f32 v[14:15], v[14:15], v[30:31]
	v_pk_mul_f32 v[10:11], v[10:11], v[22:23]
	v_mul_f32_e32 v22, v28, v42
	v_mul_f32_e32 v12, v12, v24
	v_mul_f32_e32 v24, v20, v35
	v_mov_b32_e32 v28, v17
	v_mov_b32_e32 v52, v33
	v_mov_b32_e32 v20, v13
	v_mov_b32_e32 v42, v25
	s_waitcnt lgkmcnt(1)
	v_pk_mul_f32 v[28:29], v[28:29], v[52:53]
	v_pk_fma_f32 v[36:37], v[26:27], v[44:45], v[14:15] neg_lo:[1,0,0] neg_hi:[1,0,0]
	s_waitcnt lgkmcnt(0)
	v_pk_mul_f32 v[14:15], v[20:21], v[42:43]
	v_mul_f32_e32 v16, v16, v32
	v_mov_b32_e32 v17, v28
	v_mov_b32_e32 v23, v29
	v_mov_b32_e32 v13, v14
	v_mov_b32_e32 v25, v15
	v_pk_add_f32 v[38:39], v[16:17], v[22:23] neg_lo:[0,1] neg_hi:[0,1]
	v_pk_fma_f32 v[46:47], v[18:19], v[40:41], v[10:11] neg_lo:[1,0,0] neg_hi:[1,0,0]
	v_pk_add_f32 v[48:49], v[12:13], v[24:25] neg_lo:[0,1] neg_hi:[0,1]

; DI u32 cvtpk(float lo, float hi) { u32 r; asm volatile("v_cvt_pk_bf16_f32 %0, %1, %2" : "=v"(r) : "v"(lo), "v"(hi)); return r; }
; template <int MODE>
; DI void gemm_epilogue(const Params& p, const f32x4 (&acc)[2][2][4][2], int pm, int pn, int wr, int wc, int fr, int fq) {
;     ...
;             u32x4 pk = {cvtpk(va[0], va[1]), cvtpk(va[2], va[3]), cvtpk(vb[0], vb[1]), cvtpk(vb[2], vb[3])};
;             if (cb < 1024) {
;               *(u32x4*)((u16*)(p.ws + WS_Q) + (size_t)row * 1024 + col) = pk;
;             } else {
;               const int c = col - 1024;
;               if (prompt) {
;                 float* ko = p.out + O_KP + (size_t)row * 1024 + c; *(f32x4*)ko = va; *(f32x4*)(ko + 4) = vb;
;                 *(u32x4*)((u16*)(p.ws + WS_K) + (size_t)row * 1024 + c) = pk;
;               } else {
;                 const int rs = row - TP, b = rs >> 6, t = rs & 63;
;                 float* ko = p.out + O_KS + (size_t)rs * 1024 + c; *(f32x4*)ko = va; *(f32x4*)(ko + 4) = vb;
;                 *(u32x4*)((u16*)(p.ws + WS_KC) + ((size_t)b * 1088 + 1024 + t) * 1024 + c) = pk;
.LBB0_612:
	s_andn2_b64 vcc, exec, s[94:95]
	s_mov_b64 s[0:1], -1
	s_waitcnt lgkmcnt(0)
	v_cvt_pk_bf16_f32 v18, v14, v15
	v_cvt_pk_bf16_f32 v19, v16, v17
	v_cvt_pk_bf16_f32 v20, v10, v11
	v_cvt_pk_bf16_f32 v21, v12, v13
	s_cbranch_vccnz .LBB0_618
	s_andn2_b64 vcc, exec, s[92:93]
	s_cbranch_vccnz .LBB0_615
	v_add_u32_e32 v22, 0xffff0000, v34
	v_ashrrev_i32_e32 v23, 31, v22
	v_readlane_b32 s0, v255, 21
	v_ashrrev_i32_e32 v26, 6, v22
	v_lshlrev_b64 v[22:23], 12, v[22:23]
	v_readlane_b32 s1, v255, 22
	s_ashr_i32 s91, s90, 31
	v_lshl_add_u64 v[24:25], s[90:91], 0, v[180:181]
	v_lshl_add_u64 v[22:23], s[0:1], 0, v[22:23]
	v_lshl_add_u64 v[22:23], v[24:25], 2, v[22:23]
	s_movk_i32 s0, 0x440
	global_store_dwordx4 v[22:23], v[14:17], off offset:512
	global_store_dwordx4 v[22:23], v[10:13], off offset:528
	v_mad_i64_i32 v[22:23], s[0:1], v26, s0, v[168:169]
	v_readlane_b32 s0, v255, 23
	v_lshlrev_b64 v[22:23], 11, v[22:23]
	v_readlane_b32 s1, v255, 24
	s_nop 1
	v_lshl_add_u64 v[22:23], s[0:1], 0, v[22:23]
	v_lshl_add_u64 v[22:23], v[24:25], 1, v[22:23]
	s_mov_b64 s[0:1], 0
	global_store_dwordx4 v[22:23], v[18:21], off offset:256

; template <int MODE>
; DI void gemm_epilogue(const Params& p, const f32x4 (&acc)[2][2][4][2], int pm, int pn, int wr, int wc, int fr, int fq) {
;     ...
;               const int pos = prompt ? (row & 8191) : 1024 + (row & 63);
;               const f32x4 c0 = *(const f32x4*)(rope + pos * 16), c1 = *(const f32x4*)(rope + pos * 16 + 4);
;               const f32x4 s0 = *(const f32x4*)(rope + pos * 16 + 8), s1 = *(const f32x4*)(rope + pos * 16 + 12);
;               f32x4 pa, pb;
; #pragma unroll
;               for (int j = 0; j < 4; ++j) { pa[j] = __shfl_xor(va[j], 16); pb[j] = __shfl_xor(vb[j], 16); }
;               if (fq == 0) { for (int j = 0; j < 4; ++j) { va[j] = va[j] * c0[j] - pa[j] * s0[j]; vb[j] = vb[j] * c1[j] - pb[j] * s1[j]; } }
;               else if (fq == 1) { for (int j = 0; j < 4; ++j) { va[j] = va[j] * c0[j] + pa[j] * s0[j]; vb[j] = vb[j] * c1[j] + pb[j] * s1[j]; } }
.LBB0_644:
	s_andn2_b64 vcc, exec, s[0:1]
	s_cbranch_vccnz .LBB0_79
	s_and_b64 vcc, exec, s[6:7]
	s_cbranch_vccnz .LBB0_653
	v_and_b32_e32 v10, 0x1fff, v26
	v_cndmask_b32_e64 v10, v172, v10, s[4:5]
	v_and_b32_e32 v22, 0xff, v26
	v_lshlrev_b32_e32 v22, 6, v22
	v_add_u32_e32 v22, 0x20100, v22
	ds_read_b128 v[10:13], v22 offset:48
	ds_read_b128 v[18:21], v22 offset:32
	ds_read_b128 v[14:17], v22 offset:16
	s_nop 0
	ds_read_b128 v[22:25], v22
	ds_bpermute_b32 v36, v167, v6
	ds_bpermute_b32 v32, v167, v2
	ds_bpermute_b32 v37, v167, v7
	ds_bpermute_b32 v33, v167, v3
	ds_bpermute_b32 v34, v167, v8
	ds_bpermute_b32 v27, v167, v4
	s_waitcnt lgkmcnt(0)
	ds_bpermute_b32 v43, v167, v9
	ds_bpermute_b32 v35, v167, v5
	v_cmp_lt_i32_e32 vcc, 0, v157
	s_and_saveexec_b64 s[0:1], vcc
	s_xor_b64 s[0:1], exec, s[0:1]
	s_cbranch_execz .LBB0_650
	v_cmp_eq_u32_e32 vcc, 1, v157
	v_mov_b32_e32 v31, v9
	v_mov_b32_e32 v30, v8
	v_mov_b32_e32 v29, v7
	v_mov_b32_e32 v28, v6
	v_mov_b32_e32 v41, v5
	v_mov_b32_e32 v40, v4
	v_mov_b32_e32 v39, v3
	v_mov_b32_e32 v38, v2
	s_and_saveexec_b64 s[4:5], vcc
	s_cbranch_execz .LBB0_649
	s_waitcnt lgkmcnt(0)
	v_mul_f32_e32 v30, v20, v34
	v_mul_f32_e32 v40, v12, v27
	v_mov_b32_e32 v20, v9
	v_mov_b32_e32 v42, v25
	v_mov_b32_e32 v12, v5
	v_mov_b32_e32 v34, v17
	s_waitcnt lgkmcnt(1)
	v_pk_mul_f32 v[20:21], v[20:21], v[42:43]
	s_waitcnt lgkmcnt(0)
	v_pk_mul_f32 v[12:13], v[12:13], v[34:35]
	v_pk_mul_f32 v[22:23], v[6:7], v[22:23]
	v_pk_mul_f32 v[14:15], v[2:3], v[14:15]
	v_mul_f32_e32 v24, v8, v24
	v_mul_f32_e32 v16, v4, v16
	v_mov_b32_e32 v25, v20
	v_mov_b32_e32 v31, v21
	v_mov_b32_e32 v17, v12
	v_mov_b32_e32 v41, v13
	v_pk_fma_f32 v[28:29], v[18:19], v[36:37], v[22:23]
	v_pk_add_f32 v[30:31], v[24:25], v[30:31]
	v_pk_fma_f32 v[38:39], v[10:11], v[32:33], v[14:15]
	v_pk_add_f32 v[40:41], v[16:17], v[40:41]

; template <int MODE>
; DI void gemm_epilogue(const Params& p, const f32x4 (&acc)[2][2][4][2], int pm, int pn, int wr, int wc, int fr, int fq) {
;     ...
;               if (fq == 0) { for (int j = 0; j < 4; ++j) { va[j] = va[j] * c0[j] - pa[j] * s0[j]; vb[j] = vb[j] * c1[j] - pb[j] * s1[j]; } }
.LBB0_650:
	s_andn2_saveexec_b64 s[0:1], s[0:1]
	s_cbranch_execz .LBB0_652
	s_waitcnt lgkmcnt(0)
	v_pk_mul_f32 v[6:7], v[6:7], v[22:23]
	v_pk_mul_f32 v[2:3], v[2:3], v[14:15]
	v_mul_f32_e32 v14, v20, v34
	v_mul_f32_e32 v4, v4, v16
	v_mul_f32_e32 v16, v12, v27
	v_mov_b32_e32 v20, v9
	v_mov_b32_e32 v42, v25
	v_mov_b32_e32 v12, v5
	v_mov_b32_e32 v34, v17
	s_waitcnt lgkmcnt(1)
	v_pk_mul_f32 v[20:21], v[20:21], v[42:43]
	v_pk_fma_f32 v[28:29], v[18:19], v[36:37], v[6:7] neg_lo:[1,0,0] neg_hi:[1,0,0]
	s_waitcnt lgkmcnt(0)
	v_pk_mul_f32 v[6:7], v[12:13], v[34:35]
	v_mul_f32_e32 v8, v8, v24
	v_mov_b32_e32 v9, v20
	v_mov_b32_e32 v15, v21
	v_mov_b32_e32 v5, v6
	v_mov_b32_e32 v17, v7
	v_pk_add_f32 v[30:31], v[8:9], v[14:15] neg_lo:[0,1] neg_hi:[0,1]
	v_pk_fma_f32 v[38:39], v[10:11], v[32:33], v[2:3] neg_lo:[1,0,0] neg_hi:[1,0,0]
	v_pk_add_f32 v[40:41], v[4:5], v[16:17] neg_lo:[0,1] neg_hi:[0,1]

; DI u32 cvtpk(float lo, float hi) { u32 r; asm volatile("v_cvt_pk_bf16_f32 %0, %1, %2" : "=v"(r) : "v"(lo), "v"(hi)); return r; }
; template <int MODE>
; DI void gemm_epilogue(const Params& p, const f32x4 (&acc)[2][2][4][2], int pm, int pn, int wr, int wc, int fr, int fq) {
;     ...
;             u32x4 pk = {cvtpk(va[0], va[1]), cvtpk(va[2], va[3]), cvtpk(vb[0], vb[1]), cvtpk(vb[2], vb[3])};
;             if (cb < 1024) {
;               *(u32x4*)((u16*)(p.ws + WS_Q) + (size_t)row * 1024 + col) = pk;
;             } else {
;               const int c = col - 1024;
;               if (prompt) {
;                 float* ko = p.out + O_KP + (size_t)row * 1024 + c; *(f32x4*)ko = va; *(f32x4*)(ko + 4) = vb;
;                 *(u32x4*)((u16*)(p.ws + WS_K) + (size_t)row * 1024 + c) = pk;
;               } else {
;                 const int rs = row - TP, b = rs >> 6, t = rs & 63;
;                 float* ko = p.out + O_KS + (size_t)rs * 1024 + c; *(f32x4*)ko = va; *(f32x4*)(ko + 4) = vb;
;                 *(u32x4*)((u16*)(p.ws + WS_KC) + ((size_t)b * 1088 + 1024 + t) * 1024 + c) = pk;
.LBB0_653:
	s_andn2_b64 vcc, exec, s[94:95]
	s_mov_b64 s[0:1], -1
	s_waitcnt lgkmcnt(0)
	v_cvt_pk_bf16_f32 v10, v6, v7
	v_cvt_pk_bf16_f32 v11, v8, v9
	v_cvt_pk_bf16_f32 v12, v2, v3
	v_cvt_pk_bf16_f32 v13, v4, v5
	s_cbranch_vccnz .LBB0_659
	s_andn2_b64 vcc, exec, s[92:93]
	s_cbranch_vccnz .LBB0_656
	v_add_u32_e32 v14, 0xffff0000, v26
	v_ashrrev_i32_e32 v15, 31, v14
	v_readlane_b32 s0, v255, 21
	v_ashrrev_i32_e32 v18, 6, v14
	v_lshlrev_b64 v[14:15], 12, v[14:15]
	v_readlane_b32 s1, v255, 22
	s_ashr_i32 s91, s90, 31
	v_lshl_add_u64 v[16:17], s[90:91], 0, v[180:181]
	v_lshl_add_u64 v[14:15], s[0:1], 0, v[14:15]
	v_lshl_add_u64 v[14:15], v[16:17], 2, v[14:15]
	s_movk_i32 s0, 0x440
	global_store_dwordx4 v[14:15], v[6:9], off offset:512
	global_store_dwordx4 v[14:15], v[2:5], off offset:528
	v_mad_i64_i32 v[14:15], s[0:1], v18, s0, v[172:173]
	v_readlane_b32 s0, v255, 23
	v_lshlrev_b64 v[14:15], 11, v[14:15]
	v_readlane_b32 s1, v255, 24
	s_nop 1
	v_lshl_add_u64 v[14:15], s[0:1], 0, v[14:15]
	v_lshl_add_u64 v[14:15], v[16:17], 1, v[14:15]
	s_mov_b64 s[0:1], 0
	global_store_dwordx4 v[14:15], v[10:13], off offset:256

.LBB0_785:
	s_cmp_eq_u32 s4, 0
	s_cbranch_scc1 .LBB0_787
	s_bitcmp1_b32 s6, 0
	s_cselect_b32 s34, 0xe180, 0
	s_add_i32 s34, s34, 16
	v_add3_u32 v145, s34, v149, v123
	ds_read_b128 v[136:139], v145 offset:49168
	ds_read_b128 v[140:143], v145 offset:49152
	s_nop 0
	v_lshlrev_b32_e32 v178, 16, v108
	v_and_b32_e32 v180, 0xffff0000, v108
	v_lshlrev_b32_e32 v184, 16, v109
	v_and_b32_e32 v186, 0xffff0000, v109
	s_waitcnt lgkmcnt(0)
	v_add_f32_e32 v144, 0, v140
	v_add_f32_e32 v144, v144, v141
	v_add_f32_e32 v144, v144, v142
	v_add_f32_e32 v144, v144, v143
	v_add_f32_e32 v144, v144, v136
	v_add_f32_e32 v144, v144, v137
	v_add_f32_e32 v144, v144, v138
	v_add_f32_e32 v144, v144, v139
	v_lshlrev_b32_e32 v188, 16, v110
	s_nop 0
	v_add_f32_dpp v144, v144, v144 quad_perm:[1,0,3,2] row_mask:0xf bank_mask:0xf bound_ctrl:1
	s_nop 1
	v_add_f32_dpp v144, v144, v144 quad_perm:[2,3,0,1] row_mask:0xf bank_mask:0xf bound_ctrl:1
	s_nop 1
	v_add_f32_dpp v144, v144, v144 row_half_mirror row_mask:0xf bank_mask:0xf bound_ctrl:1
	v_mul_f32_e32 v144, 0x3c800000, v144
	v_pk_add_f32 v[174:175], v[140:141], v[144:145] op_sel_hi:[1,0] neg_lo:[0,1] neg_hi:[0,1]
	v_pk_add_f32 v[176:177], v[142:143], v[144:145] op_sel_hi:[1,0] neg_lo:[0,1] neg_hi:[0,1]
	v_pk_mul_f32 v[162:163], v[174:175], v[174:175]
	v_pk_mul_f32 v[142:143], v[176:177], v[176:177]
	v_pk_add_f32 v[146:147], v[136:137], v[144:145] op_sel_hi:[1,0] neg_lo:[0,1] neg_hi:[0,1]
	v_pk_add_f32 v[140:141], v[138:139], v[144:145] op_sel_hi:[1,0] neg_lo:[0,1] neg_hi:[0,1]
	v_add_f32_e32 v144, v162, v163
	v_add_f32_e32 v142, v142, v144
	v_pk_mul_f32 v[136:137], v[146:147], v[146:147]
	v_add_f32_e32 v142, v143, v142
	v_add_f32_e32 v136, v136, v142
	v_pk_mul_f32 v[138:139], v[140:141], v[140:141]
	v_add_f32_e32 v136, v137, v136
	v_add_f32_e32 v136, v138, v136
	v_add_f32_e32 v136, v139, v136
	v_and_b32_e32 v144, 0xffff0000, v110
	v_lshlrev_b32_e32 v142, 16, v111
	v_add_f32_dpp v136, v136, v136 quad_perm:[1,0,3,2] row_mask:0xf bank_mask:0xf bound_ctrl:1
	v_and_b32_e32 v138, 0xffff0000, v111
	s_nop 0
	v_add_f32_dpp v136, v136, v136 quad_perm:[2,3,0,1] row_mask:0xf bank_mask:0xf bound_ctrl:1
	s_nop 1
	v_add_f32_dpp v136, v136, v136 row_half_mirror row_mask:0xf bank_mask:0xf bound_ctrl:1
	v_fmamk_f32 v136, v136, 0x3c800000, v197
	v_cmp_gt_f32_e32 vcc, s98, v136
	v_mul_f32_e32 v137, 0x4b800000, v136
	s_nop 0
	v_cndmask_b32_e32 v136, v136, v137, vcc
	v_rsq_f32_e32 v136, v136
	v_lshl_add_u32 v137, v156, 2, s34
	ds_read_b32 v137, v137 offset:57216
	ds_read_b128 v[162:165], v158 offset:2560
	ds_read_b128 v[166:169], v158 offset:2816
	v_mul_f32_e32 v139, 0x45800000, v136
	v_cndmask_b32_e32 v139, v136, v139, vcc
	v_mul_f32_e32 v136, 0xbfb8aa3b, v178
	v_exp_f32_e32 v136, v136
	v_mul_f32_e32 v108, v174, v139
	s_waitcnt lgkmcnt(0)
	v_fma_f32 v143, v162, v108, v166
	ds_read_b128 v[170:173], v145 offset:40960
	ds_read_b128 v[108:111], v145 offset:40976
	v_add_f32_e32 v136, 1.0, v136
	v_rcp_f32_e32 v136, v136
	s_lshl_b64 s[34:35], s[6:7], 5
	s_waitcnt lgkmcnt(1)
	v_mov_b32_e32 v179, v170
	v_mov_b32_e32 v181, v171
	v_pk_mul_f32 v[178:179], v[136:137], v[178:179]
	v_mov_b32_e32 v185, v172
	v_add_f32_e32 v136, v179, v143
	v_mul_f32_e32 v161, v178, v136
	v_mul_f32_e32 v136, v175, v139
	v_fma_f32 v143, v163, v136, v167
	v_mul_f32_e32 v136, 0xbfb8aa3b, v180
	v_exp_f32_e32 v136, v136
	v_mov_b32_e32 v187, v173
	s_waitcnt lgkmcnt(0)
	v_mov_b32_e32 v189, v108
	v_mov_b32_e32 v145, v109
	v_add_f32_e32 v136, 1.0, v136
	v_rcp_f32_e32 v136, v136
	s_nop 0
	v_pk_mul_f32 v[162:163], v[136:137], v[180:181]
	s_nop 0
	v_add_f32_e32 v136, v163, v143
	v_mul_f32_e32 v174, v162, v136
	v_mul_f32_e32 v136, v176, v139
	v_fma_f32 v143, v164, v136, v168
	v_mul_f32_e32 v136, 0xbfb8aa3b, v184
	v_exp_f32_e32 v136, v136
	s_nop 0
	v_add_f32_e32 v136, 1.0, v136
	v_rcp_f32_e32 v136, v136
	s_nop 0
	v_pk_mul_f32 v[162:163], v[136:137], v[184:185]
	s_nop 0
	v_add_f32_e32 v136, v163, v143
	v_mul_f32_e32 v172, v162, v136
	v_mul_f32_e32 v136, v177, v139
	v_fmac_f32_e32 v169, v165, v136
	v_mul_f32_e32 v136, 0xbfb8aa3b, v186
	v_exp_f32_e32 v136, v136
	s_nop 0
	v_add_f32_e32 v136, 1.0, v136
	v_rcp_f32_e32 v136, v136
	s_nop 0
	v_pk_mul_f32 v[162:163], v[136:137], v[186:187]
	s_nop 0
	v_add_f32_e32 v136, v163, v169
	v_mul_f32_e32 v173, v162, v136
	ds_read_b128 v[162:165], v157 offset:2560
	ds_read_b128 v[166:169], v157 offset:2816
	v_mul_f32_e32 v136, v146, v139
	s_waitcnt lgkmcnt(0)
	v_fma_f32 v143, v162, v136, v166
	v_mul_f32_e32 v136, 0xbfb8aa3b, v188
	v_exp_f32_e32 v136, v136
	s_nop 0
	v_add_f32_e32 v136, 1.0, v136
	v_rcp_f32_e32 v136, v136
	s_nop 0
	v_pk_mul_f32 v[170:171], v[136:137], v[188:189]
	s_nop 0
	v_add_f32_e32 v108, v171, v143
	v_mul_f32_e32 v146, v170, v108
	v_mul_f32_e32 v108, v147, v139
	v_fma_f32 v143, v163, v108, v167
	v_mul_f32_e32 v108, 0xbfb8aa3b, v144
	v_exp_f32_e32 v108, v108
	s_nop 0
	v_add_f32_e32 v108, 1.0, v108
	v_rcp_f32_e32 v136, v108
	s_nop 0
	v_pk_mul_f32 v[108:109], v[136:137], v[144:145]
	s_nop 0
	v_add_f32_e32 v109, v109, v143
	v_mul_f32_e32 v144, v108, v109
	v_mul_f32_e32 v108, v140, v139
	v_fma_f32 v140, v164, v108, v168
	v_mul_f32_e32 v108, 0xbfb8aa3b, v142
	v_exp_f32_e32 v108, v108
	v_mov_b32_e32 v143, v110
	v_add_f32_e32 v108, 1.0, v108
	v_rcp_f32_e32 v136, v108
	s_nop 0
	v_pk_mul_f32 v[108:109], v[136:137], v[142:143]
	s_nop 0
	v_add_f32_e32 v109, v140, v109
	v_mul_f32_e32 v140, v108, v109
	v_mul_f32_e32 v108, v141, v139
	v_fmac_f32_e32 v169, v108, v165
	v_mul_f32_e32 v108, 0xbfb8aa3b, v138
	v_exp_f32_e32 v108, v108
	v_mov_b32_e32 v139, v111
	v_add_f32_e32 v108, 1.0, v108
	v_rcp_f32_e32 v136, v108
	s_nop 0
	v_pk_mul_f32 v[108:109], v[136:137], v[138:139]
	v_lshl_add_u64 v[136:137], s[34:35], 0, v[116:117]
	v_mad_u64_u32 v[138:139], s[34:35], v136, s86, v[112:113]
	v_mov_b32_e32 v136, v139
	v_add_f32_e32 v109, v169, v109
	v_mad_u64_u32 v[136:137], s[34:35], v137, s86, v[136:137]
	v_mul_f32_e32 v111, v108, v109
	v_mov_b32_e32 v139, v136
	v_cvt_pk_bf16_f32 v108, v161, v174
	v_cvt_pk_bf16_f32 v109, v172, v173
	v_cvt_pk_bf16_f32 v110, v146, v144
	v_cvt_pk_bf16_f32 v111, v140, v111
	global_store_dwordx4 v[138:139], v[108:111], off
.LBB0_787:
	global_load_dwordx4 v[108:111], v[114:115], off
	s_add_i32 s34, s6, 2
	s_cmp_ge_u32 s34, s43
	s_cbranch_scc1 .LBB0_784
	s_bitcmp1_b32 s34, 0
	s_cselect_b32 s34, 0xe180, 0
	s_add_i32 s34, s34, 16
	v_lshlrev_b32_e32 v136, 2, v118
	v_add3_u32 v142, s34, v136, v149
	s_waitcnt vmcnt(8)
	v_lshlrev_b32_e32 v136, 16, v72
	v_and_b32_e32 v137, 0xffff0000, v72
	v_lshlrev_b32_e32 v138, 16, v68
	v_and_b32_e32 v139, 0xffff0000, v68
	v_pk_add_f32 v[136:137], v[136:137], v[138:139] neg_lo:[0,1] neg_hi:[0,1]
	v_lshlrev_b32_e32 v140, 16, v69
	v_pk_fma_f32 v[136:137], v[4:5], v[136:137], v[138:139]
	v_lshlrev_b32_e32 v138, 16, v73
	v_and_b32_e32 v139, 0xffff0000, v73
	v_and_b32_e32 v141, 0xffff0000, v69
	v_pk_add_f32 v[138:139], v[138:139], v[140:141] neg_lo:[0,1] neg_hi:[0,1]
	s_waitcnt vmcnt(2)
	v_lshlrev_b32_e32 v145, 16, v96
	v_pk_fma_f32 v[138:139], v[6:7], v[138:139], v[140:141]
	ds_write_b128 v142, v[136:139] offset:32768
	v_lshlrev_b32_e32 v136, 16, v74
	v_and_b32_e32 v137, 0xffff0000, v74
	v_lshlrev_b32_e32 v138, 16, v70
	v_and_b32_e32 v139, 0xffff0000, v70
	v_pk_add_f32 v[136:137], v[136:137], v[138:139] neg_lo:[0,1] neg_hi:[0,1]
	v_lshlrev_b32_e32 v140, 16, v71
	v_pk_fma_f32 v[136:137], v[8:9], v[136:137], v[138:139]
	v_lshlrev_b32_e32 v138, 16, v75
	v_and_b32_e32 v139, 0xffff0000, v75
	v_and_b32_e32 v141, 0xffff0000, v71
	v_pk_add_f32 v[138:139], v[138:139], v[140:141] neg_lo:[0,1] neg_hi:[0,1]
	v_lshlrev_b32_e32 v143, 16, v94
	v_pk_fma_f32 v[138:139], v[10:11], v[138:139], v[140:141]
	ds_write_b128 v142, v[136:139] offset:32784
	v_lshlrev_b32_e32 v136, 16, v80
	v_and_b32_e32 v137, 0xffff0000, v80
	v_lshlrev_b32_e32 v138, 16, v76
	v_and_b32_e32 v139, 0xffff0000, v76
	v_pk_add_f32 v[136:137], v[136:137], v[138:139] neg_lo:[0,1] neg_hi:[0,1]
	v_lshlrev_b32_e32 v140, 16, v77
	v_pk_fma_f32 v[136:137], v[44:45], v[136:137], v[138:139]
	v_lshlrev_b32_e32 v138, 16, v81
	v_and_b32_e32 v139, 0xffff0000, v81
	v_and_b32_e32 v141, 0xffff0000, v77
	v_pk_add_f32 v[138:139], v[138:139], v[140:141] neg_lo:[0,1] neg_hi:[0,1]
	v_lshlrev_b32_e32 v144, 16, v98
	v_pk_fma_f32 v[138:139], v[46:47], v[138:139], v[140:141]
	ds_write_b128 v142, v[136:139] offset:24576
	v_lshlrev_b32_e32 v136, 16, v82
	v_and_b32_e32 v137, 0xffff0000, v82
	v_lshlrev_b32_e32 v138, 16, v78
	v_and_b32_e32 v139, 0xffff0000, v78
	v_pk_add_f32 v[136:137], v[136:137], v[138:139] neg_lo:[0,1] neg_hi:[0,1]
	v_lshlrev_b32_e32 v140, 16, v79
	v_pk_fma_f32 v[136:137], v[48:49], v[136:137], v[138:139]
	v_lshlrev_b32_e32 v138, 16, v83
	v_and_b32_e32 v139, 0xffff0000, v83
	v_and_b32_e32 v141, 0xffff0000, v79
	v_pk_add_f32 v[138:139], v[138:139], v[140:141] neg_lo:[0,1] neg_hi:[0,1]
	v_sub_f32_e32 v144, v144, v143
	v_pk_fma_f32 v[138:139], v[50:51], v[138:139], v[140:141]
	ds_write_b128 v142, v[136:139] offset:24592
	v_lshlrev_b32_e32 v136, 16, v88
	v_and_b32_e32 v137, 0xffff0000, v88
	v_lshlrev_b32_e32 v138, 16, v84
	v_and_b32_e32 v139, 0xffff0000, v84
	v_pk_add_f32 v[136:137], v[136:137], v[138:139] neg_lo:[0,1] neg_hi:[0,1]
	v_lshlrev_b32_e32 v140, 16, v85
	v_pk_fma_f32 v[136:137], v[52:53], v[136:137], v[138:139]
	v_lshlrev_b32_e32 v138, 16, v89
	v_and_b32_e32 v139, 0xffff0000, v89
	v_and_b32_e32 v141, 0xffff0000, v85
	v_pk_add_f32 v[138:139], v[138:139], v[140:141] neg_lo:[0,1] neg_hi:[0,1]
	v_fmac_f32_e32 v143, v16, v144
	v_pk_fma_f32 v[138:139], v[54:55], v[138:139], v[140:141]
	ds_write_b128 v142, v[136:139] offset:40960
	v_lshlrev_b32_e32 v136, 16, v90
	v_and_b32_e32 v137, 0xffff0000, v90
	v_lshlrev_b32_e32 v138, 16, v86
	v_and_b32_e32 v139, 0xffff0000, v86
	v_pk_add_f32 v[136:137], v[136:137], v[138:139] neg_lo:[0,1] neg_hi:[0,1]
	v_lshlrev_b32_e32 v140, 16, v87
	v_pk_fma_f32 v[136:137], v[56:57], v[136:137], v[138:139]
	v_lshlrev_b32_e32 v138, 16, v91
	v_and_b32_e32 v139, 0xffff0000, v91
	v_and_b32_e32 v141, 0xffff0000, v87
	v_pk_add_f32 v[138:139], v[138:139], v[140:141] neg_lo:[0,1] neg_hi:[0,1]
	v_add3_u32 v214, s34, v155, v120
	v_pk_fma_f32 v[138:139], v[58:59], v[138:139], v[140:141]
	ds_write_b128 v142, v[136:139] offset:40976
	v_and_b32_e32 v140, 0xffff0000, v95
	v_and_b32_e32 v136, 0xffff0000, v99
	v_sub_f32_e32 v136, v136, v140
	v_fmac_f32_e32 v140, v19, v136
	v_lshlrev_b32_e32 v141, 16, v95
	v_lshlrev_b32_e32 v136, 16, v99
	v_sub_f32_e32 v136, v136, v141
	v_fmac_f32_e32 v141, v18, v136
	v_and_b32_e32 v142, 0xffff0000, v94
	v_and_b32_e32 v136, 0xffff0000, v98
	v_sub_f32_e32 v136, v136, v142
	v_fmac_f32_e32 v142, v17, v136
	v_and_b32_e32 v136, 0xffff0000, v93
	v_and_b32_e32 v137, 0xffff0000, v97
	v_sub_f32_e32 v137, v137, v136
	v_fmac_f32_e32 v136, v15, v137
	v_lshlrev_b32_e32 v137, 16, v93
	v_lshlrev_b32_e32 v138, 16, v97
	v_sub_f32_e32 v138, v138, v137
	v_fmac_f32_e32 v137, v14, v138
	v_and_b32_e32 v138, 0xffff0000, v92
	v_and_b32_e32 v139, 0xffff0000, v96
	v_sub_f32_e32 v139, v139, v138
	v_fmac_f32_e32 v138, v13, v139
	v_lshlrev_b32_e32 v139, 16, v92
	v_sub_f32_e32 v145, v145, v139
	v_fmac_f32_e32 v139, v12, v145
	v_add_f32_e32 v139, v139, v139
	v_add_f32_e32 v138, v138, v138
	v_mul_f32_e32 v139, 0x3fb8aa3b, v139
	v_mul_f32_e32 v138, 0x3fb8aa3b, v138
	v_add_f32_e32 v137, v137, v137
	v_add_f32_e32 v136, v136, v136
	v_exp_f32_e32 v139, v139
	v_exp_f32_e32 v138, v138
	v_mul_f32_e32 v137, 0x3fb8aa3b, v137
	v_mul_f32_e32 v136, 0x3fb8aa3b, v136
	v_exp_f32_e32 v137, v137
	v_exp_f32_e32 v136, v136
	v_add_f32_e32 v139, 1.0, v139
	v_add_f32_e32 v138, 1.0, v138
	v_add_f32_e32 v145, 1.0, v137
	v_add_f32_e32 v146, 1.0, v136
	v_rcp_f32_e64 v137, -v138
	v_rcp_f32_e64 v136, -v139
	v_rcp_f32_e64 v139, -v146
	v_add_f32_e32 v141, v141, v141
	v_add_f32_e32 v140, v140, v140
	v_pk_fma_f32 v[136:137], v[136:137], 2.0, 1.0 op_sel_hi:[1,0,0]
	v_mul_f32_e32 v141, 0x3fb8aa3b, v141
	v_bfe_u32 v146, v137, 16, 1
	v_bfe_u32 v147, v136, 16, 1
	v_add3_u32 v147, v136, v147, s89
	v_add3_u32 v146, v137, v146, s89
	v_add_f32_e32 v136, v143, v143
	v_add_f32_e32 v137, v142, v142
	v_mul_f32_e32 v136, 0x3fb8aa3b, v136
	v_mul_f32_e32 v137, 0x3fb8aa3b, v137
	v_mul_f32_e32 v140, 0x3fb8aa3b, v140
	v_exp_f32_e32 v136, v136
	v_exp_f32_e32 v137, v137
	v_exp_f32_e32 v141, v141
	v_exp_f32_e32 v140, v140
	v_rcp_f32_e64 v138, -v145
	v_add_f32_e32 v136, 1.0, v136
	v_add_f32_e32 v137, 1.0, v137
	v_add_f32_e32 v142, 1.0, v141
	v_add_f32_e32 v140, 1.0, v140
	v_rcp_f32_e64 v137, -v137
	v_rcp_f32_e64 v136, -v136
	v_rcp_f32_e64 v141, -v140
	v_rcp_f32_e64 v140, -v142
	v_pk_fma_f32 v[138:139], v[138:139], 2.0, 1.0 op_sel_hi:[1,0,0]
	v_pk_fma_f32 v[136:137], v[136:137], 2.0, 1.0 op_sel_hi:[1,0,0]
	v_bfe_u32 v144, v139, 16, 1
	v_bfe_u32 v145, v138, 16, 1
	v_add3_u32 v142, v138, v145, s89
	v_add3_u32 v143, v139, v144, s89
	v_pk_fma_f32 v[138:139], v[140:141], 2.0, 1.0 op_sel_hi:[1,0,0]
	v_bfe_u32 v144, v137, 16, 1
	v_bfe_u32 v140, v139, 16, 1
	v_bfe_u32 v141, v138, 16, 1
	v_bfe_u32 v145, v136, 16, 1
	v_add3_u32 v136, v136, v145, s89
	v_add3_u32 v137, v137, v144, s89
	v_add3_u32 v138, v138, v141, s89
	v_add3_u32 v139, v139, v140, s89
	v_perm_b32 v139, v139, v138, s90
	v_perm_b32 v138, v137, v136, s90
	v_perm_b32 v137, v143, v142, s90
	v_perm_b32 v136, v146, v147, s90
	ds_write_b128 v121, v[136:139]
	s_waitcnt vmcnt(1)
	v_lshlrev_b32_e32 v142, 16, v104
	v_lshlrev_b32_e32 v140, 16, v105
	v_and_b32_e32 v143, 0xffff0000, v104
	v_and_b32_e32 v141, 0xffff0000, v105
	v_lshlrev_b32_e32 v136, 16, v100
	v_lshlrev_b32_e32 v138, 16, v101
	v_and_b32_e32 v137, 0xffff0000, v100
	v_and_b32_e32 v139, 0xffff0000, v101
	v_sub_f32_e32 v141, v141, v139
	v_sub_f32_e32 v140, v140, v138
	v_sub_f32_e32 v143, v143, v137
	v_sub_f32_e32 v142, v142, v136
	v_pk_fma_f32 v[136:137], v[60:61], v[142:143], v[136:137]
	v_pk_fma_f32 v[138:139], v[62:63], v[140:141], v[138:139]
	v_bfe_u32 v142, v137, 16, 1
	v_bfe_u32 v140, v139, 16, 1
	v_bfe_u32 v141, v138, 16, 1
	v_bfe_u32 v143, v136, 16, 1
	v_add3_u32 v144, v136, v143, s89
	v_add3_u32 v145, v137, v142, s89
	v_add3_u32 v146, v138, v141, s89
	v_add3_u32 v147, v139, v140, s89
	v_lshlrev_b32_e32 v142, 16, v106
	v_lshlrev_b32_e32 v140, 16, v107
	v_and_b32_e32 v143, 0xffff0000, v106
	v_and_b32_e32 v141, 0xffff0000, v107
	v_lshlrev_b32_e32 v136, 16, v102
	v_lshlrev_b32_e32 v138, 16, v103
	v_and_b32_e32 v137, 0xffff0000, v102
	v_and_b32_e32 v139, 0xffff0000, v103
	v_sub_f32_e32 v141, v141, v139
	v_sub_f32_e32 v140, v140, v138
	v_sub_f32_e32 v143, v143, v137
	v_sub_f32_e32 v142, v142, v136
	v_pk_fma_f32 v[136:137], v[64:65], v[142:143], v[136:137]
	v_pk_fma_f32 v[138:139], v[66:67], v[140:141], v[138:139]
	v_bfe_u32 v142, v137, 16, 1
	v_bfe_u32 v140, v139, 16, 1
	v_bfe_u32 v141, v138, 16, 1
	v_bfe_u32 v143, v136, 16, 1
	v_add3_u32 v136, v136, v143, s89
	v_add3_u32 v137, v137, v142, s89
	v_add3_u32 v138, v138, v141, s89
	v_add3_u32 v139, v139, v140, s89
	v_perm_b32 v139, v139, v138, s90
	v_perm_b32 v138, v137, v136, s90
	v_perm_b32 v137, v147, v146, s90
	v_perm_b32 v136, v145, v144, s90
	ds_write_b128 v159, v[136:139]
	s_waitcnt lgkmcnt(0)
	ds_read_b128 v[136:139], v150
	ds_read_b128 v[140:143], v150 offset:64
	ds_read_b128 v[144:147], v160
	ds_read_b128 v[162:165], v160 offset:64
	s_waitcnt lgkmcnt(1)
	v_mfma_f32_16x16x32_bf16 v[144:147], v[136:139], v[144:147], 0
	v_lshl_add_u32 v215, v156, 2, s34
	v_lshl_add_u32 v216, v156, 3, s34
	s_waitcnt lgkmcnt(0)
	v_mfma_f32_16x16x32_bf16 v[144:147], v[140:143], v[162:165], v[144:147]
	ds_read_b128 v[162:165], v160 offset:2304
	ds_read_b128 v[166:169], v160 offset:2368
	s_waitcnt lgkmcnt(1)
	v_mfma_f32_16x16x32_bf16 v[162:165], v[136:139], v[162:165], 0
	s_waitcnt lgkmcnt(0)
	v_mfma_f32_16x16x32_bf16 v[162:165], v[140:143], v[166:169], v[162:165]
	ds_read_b128 v[166:169], v160 offset:4608
	ds_read_b128 v[170:173], v160 offset:4672
	s_waitcnt lgkmcnt(1)
	v_mfma_f32_16x16x32_bf16 v[166:169], v[136:139], v[166:169], 0
	s_waitcnt lgkmcnt(0)
	v_mfma_f32_16x16x32_bf16 v[166:169], v[140:143], v[170:173], v[166:169]
	ds_read_b128 v[170:173], v160 offset:6912
	ds_read_b128 v[174:177], v160 offset:6976
	s_waitcnt lgkmcnt(1)
	v_mfma_f32_16x16x32_bf16 v[136:139], v[136:139], v[170:173], 0
	ds_read_b128 v[170:173], v151
	s_nop 2
	v_cndmask_b32_e64 v144, v144, v166, s[0:1]
	v_add_f32_e32 v144, v124, v144
	s_waitcnt lgkmcnt(1)
	v_mfma_f32_16x16x32_bf16 v[136:139], v[140:143], v[174:177], v[136:139]
	ds_read_b128 v[140:143], v151 offset:64
	ds_read_b128 v[174:177], v160 offset:9216
	ds_read_b128 v[178:181], v160 offset:9280
	v_mul_f32_e32 v144, 0xbfb8aa3b, v144
	v_exp_f32_e32 v144, v144
	s_waitcnt lgkmcnt(1)
	v_mfma_f32_16x16x32_bf16 v[174:177], v[170:173], v[174:177], 0
	v_cndmask_b32_e64 v145, v145, v167, s[0:1]
	v_add_f32_e32 v144, 1.0, v144
	v_rcp_f32_e32 v144, v144
	s_waitcnt lgkmcnt(0)
	v_mfma_f32_16x16x32_bf16 v[174:177], v[140:143], v[178:181], v[174:177]
	ds_read_b128 v[178:181], v160 offset:11520
	ds_read_b128 v[184:187], v160 offset:11584
	v_add_f32_e32 v145, v124, v145
	v_mul_f32_e32 v144, 0xbf1b4598, v144
	s_waitcnt lgkmcnt(1)
	v_mfma_f32_16x16x32_bf16 v[178:181], v[170:173], v[178:181], 0
	v_mul_f32_e32 v144, 0x3fb8aa3b, v144
	v_mul_f32_e32 v145, 0xbfb8aa3b, v145
	v_exp_f32_e32 v144, v144
	s_waitcnt lgkmcnt(0)
	v_mfma_f32_16x16x32_bf16 v[178:181], v[140:143], v[184:187], v[178:181]
	ds_read_b128 v[184:187], v160 offset:13824
	ds_read_b128 v[188:191], v160 offset:13888
	v_exp_f32_e32 v145, v145
	v_cndmask_b32_e64 v147, v147, v169, s[0:1]
	s_waitcnt lgkmcnt(1)
	v_mfma_f32_16x16x32_bf16 v[184:187], v[170:173], v[184:187], 0
	v_cndmask_b32_e64 v146, v146, v168, s[0:1]
	v_lshl_add_u32 v169, v152, 2, s34
	v_cndmask_b32_e64 v136, v162, v136, s[0:1]
	s_waitcnt lgkmcnt(0)
	v_mfma_f32_16x16x32_bf16 v[184:187], v[140:143], v[188:191], v[184:187]
	ds_read_b128 v[188:191], v160 offset:16128
	ds_read_b128 v[192:195], v160 offset:16192
	v_add_f32_e32 v147, v124, v147
	v_add_f32_e32 v136, v125, v136
	s_waitcnt lgkmcnt(1)
	v_mfma_f32_16x16x32_bf16 v[170:173], v[170:173], v[188:191], 0
	s_nop 1
	v_cndmask_b32_e64 v167, v174, v184, s[0:1]
	v_add_f32_e32 v167, v126, v167
	v_mul_f32_e32 v167, 0xbfb8aa3b, v167
	v_exp_f32_e32 v167, v167
	v_mul_f32_e32 v147, 0xbfb8aa3b, v147
	v_mul_f32_e32 v136, 0xbfb8aa3b, v136
	s_waitcnt lgkmcnt(0)
	v_mfma_f32_16x16x32_bf16 v[140:143], v[140:143], v[192:195], v[170:173]
	v_add_f32_e32 v167, 1.0, v167
	v_rcp_f32_e32 v167, v167
	v_exp_f32_e32 v147, v147
	v_exp_f32_e32 v136, v136
	v_cndmask_b32_e64 v161, v177, v187, s[0:1]
	ds_write2st64_b32 v169, v144, v167 offset1:64
	v_add_f32_e32 v144, 1.0, v145
	v_add_f32_e32 v145, v124, v146
	v_mul_f32_e32 v145, 0xbfb8aa3b, v145
	v_exp_f32_e32 v145, v145
	v_cndmask_b32_e64 v166, v176, v186, s[0:1]
	v_cndmask_b32_e64 v168, v175, v185, s[0:1]
	v_add_f32_e32 v147, 1.0, v147
	v_add_f32_e32 v145, 1.0, v145
	v_cndmask_b32_e64 v137, v163, v137, s[0:1]
	v_add_f32_e32 v136, 1.0, v136
	v_cndmask_b32_e64 v140, v178, v140, s[0:1]
	v_rcp_f32_e32 v144, v144
	v_rcp_f32_e32 v145, v145
	v_add_f32_e32 v146, v126, v168
	v_add_f32_e32 v166, v126, v166
	v_rcp_f32_e32 v147, v147
	v_add_f32_e32 v161, v126, v161
	v_rcp_f32_e32 v136, v136
	v_add_f32_e32 v140, v127, v140
	v_add_f32_e32 v137, v125, v137
	v_mul_f32_e32 v146, 0xbfb8aa3b, v146
	v_mul_f32_e32 v166, 0xbfb8aa3b, v166
	v_mul_f32_e32 v161, 0xbfb8aa3b, v161
	v_mul_f32_e32 v140, 0xbfb8aa3b, v140
	v_mul_f32_e32 v137, 0xbfb8aa3b, v137
	v_exp_f32_e32 v146, v146
	v_exp_f32_e32 v166, v166
	v_exp_f32_e32 v161, v161
	v_exp_f32_e32 v140, v140
	v_exp_f32_e32 v137, v137
	v_mul_f32_e32 v144, 0xbf1b4598, v144
	v_mul_f32_e32 v145, 0xbf1b4598, v145
	v_mul_f32_e32 v147, 0xbf1b4598, v147
	v_mul_f32_e32 v136, 0xbf1b4598, v136
	v_mul_f32_e32 v144, 0x3fb8aa3b, v144
	v_mul_f32_e32 v145, 0x3fb8aa3b, v145
	v_mul_f32_e32 v147, 0x3fb8aa3b, v147
	v_mul_f32_e32 v136, 0x3fb8aa3b, v136
	v_exp_f32_e32 v144, v144
	v_exp_f32_e32 v145, v145
	v_add_f32_e32 v166, 1.0, v166
	v_exp_f32_e32 v147, v147
	v_add_f32_e32 v161, 1.0, v161
	v_add_f32_e32 v146, 1.0, v146
	v_exp_f32_e32 v136, v136
	v_add_f32_e32 v140, 1.0, v140
	v_add_f32_e32 v137, 1.0, v137
	v_rcp_f32_e32 v166, v166
	v_rcp_f32_e32 v161, v161
	v_rcp_f32_e32 v146, v146
	v_rcp_f32_e32 v140, v140
	v_rcp_f32_e32 v137, v137
	ds_write2st64_b32 v169, v145, v147 offset0:2 offset1:3
	ds_write2st64_b32 v169, v166, v161 offset0:66 offset1:67
	v_cndmask_b32_e64 v138, v164, v138, s[0:1]
	ds_write2_b32 v169, v136, v144 offset0:16 offset1:64
	v_add_u32_e32 v136, 0x4000, v169
	v_cndmask_b32_e64 v139, v165, v139, s[0:1]
	ds_write2_b32 v136, v140, v146 offset0:16 offset1:64
	v_mul_f32_e32 v136, 0xbf1b4598, v137
	v_add_f32_e32 v137, v125, v138
	v_mul_f32_e32 v137, 0xbfb8aa3b, v137
	v_add_f32_e32 v139, v125, v139
	v_exp_f32_e32 v137, v137
	v_mul_f32_e32 v139, 0xbfb8aa3b, v139
	v_exp_f32_e32 v139, v139
	v_cndmask_b32_e64 v141, v179, v141, s[0:1]
	v_add_f32_e32 v137, 1.0, v137
	v_cndmask_b32_e64 v143, v181, v143, s[0:1]
	v_cndmask_b32_e64 v142, v180, v142, s[0:1]
	v_add_f32_e32 v138, v127, v141
	v_rcp_f32_e32 v137, v137
	v_add_f32_e32 v139, 1.0, v139
	v_mul_f32_e32 v138, 0xbfb8aa3b, v138
	v_add_f32_e32 v140, v127, v142
	v_rcp_f32_e32 v139, v139
	v_add_f32_e32 v141, v127, v143
	v_exp_f32_e32 v138, v138
	v_mul_f32_e32 v140, 0xbfb8aa3b, v140
	v_mul_f32_e32 v141, 0xbfb8aa3b, v141
	v_exp_f32_e32 v140, v140
	v_exp_f32_e32 v141, v141
	v_mul_f32_e32 v137, 0xbf1b4598, v137
	v_mul_f32_e32 v136, 0x3fb8aa3b, v136
	v_mul_f32_e32 v137, 0x3fb8aa3b, v137
	v_mul_f32_e32 v139, 0xbf1b4598, v139
	v_exp_f32_e32 v136, v136
	v_add_f32_e32 v138, 1.0, v138
	v_exp_f32_e32 v137, v137
	v_mul_f32_e32 v139, 0x3fb8aa3b, v139
	v_rcp_f32_e32 v138, v138
	v_add_f32_e32 v140, 1.0, v140
	v_exp_f32_e32 v139, v139
	v_add_f32_e32 v141, 1.0, v141
	v_rcp_f32_e32 v140, v140
	v_rcp_f32_e32 v141, v141
	v_lshl_add_u32 v142, v153, 2, s34
	ds_write2st64_b32 v142, v136, v137 offset0:1 offset1:2
	ds_write2st64_b32 v142, v139, v138 offset0:3 offset1:65
	ds_write2st64_b32 v142, v140, v141 offset0:66 offset1:67
	s_waitcnt lgkmcnt(0)
	v_lshl_add_u32 v161, v154, 2, s34
	ds_read_b128 v[136:139], v161 offset:32768
	ds_read_b128 v[140:143], v161
	ds_read_b128 v[144:147], v161 offset:16
	ds_read_b128 v[162:165], v161 offset:32784
	s_add_i32 s34, s6, 3
	s_cmp_ge_u32 s34, s43
	s_waitcnt lgkmcnt(2)
	v_mul_f32_e32 v206, v136, v140
	v_mul_f32_e32 v207, v137, v141
	v_mul_f32_e32 v208, v138, v142
	v_mul_f32_e32 v209, v139, v143
	s_waitcnt lgkmcnt(0)
	v_mul_f32_e32 v210, v162, v144
	v_mul_f32_e32 v211, v163, v145
	v_mul_f32_e32 v212, v164, v146
	v_mul_f32_e32 v213, v165, v147
	ds_read_b128 v[140:143], v161 offset:16384
	ds_read_b128 v[144:147], v161 offset:16400
	ds_read_b128 v[166:169], v161 offset:24576
	ds_read_b128 v[170:173], v161 offset:24592
	s_waitcnt lgkmcnt(3)
	v_pk_add_f32 v[186:187], v[140:141], -1.0 op_sel_hi:[1,0]
	s_nop 0
	v_pk_fma_f32 v[186:187], v[28:29], v[186:187], 1.0 op_sel_hi:[1,1,0]
	s_waitcnt lgkmcnt(1)
	v_pk_mul_f32 v[184:185], v[20:21], v[166:167]
	v_pk_mul_f32 v[166:167], v[166:167], v[186:187]
	v_add_f32_e32 v187, -1.0, v142
	v_mov_b32_e32 v186, v168
	v_pk_mul_f32 v[198:199], v[22:23], v[186:187]
	v_add_f32_e32 v175, -1.0, v144
	s_waitcnt lgkmcnt(0)
	v_mov_b32_e32 v174, v170
	v_add_f32_e32 v191, -1.0, v143
	v_mov_b32_e32 v190, v169
	v_mov_b32_e32 v200, v184
	v_mov_b32_e32 v201, v198
	v_pk_mul_f32 v[176:177], v[24:25], v[174:175]
	v_pk_mul_f32 v[192:193], v[30:31], v[190:191]
	v_pk_mul_f32 v[200:201], v[200:201], v[200:201]
	v_mov_b32_e32 v188, v142
	v_mov_b32_e32 v194, v192
	v_mov_b32_e32 v195, v176
	v_fma_f32 v142, v185, v185, v200
	v_pk_mul_f32 v[194:195], v[194:195], v[194:195]
	v_add_f32_e32 v142, v142, v201
	v_add_f32_e32 v203, -1.0, v145
	v_mov_b32_e32 v202, v171
	v_add_f32_e32 v142, v142, v194
	v_pk_mul_f32 v[178:179], v[26:27], v[172:173]
	v_pk_mul_f32 v[204:205], v[32:33], v[202:203]
	v_add_f32_e32 v142, v142, v195
	v_pk_mul_f32 v[180:181], v[178:179], v[178:179]
	v_fmac_f32_e32 v142, v204, v204
	v_add_f32_e32 v142, v142, v180
	v_add_f32_e32 v142, v142, v181
	v_mov_b32_e32 v189, v168
	v_mov_b32_e32 v168, v143
	v_add_f32_dpp v142, v142, v142 quad_perm:[1,0,3,2] row_mask:0xf bank_mask:0xf bound_ctrl:1
	v_mov_b32_e32 v194, v144
	v_mul_f32_e32 v144, v137, v167
	v_add_f32_dpp v142, v142, v142 quad_perm:[2,3,0,1] row_mask:0xf bank_mask:0xf bound_ctrl:1
	v_mov_b32_e32 v180, v139
	v_mov_b32_e32 v195, v170
	v_add_f32_dpp v142, v142, v142 row_half_mirror row_mask:0xf bank_mask:0xf bound_ctrl:1
	v_max_f32_e32 v142, 0x179abe15, v142
	v_rsq_f32_e32 v182, v142
	v_mov_b32_e32 v170, v145
	v_mov_b32_e32 v145, v172
	v_mov_b32_e32 v172, v147
	v_pk_mul_f32 v[142:143], v[184:185], v[182:183] op_sel_hi:[1,0]
	v_mov_b32_e32 v185, v166
	v_pk_mul_f32 v[140:141], v[140:141], v[142:143]
	v_xor_b32_e32 v181, 0x80000000, v142
	v_mov_b32_e32 v184, v140
	v_mul_f32_e32 v142, v136, v166
	v_fma_f32 v200, v36, v142, 0
	v_pk_fma_f32 v[184:185], v[136:137], v[184:185], 0 op_sel_hi:[0,1,0]
	v_xor_b32_e32 v201, 0x80000000, v143
	v_mov_b32_e32 v142, v141
	v_mov_b32_e32 v143, v167
	v_pk_fma_f32 v[136:137], v[136:137], v[142:143], v[184:185] op_sel:[1,0,0]
	v_pk_mul_f32 v[142:143], v[198:199], v[182:183]
	v_pk_fma_f32 v[184:185], v[22:23], v[186:187], s[2:3]
	v_fmac_f32_e32 v200, v37, v144
	v_mov_b32_e32 v143, v185
	v_pk_mul_f32 v[184:185], v[188:189], v[142:143]
	v_xor_b32_e32 v188, 0x80000000, v142
	v_mul_f32_e32 v142, v185, v138
	v_fmac_f32_e32 v200, v38, v142
	v_pk_mul_f32 v[142:143], v[192:193], v[182:183]
	v_pk_fma_f32 v[186:187], v[30:31], v[190:191], s[2:3]
	v_pk_fma_f32 v[136:137], v[184:185], v[138:139], v[136:137] op_sel_hi:[1,0,1]
	v_mov_b32_e32 v143, v187
	v_pk_mul_f32 v[186:187], v[168:169], v[142:143]
	v_xor_b32_e32 v189, 0x80000000, v142
	v_mov_b32_e32 v142, v184
	v_mov_b32_e32 v143, v186
	v_mul_f32_e32 v138, v187, v139
	ds_write_b128 v161, v[140:143] offset:16384
	v_fmac_f32_e32 v200, v39, v138
	v_pk_mul_f32 v[138:139], v[176:177], v[182:183]
	v_pk_fma_f32 v[140:141], v[24:25], v[174:175], s[2:3]
	v_mov_b32_e32 v168, v185
	v_mov_b32_e32 v139, v141
	v_mov_b32_e32 v169, v187
	v_pk_mul_f32 v[142:143], v[194:195], v[138:139]
	ds_write_b128 v161, v[166:169] offset:24576
	v_pk_fma_f32 v[136:137], v[186:187], v[180:181], v[136:137] op_sel_hi:[1,0,1]
	v_xor_b32_e32 v166, 0x80000000, v138
	v_mul_f32_e32 v138, v143, v162
	v_fmac_f32_e32 v200, v40, v138
	v_pk_fma_f32 v[138:139], v[142:143], v[162:163], v[136:137] op_sel_hi:[1,0,1]
	v_pk_mul_f32 v[140:141], v[204:205], v[182:183]
	v_pk_fma_f32 v[136:137], v[32:33], v[202:203], s[2:3]
	v_xor_b32_e32 v167, 0x80000000, v140
	v_mov_b32_e32 v141, v137
	v_pk_mul_f32 v[136:137], v[170:171], v[140:141]
	v_mul_f32_e64 v168, v178, -v182
	v_mul_f32_e32 v140, v137, v163
	v_fmac_f32_e32 v200, v41, v140
	v_add_f32_e32 v140, -1.0, v146
	v_fma_f32 v141, v34, v140, 1.0
	v_mov_b32_e32 v144, v146
	v_xor_b32_e32 v140, 0x80000000, v168
	v_pk_fma_f32 v[138:139], v[136:137], v[162:163], v[138:139] op_sel:[0,1,0]
	v_pk_mul_f32 v[144:145], v[144:145], v[140:141]
	s_nop 0
	v_mul_f32_e32 v140, v145, v164
	v_pk_fma_f32 v[162:163], v[144:145], v[164:165], v[138:139] op_sel_hi:[1,0,1]
	v_add_f32_e32 v138, -1.0, v147
	v_mul_f32_e64 v164, v179, -v182
	v_fma_f32 v139, v35, v138, 1.0
	v_xor_b32_e32 v138, 0x80000000, v164
	v_pk_mul_f32 v[146:147], v[172:173], v[138:139]
	v_fmac_f32_e32 v200, v42, v140
	v_mov_b32_e32 v138, v142
	v_mov_b32_e32 v139, v136
	v_mov_b32_e32 v140, v144
	v_mov_b32_e32 v141, v146
	ds_write_b128 v161, v[138:141] offset:16400
	v_mov_b32_e32 v136, v143
	v_mov_b32_e32 v138, v145
	v_mov_b32_e32 v139, v147
	ds_write_b128 v161, v[136:139] offset:24592
	v_mov_b32_e32 v136, v165
	v_mul_f32_e32 v137, v147, v165
	v_fmac_f32_e32 v200, v43, v137
	v_pk_fma_f32 v[144:145], v[146:147], v[136:137], v[162:163] op_sel_hi:[1,0,1]
	v_cvt_pk_bf16_f32 v136, v181, v201
	v_cvt_pk_bf16_f32 v137, v188, v189
	v_cvt_pk_bf16_f32 v138, v166, v167
	v_cvt_pk_bf16_f32 v139, v168, v164
	v_cvt_pk_bf16_f32 v140, v206, v207
	v_cvt_pk_bf16_f32 v141, v208, v209
	v_cvt_pk_bf16_f32 v142, v210, v211
	v_cvt_pk_bf16_f32 v143, v212, v213
	ds_write_b128 v214, v[136:139] offset:8192
	ds_write_b128 v214, v[140:143] offset:12288
	v_add_f32_dpp v136, v200, v200 quad_perm:[1,0,3,2] row_mask:0xf bank_mask:0xf bound_ctrl:1
	v_mov_b32_dpp v137, v145 quad_perm:[1,0,3,2] row_mask:0xf bank_mask:0xf bound_ctrl:1
	s_nop 0
	v_add_f32_dpp v136, v136, v136 quad_perm:[2,3,0,1] row_mask:0xf bank_mask:0xf bound_ctrl:1
	s_nop 1
	v_add_f32_dpp v140, v136, v136 row_half_mirror row_mask:0xf bank_mask:0xf bound_ctrl:1
	v_mov_b32_dpp v136, v144 quad_perm:[1,0,3,2] row_mask:0xf bank_mask:0xf bound_ctrl:1
	v_pk_add_f32 v[136:137], v[144:145], v[136:137]
	ds_write_b32 v215, v140 offset:57216
	s_nop 0
	v_mov_b32_dpp v138, v136 quad_perm:[2,3,0,1] row_mask:0xf bank_mask:0xf bound_ctrl:1
	v_mov_b32_dpp v139, v137 quad_perm:[2,3,0,1] row_mask:0xf bank_mask:0xf bound_ctrl:1
	v_pk_add_f32 v[136:137], v[136:137], v[138:139]
	s_nop 1
	v_mov_b32_dpp v138, v136 row_half_mirror row_mask:0xf bank_mask:0xf bound_ctrl:1
	v_mov_b32_dpp v139, v137 row_half_mirror row_mask:0xf bank_mask:0xf bound_ctrl:1
	v_pk_add_f32 v[136:137], v[136:137], v[138:139]
	ds_write_b64 v216, v[136:137] offset:57216
	s_waitcnt vmcnt(0)
	s_cbranch_scc1 .LBB0_784
	v_lshl_add_u64 v[84:85], v[128:129], 0, s[4:5]
	v_add_co_u32_e32 v72, vcc, 0x239a5000, v84
	v_lshl_add_u64 v[92:93], v[130:131], 0, s[4:5]
	s_nop 0
	v_addc_co_u32_e32 v73, vcc, 0, v85, vcc
	v_add_co_u32_e32 v74, vcc, 0x239a3000, v84
	v_lshl_add_u64 v[80:81], v[132:133], 0, s[4:5]
	s_nop 0
	v_addc_co_u32_e32 v75, vcc, 0, v85, vcc
	v_add_co_u32_e32 v88, vcc, 0x239a4000, v84
	v_lshl_add_u64 v[86:87], v[134:135], 0, s[4:5]
	s_nop 0
	v_addc_co_u32_e32 v89, vcc, 0, v85, vcc
	v_add_co_u32_e32 v96, vcc, 0x239a6000, v92
	global_load_dwordx4 v[68:71], v[72:73], off
	global_load_dwordx4 v[76:79], v[72:73], off offset:2048
	v_addc_co_u32_e32 v97, vcc, 0, v93, vcc
	v_add_co_u32_e32 v104, vcc, 0x239a4000, v92
	global_load_dwordx4 v[72:75], v[74:75], off offset:1792
	s_nop 0
	global_load_dwordx4 v[80:83], v[80:81], off
	v_addc_co_u32_e32 v105, vcc, 0, v93, vcc
	global_load_dwordx4 v[84:87], v[86:87], off
	s_nop 0
	global_load_dwordx4 v[88:91], v[88:89], off offset:1792
	s_nop 0
	global_load_dwordx4 v[92:95], v[96:97], off offset:2048
	global_load_dwordx4 v[100:103], v[96:97], off offset:2176
	s_nop 0
	global_load_dwordx4 v[96:99], v[104:105], off offset:3840
	s_nop 0
	global_load_dwordx4 v[104:107], v[104:105], off offset:3968
	s_branch .LBB0_784

; DI void scan_item(const Params& p, char* smem, int b, int h, bool prompt, const int g_wave) {
;     ...
;     const int li = lane & 15, g = lane >> 4, irow = wid * 16 + li;
;     f32x2 S0[4], S1[4];
;     if (prompt) { for (int e = 0; e < 4; ++e) { S0[e] = (f32x2){0.f, 0.f}; S1[e] = (f32x2){0.f, 0.f}; } }
;     else {
;       const float* s0 = p.state_wkv + ((size_t)(b * 16 + h) * 64 + irow) * 64 + 8 * g;
;       for (int e = 0; e < 4; ++e) { S0[e] = (f32x2){s0[2 * e], s0[2 * e + 1]}; S1[e] = (f32x2){s0[32 + 2 * e], s0[32 + 2 * e + 1]}; }
;     }
;     const int abf_off = ((lane & 3) == 1 ? 12288 : 8192) + 16 * g;
;     __syncthreads();
; #pragma unroll 1
;     for (int k = 0; k < nch; ++k) {
;       const char* set = smem + (k & 1) * SETB;
;       const float* bW = (const float*)set + 8 * g;
;       const char* bA = set + abf_off;
;       const float* bV = (const float*)(set + 40960) + irow;
;       float* Yp = (float*)(set + 49152) + irow;
;       const float2* BK = (const float2*)(set + 57472);
;     ...
;       f32x4v Pw0, Pw1, Pw2, Pw3, Pb0, Pb1, Pb2, Pb3, Pk0, Pk1, Pk2, Pk3; bf16x8 Pa0, Pa1; float Pv; float2 Ps;
;       f32x4v Qw0, Qw1, Qw2, Qw3, Qb0, Qb1, Qb2, Qb3, Qk0, Qk1, Qk2, Qk3; bf16x8 Qa0, Qa1; float Qv; float2 Qs;
;       LOADV(P, 0);
; #pragma unroll 1
;       for (int t = 0; t < 32; t += 2) {
;         LOADV(Q, t + 1);
;         STEP(P, t);
;         LOADV(P, t + 2);
;         STEP(Q, t + 1);
;       }
;     ...
;       asm volatile("s_waitcnt lgkmcnt(0)" ::: "memory");
;       __builtin_amdgcn_s_barrier();
;       asm volatile("" ::: "memory");
;     }
;     float* so = p.out + (prompt ? O_WKVP : O_WKVS) + ((size_t)(b * 16 + h) * 64 + irow) * 64 + 8 * g;
;     *(float4*)so = make_float4(S0[0].x, S0[0].y, S0[1].x, S0[1].y); *(float4*)(so + 4) = make_float4(S0[2].x, S0[2].y, S0[3].x, S0[3].y);
;     *(float4*)(so + 32) = make_float4(S1[0].x, S1[0].y, S1[1].x, S1[1].y); *(float4*)(so + 36) = make_float4(S1[2].x, S1[2].y, S1[3].x, S1[3].y);
.LBB0_791:
	s_and_b64 vcc, exec, s[4:5]
	s_cbranch_vccz .LBB0_680
	v_and_b32_e32 v20, 15, v119
	v_readlane_b32 s0, v255, 9
	v_and_b32_e32 v82, 48, v119
	v_mov_b32_e32 v4, 0
	v_or_b32_e32 v79, s0, v20
	s_andn2_b64 vcc, exec, s[40:41]
	v_lshlrev_b32_e32 v2, 8, v79
	v_mov_b32_e32 v76, v82
	v_mov_b32_e32 v5, 0
	v_mov_b32_e32 v6, 0
	v_mov_b32_e32 v7, 0
	v_mov_b32_e32 v8, 0
	v_mov_b32_e32 v9, 0
	v_mov_b32_e32 v10, 0
	v_mov_b32_e32 v11, 0
	v_mov_b32_e32 v16, 0
	v_mov_b32_e32 v17, 0
	v_mov_b32_e32 v18, 0
	v_mov_b32_e32 v19, 0
	v_mov_b32_e32 v12, 0
	v_mov_b32_e32 v13, 0
	v_mov_b32_e32 v14, 0
	v_mov_b32_e32 v15, 0
	s_cbranch_vccnz .LBB0_794
	s_ashr_i32 s51, s50, 31
	s_lshl_b64 s[0:1], s[50:51], 14
	s_add_u32 s0, s20, s0
	s_addc_u32 s1, s21, s1
	v_lshl_add_u64 v[4:5], s[0:1], 0, v[2:3]
	v_mov_b32_e32 v77, v3
	v_lshl_add_u64 v[8:9], v[4:5], 0, v[76:77]
	global_load_dwordx4 v[16:19], v[8:9], off
	global_load_dwordx4 v[12:15], v[8:9], off offset:64
	global_load_dwordx4 v[4:7], v[8:9], off offset:128
	s_nop 0
	global_load_dwordx4 v[8:11], v[8:9], off offset:192
.LBB0_794:
	v_and_b32_e32 v21, 3, v119
	v_mov_b32_e32 v22, 0x2000
	v_mov_b32_e32 v23, 0x3000
	v_cmp_eq_u32_e32 vcc, 1, v21
	v_lshrrev_b32_e32 v21, 1, v82
	s_nop 0
	v_cndmask_b32_e32 v77, v22, v23, vcc
	v_add_u32_e32 v77, v77, v21
	v_and_b32_e32 v21, 16, v119
	v_mov_b32_e32 v22, 0x4000
	v_mov_b32_e32 v23, 0x6000
	v_cmp_eq_u32_e32 vcc, 16, v21
	s_nop 1
	v_cndmask_b32_e32 v83, v22, v23, vcc
	v_lshl_add_u32 v83, v20, 2, v83
	v_lshlrev_b32_e32 v84, 2, v79
	v_add_u32_e32 v84, 0xa000, v84
	v_mov_b32_e32 v85, v82
	v_cmp_eq_u32_e32 vcc, 0, v82
	s_nop 1
	v_cndmask_b32_e64 v24, 0, 1.0, vcc
	v_cmp_eq_u32_e32 vcc, 16, v82
	s_nop 1
	v_cndmask_b32_e64 v25, 0, 1.0, vcc
	s_mov_b32 s0, 0
	s_waitcnt vmcnt(0)
	s_barrier
.LBB0_795:
	s_bitcmp1_b32 s0, 0
	s_cselect_b32 s4, 0xe180, 0
	s_add_i32 s1, s4, 16
	v_add_u32_e32 v88, s1, v85
	v_add_u32_e32 v86, s1, v83
	v_add_u32_e32 v89, s1, v77
	v_add_u32_e32 v87, s1, v84
	s_add_i32 s1, s1, 0xe080
	v_mov_b32_e32 v111, s1
	ds_read_b128 v[52:55], v88
	ds_read_b128 v[40:43], v88 offset:64
	ds_read_b128 v[28:31], v88 offset:128
	ds_read_b128 v[20:23], v88 offset:192
	ds_read_b32 v60, v86
	ds_read_b32 v61, v86 offset:64
	ds_read_b32 v62, v86 offset:128
	ds_read_b32 v63, v86 offset:192
	ds_read_b64 v[72:73], v89
	ds_read_b64 v[74:75], v89 offset:32
	ds_read_b64 v[68:69], v89 offset:64
	ds_read_b64 v[70:71], v89 offset:96
	ds_read_b32 v78, v87
	ds_read_b64 v[80:81], v111
	s_mov_b32 s4, -2
.LBB0_796:
	ds_read_b128 v[90:93], v88 offset:256
	ds_read_b128 v[94:97], v88 offset:320
	ds_read_b128 v[98:101], v88 offset:384
	ds_read_b128 v[102:105], v88 offset:448
	ds_read_b32 v106, v86 offset:256
	ds_read_b32 v107, v86 offset:320
	ds_read_b32 v108, v86 offset:384
	ds_read_b32 v109, v86 offset:448
	ds_read_b64 v[138:139], v89 offset:128
	ds_read_b64 v[140:141], v89 offset:160
	ds_read_b64 v[142:143], v89 offset:192
	ds_read_b64 v[144:145], v89 offset:224
	ds_read_b32 v154, v87 offset:256
	ds_read_b64 v[156:157], v111 offset:8
	v_cvt_pk_bf16_f32 v146, v16, v17
	v_cvt_pk_bf16_f32 v147, v18, v19
	v_cvt_pk_bf16_f32 v148, v12, v13
	v_cvt_pk_bf16_f32 v149, v14, v15
	v_cvt_pk_bf16_f32 v150, v4, v5
	v_cvt_pk_bf16_f32 v151, v6, v7
	v_cvt_pk_bf16_f32 v152, v8, v9
	v_cvt_pk_bf16_f32 v153, v10, v11
	s_waitcnt lgkmcnt(14)
	v_mfma_f32_16x16x32_bf16 v[72:75], v[72:75], v[146:149], 0
	v_mfma_f32_16x16x32_bf16 v[68:71], v[68:71], v[150:153], v[72:75]
	v_mul_f32_e32 v64, v78, v25
	v_pk_mul_f32 v[16:17], v[16:17], v[52:53]
	v_pk_mul_f32 v[18:19], v[18:19], v[54:55]
	v_pk_mul_f32 v[12:13], v[12:13], v[40:41]
	v_pk_mul_f32 v[14:15], v[14:15], v[42:43]
	v_pk_mul_f32 v[4:5], v[4:5], v[28:29]
	v_pk_mul_f32 v[6:7], v[6:7], v[30:31]
	v_pk_mul_f32 v[8:9], v[8:9], v[20:21]
	v_pk_mul_f32 v[10:11], v[10:11], v[22:23]
	v_fmac_f32_e32 v64, v68, v24
	v_fma_f32 v146, v78, v81, v69
	v_fmac_f32_e32 v146, v68, v80
	v_mfma_f32_16x16x4_f32 v[16:19], v60, v64, v[16:19]
	v_mfma_f32_16x16x4_f32 v[12:15], v61, v64, v[12:15]
	v_mfma_f32_16x16x4_f32 v[4:7], v62, v64, v[4:7]
	v_mfma_f32_16x16x4_f32 v[8:11], v63, v64, v[8:11]
	ds_write_b32 v87, v146 offset:8192
	ds_read_b128 v[52:55], v88 offset:512
	ds_read_b128 v[40:43], v88 offset:576
	ds_read_b128 v[28:31], v88 offset:640
	ds_read_b128 v[20:23], v88 offset:704
	ds_read_b32 v60, v86 offset:512
	ds_read_b32 v61, v86 offset:576
	ds_read_b32 v62, v86 offset:640
	ds_read_b32 v63, v86 offset:704
	ds_read_b64 v[72:73], v89 offset:256
	ds_read_b64 v[74:75], v89 offset:288
	ds_read_b64 v[68:69], v89 offset:320
	ds_read_b64 v[70:71], v89 offset:352
	ds_read_b32 v78, v87 offset:512
	ds_read_b64 v[80:81], v111 offset:16
	v_cvt_pk_bf16_f32 v146, v16, v17
	v_cvt_pk_bf16_f32 v147, v18, v19
	v_cvt_pk_bf16_f32 v148, v12, v13
	v_cvt_pk_bf16_f32 v149, v14, v15
	v_cvt_pk_bf16_f32 v150, v4, v5
	v_cvt_pk_bf16_f32 v151, v6, v7
	v_cvt_pk_bf16_f32 v152, v8, v9
	v_cvt_pk_bf16_f32 v153, v10, v11
	s_waitcnt lgkmcnt(14)
	v_mfma_f32_16x16x32_bf16 v[138:141], v[138:141], v[146:149], 0
	v_mfma_f32_16x16x32_bf16 v[142:145], v[142:145], v[150:153], v[138:141]
	v_mul_f32_e32 v110, v154, v25
	v_pk_mul_f32 v[16:17], v[16:17], v[90:91]
	v_pk_mul_f32 v[18:19], v[18:19], v[92:93]
	v_pk_mul_f32 v[12:13], v[12:13], v[94:95]
	v_pk_mul_f32 v[14:15], v[14:15], v[96:97]
	v_pk_mul_f32 v[4:5], v[4:5], v[98:99]
	v_pk_mul_f32 v[6:7], v[6:7], v[100:101]
	v_pk_mul_f32 v[8:9], v[8:9], v[102:103]
	v_pk_mul_f32 v[10:11], v[10:11], v[104:105]
	v_fmac_f32_e32 v110, v142, v24
	v_fma_f32 v146, v154, v157, v143
	v_fmac_f32_e32 v146, v142, v156
	v_mfma_f32_16x16x4_f32 v[16:19], v106, v110, v[16:19]
	v_mfma_f32_16x16x4_f32 v[12:15], v107, v110, v[12:15]
	v_mfma_f32_16x16x4_f32 v[4:7], v108, v110, v[4:7]
	v_mfma_f32_16x16x4_f32 v[8:11], v109, v110, v[8:11]
	ds_write_b32 v87, v146 offset:8448
	s_add_i32 s4, s4, 2
	v_add_u32_e32 v88, 0x200, v88
	v_add_u32_e32 v86, 0x200, v86
	v_add_u32_e32 v89, 0x100, v89
	v_add_u32_e32 v87, 0x200, v87
	v_add_u32_e32 v111, 16, v111
	s_cmp_gt_u32 s4, 29
	s_cbranch_scc0 .LBB0_796
	s_waitcnt lgkmcnt(0)
	s_barrier
	s_add_i32 s0, s0, 1
	s_cmp_eq_u32 s0, s43
	s_cbranch_scc0 .LBB0_795
	s_and_b64 s[0:1], s[38:39], exec
	s_mov_b32 s0, 0x30200000
	s_cselect_b32 s0, s0, 0x30819000
	s_add_u32 s4, s70, s0
	s_addc_u32 s5, s71, 0
	s_ashr_i32 s43, s42, 31
	s_lshl_b64 s[0:1], s[42:43], 14
	s_add_u32 s0, s4, s0
	s_addc_u32 s1, s5, s1
	s_nop 7
	s_nop 3
	v_lshl_add_u64 v[20:21], s[0:1], 0, v[2:3]
	v_mov_b32_e32 v77, v3
	v_lshl_add_u64 v[20:21], v[20:21], 0, v[76:77]
	global_store_dwordx4 v[20:21], v[16:19], off
	global_store_dwordx4 v[20:21], v[12:15], off offset:64
	global_store_dwordx4 v[20:21], v[4:7], off offset:128
	global_store_dwordx4 v[20:21], v[8:11], off offset:192
	s_branch .LBB0_680
